# v55 + back-edge rotation (7.11): loop bookkeeping and next-iteration pointer selects hoisted into P4 load part; only exit/rare tests + one branch after the barrier
# baseline (speedup 1.0000x reference)
.LBB0_261:
.LBB0_262:
	s_cmp_eq_u32 s65, 28
	s_cselect_b64 s[84:85], -1, 0
	s_and_b64 vcc, s[84:85], s[36:37]
	s_andn2_b64 vcc, exec, vcc
	s_cbranch_vccnz .Lpeel_disp_ine
	s_mov_b32 m0, s59
	s_nop 0
	global_load_lds_dwordx4 v[142:143], off
	s_mov_b32 m0, s60
	s_nop 0
	global_load_lds_dwordx4 v[144:145], off
	s_branch .Lpeel_disp_ine
.Lpeel_disp_ine:
	s_add_u32 s0, s76, 0xfff80080
	s_addc_u32 s1, s77, -1
	s_and_b64 s[84:85], s[84:85], exec
	s_cselect_b32 vcc_hi, s22, s1
	s_cselect_b32 vcc_lo, s23, s0
	s_cselect_b32 s85, s49, s58
	s_cselect_b32 s84, s57, s51
	s_add_i32 s0, 0, 0x10000
	s_add_i32 s1, 0, 0x14000
	v_add_u32_e32 v158, s0, v176
	v_add_u32_e32 v174, s1, v176
	ds_read_b128 v[146:149], v158
	ds_read_b128 v[150:153], v158 offset:1024
	ds_read_b128 v[154:157], v158 offset:2048
	ds_read_b128 v[158:161], v158 offset:3072
	ds_read_b128 v[162:165], v174
	ds_read_b128 v[166:169], v174 offset:1024
	ds_read_b128 v[170:173], v174 offset:2048
	ds_read_b128 v[178:181], v174 offset:3072
	s_add_i32 m0, s21, 0xc000
	ds_read_b128 v[182:185], v177
	ds_read_b128 v[186:189], v177 offset:1024
	ds_read_b128 v[190:193], v177 offset:2048
	ds_read_b128 v[204:207], v177 offset:3072
	ds_read_b128 v[208:211], v177 offset:4096
	ds_read_b128 v[212:215], v177 offset:5120
	ds_read_b128 v[216:219], v177 offset:6144
	ds_read_b128 v[220:223], v177 offset:7168
	global_load_lds_dwordx4 v138, s[76:77]
	s_add_i32 m0, s21, 0xe000
	s_nop 0
	global_load_lds_dwordx4 v140, s[76:77]
	s_waitcnt vmcnt(8)
	s_waitcnt lgkmcnt(0)
	s_barrier
	s_waitcnt lgkmcnt(0)
	v_mfma_f32_16x16x32_bf16 v[126:129], v[146:149], v[182:185], 0
	v_mfma_f32_16x16x32_bf16 v[126:129], v[150:153], v[186:189], v[126:129]
	v_mfma_f32_16x16x32_bf16 v[122:125], v[158:161], v[186:189], 0
	v_mfma_f32_16x16x32_bf16 v[122:125], v[154:157], v[182:185], v[122:125]
	v_mfma_f32_16x16x32_bf16 v[118:121], v[162:165], v[182:185], 0
	v_mfma_f32_16x16x32_bf16 v[118:121], v[166:169], v[186:189], v[118:121]
	v_mfma_f32_16x16x32_bf16 v[114:117], v[178:181], v[186:189], 0
	v_mfma_f32_16x16x32_bf16 v[114:117], v[170:173], v[182:185], v[114:117]
	v_mfma_f32_16x16x32_bf16 v[98:101], v[170:173], v[190:193], 0
	v_mfma_f32_16x16x32_bf16 v[98:101], v[178:181], v[204:207], v[98:101]
	v_mfma_f32_16x16x32_bf16 v[102:105], v[166:169], v[204:207], 0
	v_mfma_f32_16x16x32_bf16 v[102:105], v[162:165], v[190:193], v[102:105]
	v_mfma_f32_16x16x32_bf16 v[106:109], v[154:157], v[190:193], 0
	v_mfma_f32_16x16x32_bf16 v[106:109], v[158:161], v[204:207], v[106:109]
	v_mfma_f32_16x16x32_bf16 v[110:113], v[150:153], v[204:207], 0
	v_mfma_f32_16x16x32_bf16 v[110:113], v[146:149], v[190:193], v[110:113]
	v_mfma_f32_16x16x32_bf16 v[94:97], v[146:149], v[208:211], 0
	v_mfma_f32_16x16x32_bf16 v[94:97], v[150:153], v[212:215], v[94:97]
	v_mfma_f32_16x16x32_bf16 v[90:93], v[158:161], v[212:215], 0
	v_mfma_f32_16x16x32_bf16 v[90:93], v[154:157], v[208:211], v[90:93]
	v_mfma_f32_16x16x32_bf16 v[86:89], v[162:165], v[208:211], 0
	v_mfma_f32_16x16x32_bf16 v[86:89], v[166:169], v[212:215], v[86:89]
	v_mfma_f32_16x16x32_bf16 v[82:85], v[178:181], v[212:215], 0
	v_mfma_f32_16x16x32_bf16 v[82:85], v[170:173], v[208:211], v[82:85]
	v_mfma_f32_16x16x32_bf16 v[66:69], v[170:173], v[216:219], 0
	v_mfma_f32_16x16x32_bf16 v[66:69], v[178:181], v[220:223], v[66:69]
	v_mfma_f32_16x16x32_bf16 v[70:73], v[166:169], v[220:223], 0
	v_mfma_f32_16x16x32_bf16 v[70:73], v[162:165], v[216:219], v[70:73]
	v_mfma_f32_16x16x32_bf16 v[74:77], v[154:157], v[216:219], 0
	v_mfma_f32_16x16x32_bf16 v[74:77], v[158:161], v[220:223], v[74:77]
	v_mfma_f32_16x16x32_bf16 v[78:81], v[150:153], v[220:223], 0
	v_mfma_f32_16x16x32_bf16 v[78:81], v[146:149], v[216:219], v[78:81]
	s_barrier
	s_add_i32 s0, s0, s20
	s_mov_b32 m0, s0
	ds_read_b128 v[182:185], v177 offset:16384
	ds_read_b128 v[186:189], v177 offset:17408
	ds_read_b128 v[190:193], v177 offset:18432
	ds_read_b128 v[204:207], v177 offset:19456
	ds_read_b128 v[208:211], v177 offset:20480
	ds_read_b128 v[212:215], v177 offset:21504
	ds_read_b128 v[216:219], v177 offset:22528
	ds_read_b128 v[220:223], v177 offset:23552
	global_load_lds_dwordx4 v132, s[84:85]
	s_add_i32 m0, s0, 0x2000
	s_add_u32 s94, s84, 0x80000
	s_addc_u32 s95, s85, 0
	s_add_i32 s0, s1, s20
	global_load_lds_dwordx4 v130, s[84:85]
	s_mov_b32 m0, s0
	s_nop 0
	global_load_lds_dwordx4 v132, s[94:95]
	s_add_i32 m0, s0, 0x2000
	s_nop 0
	global_load_lds_dwordx4 v130, s[94:95]
	s_mov_b32 m0, s21
	s_nop 0
	global_load_lds_dwordx4 v132, vcc
	s_mov_b32 m0, s26
	s_nop 0
	global_load_lds_dwordx4 v130, vcc
	s_waitcnt vmcnt(8)
	s_waitcnt lgkmcnt(0)
	s_barrier
	s_waitcnt lgkmcnt(0)
	v_mfma_f32_16x16x32_bf16 v[62:65], v[146:149], v[182:185], 0
	v_mfma_f32_16x16x32_bf16 v[62:65], v[150:153], v[186:189], v[62:65]
	v_mfma_f32_16x16x32_bf16 v[58:61], v[158:161], v[186:189], 0
	v_mfma_f32_16x16x32_bf16 v[58:61], v[154:157], v[182:185], v[58:61]
	v_mfma_f32_16x16x32_bf16 v[54:57], v[162:165], v[182:185], 0
	v_mfma_f32_16x16x32_bf16 v[54:57], v[166:169], v[186:189], v[54:57]
	v_mfma_f32_16x16x32_bf16 v[50:53], v[178:181], v[186:189], 0
	v_mfma_f32_16x16x32_bf16 v[50:53], v[170:173], v[182:185], v[50:53]
	v_mfma_f32_16x16x32_bf16 v[34:37], v[170:173], v[190:193], 0
	v_mfma_f32_16x16x32_bf16 v[34:37], v[178:181], v[204:207], v[34:37]
	v_mfma_f32_16x16x32_bf16 v[38:41], v[166:169], v[204:207], 0
	v_mfma_f32_16x16x32_bf16 v[38:41], v[162:165], v[190:193], v[38:41]
	v_mfma_f32_16x16x32_bf16 v[42:45], v[154:157], v[190:193], 0
	v_mfma_f32_16x16x32_bf16 v[42:45], v[158:161], v[204:207], v[42:45]
	v_mfma_f32_16x16x32_bf16 v[46:49], v[150:153], v[204:207], 0
	v_mfma_f32_16x16x32_bf16 v[46:49], v[146:149], v[190:193], v[46:49]
	v_mfma_f32_16x16x32_bf16 v[30:33], v[146:149], v[208:211], 0
	v_mfma_f32_16x16x32_bf16 v[30:33], v[150:153], v[212:215], v[30:33]
	v_mfma_f32_16x16x32_bf16 v[26:29], v[158:161], v[212:215], 0
	v_mfma_f32_16x16x32_bf16 v[26:29], v[154:157], v[208:211], v[26:29]
	v_mfma_f32_16x16x32_bf16 v[22:25], v[162:165], v[208:211], 0
	v_mfma_f32_16x16x32_bf16 v[22:25], v[166:169], v[212:215], v[22:25]
	v_mfma_f32_16x16x32_bf16 v[18:21], v[178:181], v[212:215], 0
	v_mfma_f32_16x16x32_bf16 v[18:21], v[170:173], v[208:211], v[18:21]
	v_mfma_f32_16x16x32_bf16 v[2:5], v[170:173], v[216:219], 0
	v_mfma_f32_16x16x32_bf16 v[2:5], v[178:181], v[220:223], v[2:5]
	v_mfma_f32_16x16x32_bf16 v[6:9], v[166:169], v[220:223], 0
	v_mfma_f32_16x16x32_bf16 v[6:9], v[162:165], v[216:219], v[6:9]
	v_mfma_f32_16x16x32_bf16 v[10:13], v[154:157], v[216:219], 0
	v_mfma_f32_16x16x32_bf16 v[10:13], v[158:161], v[220:223], v[10:13]
	v_mfma_f32_16x16x32_bf16 v[14:17], v[150:153], v[220:223], 0
	v_mfma_f32_16x16x32_bf16 v[14:17], v[146:149], v[216:219], v[14:17]
	s_barrier
	s_add_i32 s0, 0, 0x18000
	s_add_i32 s1, 0, 0x1c000
	v_add_u32_e32 v158, s0, v176
	v_add_u32_e32 v178, s1, v176
	ds_read_b128 v[146:149], v158
	ds_read_b128 v[150:153], v158 offset:1024
	ds_read_b128 v[154:157], v158 offset:2048
	ds_read_b128 v[158:161], v158 offset:3072
	ds_read_b128 v[162:165], v178
	ds_read_b128 v[166:169], v178 offset:1024
	ds_read_b128 v[170:173], v178 offset:2048
	ds_read_b128 v[178:181], v178 offset:3072
	s_add_u32 s94, vcc_lo, 0x80000
	s_addc_u32 s95, vcc_hi, 0
	s_mov_b32 m0, s27
	ds_read_b128 v[182:185], v177 offset:32768
	ds_read_b128 v[186:189], v177 offset:33792
	ds_read_b128 v[190:193], v177 offset:34816
	ds_read_b128 v[204:207], v177 offset:35840
	ds_read_b128 v[208:211], v177 offset:36864
	ds_read_b128 v[212:215], v177 offset:37888
	ds_read_b128 v[216:219], v177 offset:38912
	ds_read_b128 v[220:223], v177 offset:39936
	global_load_lds_dwordx4 v132, s[94:95]
	s_mov_b32 m0, s29
	s_nop 0
	global_load_lds_dwordx4 v130, s[94:95]
	s_waitcnt vmcnt(8)
	s_waitcnt lgkmcnt(0)
	s_barrier
	s_waitcnt lgkmcnt(0)
	v_mfma_f32_16x16x32_bf16 v[126:129], v[146:149], v[182:185], v[126:129]
	v_mfma_f32_16x16x32_bf16 v[126:129], v[150:153], v[186:189], v[126:129]
	v_mfma_f32_16x16x32_bf16 v[122:125], v[158:161], v[186:189], v[122:125]
	v_mfma_f32_16x16x32_bf16 v[122:125], v[154:157], v[182:185], v[122:125]
	v_mfma_f32_16x16x32_bf16 v[118:121], v[162:165], v[182:185], v[118:121]
	v_mfma_f32_16x16x32_bf16 v[118:121], v[166:169], v[186:189], v[118:121]
	v_mfma_f32_16x16x32_bf16 v[114:117], v[178:181], v[186:189], v[114:117]
	v_mfma_f32_16x16x32_bf16 v[114:117], v[170:173], v[182:185], v[114:117]
	v_mfma_f32_16x16x32_bf16 v[98:101], v[170:173], v[190:193], v[98:101]
	v_mfma_f32_16x16x32_bf16 v[98:101], v[178:181], v[204:207], v[98:101]
	v_mfma_f32_16x16x32_bf16 v[102:105], v[166:169], v[204:207], v[102:105]
	v_mfma_f32_16x16x32_bf16 v[102:105], v[162:165], v[190:193], v[102:105]
	v_mfma_f32_16x16x32_bf16 v[106:109], v[154:157], v[190:193], v[106:109]
	v_mfma_f32_16x16x32_bf16 v[106:109], v[158:161], v[204:207], v[106:109]
	v_mfma_f32_16x16x32_bf16 v[110:113], v[150:153], v[204:207], v[110:113]
	v_mfma_f32_16x16x32_bf16 v[110:113], v[146:149], v[190:193], v[110:113]
	v_mfma_f32_16x16x32_bf16 v[94:97], v[146:149], v[208:211], v[94:97]
	v_mfma_f32_16x16x32_bf16 v[94:97], v[150:153], v[212:215], v[94:97]
	v_mfma_f32_16x16x32_bf16 v[90:93], v[158:161], v[212:215], v[90:93]
	v_mfma_f32_16x16x32_bf16 v[90:93], v[154:157], v[208:211], v[90:93]
	v_mfma_f32_16x16x32_bf16 v[86:89], v[162:165], v[208:211], v[86:89]
	v_mfma_f32_16x16x32_bf16 v[86:89], v[166:169], v[212:215], v[86:89]
	v_mfma_f32_16x16x32_bf16 v[82:85], v[178:181], v[212:215], v[82:85]
	v_mfma_f32_16x16x32_bf16 v[82:85], v[170:173], v[208:211], v[82:85]
	v_mfma_f32_16x16x32_bf16 v[66:69], v[170:173], v[216:219], v[66:69]
	v_mfma_f32_16x16x32_bf16 v[66:69], v[178:181], v[220:223], v[66:69]
	v_mfma_f32_16x16x32_bf16 v[70:73], v[166:169], v[220:223], v[70:73]
	v_mfma_f32_16x16x32_bf16 v[70:73], v[162:165], v[216:219], v[70:73]
	v_mfma_f32_16x16x32_bf16 v[74:77], v[154:157], v[216:219], v[74:77]
	v_mfma_f32_16x16x32_bf16 v[74:77], v[158:161], v[220:223], v[74:77]
	v_mfma_f32_16x16x32_bf16 v[78:81], v[150:153], v[220:223], v[78:81]
	v_mfma_f32_16x16x32_bf16 v[78:81], v[146:149], v[216:219], v[78:81]
	s_barrier
	s_add_u32 s98, s84, 0x80
	s_addc_u32 s99, s85, 0
	s_add_u32 s100, vcc_lo, 0x80
	s_addc_u32 s101, vcc_hi, 0
	s_add_i32 s0, s0, s20
	s_mov_b32 m0, s0
	ds_read_b128 v[182:185], v177 offset:49152
	ds_read_b128 v[186:189], v177 offset:50176
	ds_read_b128 v[190:193], v177 offset:51200
	ds_read_b128 v[204:207], v177 offset:52224
	ds_read_b128 v[208:211], v177 offset:53248
	ds_read_b128 v[212:215], v177 offset:54272
	ds_read_b128 v[216:219], v177 offset:55296
	ds_read_b128 v[220:223], v177 offset:56320
	global_load_lds_dwordx4 v132, s[98:99]
	s_add_i32 m0, s0, 0x2000
	s_add_u32 s84, s84, 0x80080
	s_addc_u32 s85, s85, 0
	s_add_i32 s0, s1, s20
	global_load_lds_dwordx4 v130, s[98:99]
	s_mov_b32 m0, s0
	s_nop 0
	global_load_lds_dwordx4 v132, s[84:85]
	s_add_i32 m0, s0, 0x2000
	s_nop 0
	global_load_lds_dwordx4 v130, s[84:85]
	s_mov_b32 m0, s40
	s_nop 0
	global_load_lds_dwordx4 v132, s[100:101]
	s_mov_b32 m0, s41
	s_nop 0
	global_load_lds_dwordx4 v130, s[100:101]
	s_add_i32 s65, s65, 2
	s_add_u32 s76, s76, 0x100
	s_addc_u32 s77, s77, 0
	s_add_u32 s51, s51, 0x100
	s_addc_u32 s58, s58, 0
	s_cmp_eq_u32 s65, 28
	s_cselect_b64 s[84:85], -1, 0
	s_and_b64 s[100:101], s[84:85], s[36:37]
	s_add_u32 s0, s76, 0xfff80080
	s_addc_u32 s1, s77, -1
	s_and_b64 s[84:85], s[84:85], exec
	s_cselect_b32 vcc_hi, s22, s1
	s_cselect_b32 vcc_lo, s23, s0
	s_cselect_b32 s85, s49, s58
	s_cselect_b32 s84, s57, s51
	s_cmp_gt_u32 s65, 29
	s_waitcnt vmcnt(8)
	s_waitcnt lgkmcnt(0)
	s_barrier
	s_waitcnt lgkmcnt(0)
	v_mfma_f32_16x16x32_bf16 v[62:65], v[146:149], v[182:185], v[62:65]
	v_mfma_f32_16x16x32_bf16 v[62:65], v[150:153], v[186:189], v[62:65]
	v_mfma_f32_16x16x32_bf16 v[58:61], v[158:161], v[186:189], v[58:61]
	v_mfma_f32_16x16x32_bf16 v[58:61], v[154:157], v[182:185], v[58:61]
	v_mfma_f32_16x16x32_bf16 v[54:57], v[162:165], v[182:185], v[54:57]
	v_mfma_f32_16x16x32_bf16 v[54:57], v[166:169], v[186:189], v[54:57]
	v_mfma_f32_16x16x32_bf16 v[50:53], v[178:181], v[186:189], v[50:53]
	v_mfma_f32_16x16x32_bf16 v[50:53], v[170:173], v[182:185], v[50:53]
	v_mfma_f32_16x16x32_bf16 v[34:37], v[170:173], v[190:193], v[34:37]
	v_mfma_f32_16x16x32_bf16 v[34:37], v[178:181], v[204:207], v[34:37]
	v_mfma_f32_16x16x32_bf16 v[38:41], v[166:169], v[204:207], v[38:41]
	v_mfma_f32_16x16x32_bf16 v[38:41], v[162:165], v[190:193], v[38:41]
	v_mfma_f32_16x16x32_bf16 v[42:45], v[154:157], v[190:193], v[42:45]
	v_mfma_f32_16x16x32_bf16 v[42:45], v[158:161], v[204:207], v[42:45]
	v_mfma_f32_16x16x32_bf16 v[46:49], v[150:153], v[204:207], v[46:49]
	v_mfma_f32_16x16x32_bf16 v[46:49], v[146:149], v[190:193], v[46:49]
	v_mfma_f32_16x16x32_bf16 v[30:33], v[146:149], v[208:211], v[30:33]
	v_mfma_f32_16x16x32_bf16 v[30:33], v[150:153], v[212:215], v[30:33]
	v_mfma_f32_16x16x32_bf16 v[26:29], v[158:161], v[212:215], v[26:29]
	v_mfma_f32_16x16x32_bf16 v[26:29], v[154:157], v[208:211], v[26:29]
	v_mfma_f32_16x16x32_bf16 v[22:25], v[162:165], v[208:211], v[22:25]
	v_mfma_f32_16x16x32_bf16 v[22:25], v[166:169], v[212:215], v[22:25]
	v_mfma_f32_16x16x32_bf16 v[18:21], v[178:181], v[212:215], v[18:21]
	v_mfma_f32_16x16x32_bf16 v[18:21], v[170:173], v[208:211], v[18:21]
	v_mfma_f32_16x16x32_bf16 v[2:5], v[170:173], v[216:219], v[2:5]
	v_mfma_f32_16x16x32_bf16 v[2:5], v[178:181], v[220:223], v[2:5]
	v_mfma_f32_16x16x32_bf16 v[6:9], v[166:169], v[220:223], v[6:9]
	v_mfma_f32_16x16x32_bf16 v[6:9], v[162:165], v[216:219], v[6:9]
	v_mfma_f32_16x16x32_bf16 v[10:13], v[154:157], v[216:219], v[10:13]
	v_mfma_f32_16x16x32_bf16 v[10:13], v[158:161], v[220:223], v[10:13]
	v_mfma_f32_16x16x32_bf16 v[14:17], v[150:153], v[220:223], v[14:17]
	v_mfma_f32_16x16x32_bf16 v[14:17], v[146:149], v[216:219], v[14:17]
	s_barrier
	s_cbranch_scc1 .LBB0_264
	s_cmp_lg_u64 s[100:101], 0
	s_cbranch_scc1 .Lrot_rare_ine
	s_branch .Lrot_body_ine
.Lrot_rare_ine:
	s_mov_b32 m0, s59
	s_nop 0
	global_load_lds_dwordx4 v[142:143], off
	s_mov_b32 m0, s60
	s_nop 0
	global_load_lds_dwordx4 v[144:145], off
	s_branch .Lrot_body_ine
.Lrot_body_ine:
	s_add_i32 s0, 0, 0x10000
	s_add_i32 s1, 0, 0x14000
	v_add_u32_e32 v158, s0, v176
	v_add_u32_e32 v174, s1, v176
	ds_read_b128 v[146:149], v158
	ds_read_b128 v[150:153], v158 offset:1024
	ds_read_b128 v[154:157], v158 offset:2048
	ds_read_b128 v[158:161], v158 offset:3072
	ds_read_b128 v[162:165], v174
	ds_read_b128 v[166:169], v174 offset:1024
	ds_read_b128 v[170:173], v174 offset:2048
	ds_read_b128 v[178:181], v174 offset:3072
	s_add_i32 m0, s21, 0xc000
	ds_read_b128 v[182:185], v177
	ds_read_b128 v[186:189], v177 offset:1024
	ds_read_b128 v[190:193], v177 offset:2048
	ds_read_b128 v[204:207], v177 offset:3072
	ds_read_b128 v[208:211], v177 offset:4096
	ds_read_b128 v[212:215], v177 offset:5120
	ds_read_b128 v[216:219], v177 offset:6144
	ds_read_b128 v[220:223], v177 offset:7168
	global_load_lds_dwordx4 v138, s[76:77]
	s_add_i32 m0, s21, 0xe000
	s_nop 0
	global_load_lds_dwordx4 v140, s[76:77]
	s_waitcnt vmcnt(8)
	s_waitcnt lgkmcnt(0)
	s_barrier
	s_waitcnt lgkmcnt(0)
	v_mfma_f32_16x16x32_bf16 v[126:129], v[146:149], v[182:185], v[126:129]
	v_mfma_f32_16x16x32_bf16 v[126:129], v[150:153], v[186:189], v[126:129]
	v_mfma_f32_16x16x32_bf16 v[122:125], v[158:161], v[186:189], v[122:125]
	v_mfma_f32_16x16x32_bf16 v[122:125], v[154:157], v[182:185], v[122:125]
	v_mfma_f32_16x16x32_bf16 v[118:121], v[162:165], v[182:185], v[118:121]
	v_mfma_f32_16x16x32_bf16 v[118:121], v[166:169], v[186:189], v[118:121]
	v_mfma_f32_16x16x32_bf16 v[114:117], v[178:181], v[186:189], v[114:117]
	v_mfma_f32_16x16x32_bf16 v[114:117], v[170:173], v[182:185], v[114:117]
	v_mfma_f32_16x16x32_bf16 v[98:101], v[170:173], v[190:193], v[98:101]
	v_mfma_f32_16x16x32_bf16 v[98:101], v[178:181], v[204:207], v[98:101]
	v_mfma_f32_16x16x32_bf16 v[102:105], v[166:169], v[204:207], v[102:105]
	v_mfma_f32_16x16x32_bf16 v[102:105], v[162:165], v[190:193], v[102:105]
	v_mfma_f32_16x16x32_bf16 v[106:109], v[154:157], v[190:193], v[106:109]
	v_mfma_f32_16x16x32_bf16 v[106:109], v[158:161], v[204:207], v[106:109]
	v_mfma_f32_16x16x32_bf16 v[110:113], v[150:153], v[204:207], v[110:113]
	v_mfma_f32_16x16x32_bf16 v[110:113], v[146:149], v[190:193], v[110:113]
	v_mfma_f32_16x16x32_bf16 v[94:97], v[146:149], v[208:211], v[94:97]
	v_mfma_f32_16x16x32_bf16 v[94:97], v[150:153], v[212:215], v[94:97]
	v_mfma_f32_16x16x32_bf16 v[90:93], v[158:161], v[212:215], v[90:93]
	v_mfma_f32_16x16x32_bf16 v[90:93], v[154:157], v[208:211], v[90:93]
	v_mfma_f32_16x16x32_bf16 v[86:89], v[162:165], v[208:211], v[86:89]
	v_mfma_f32_16x16x32_bf16 v[86:89], v[166:169], v[212:215], v[86:89]
	v_mfma_f32_16x16x32_bf16 v[82:85], v[178:181], v[212:215], v[82:85]
	v_mfma_f32_16x16x32_bf16 v[82:85], v[170:173], v[208:211], v[82:85]
	v_mfma_f32_16x16x32_bf16 v[66:69], v[170:173], v[216:219], v[66:69]
	v_mfma_f32_16x16x32_bf16 v[66:69], v[178:181], v[220:223], v[66:69]
	v_mfma_f32_16x16x32_bf16 v[70:73], v[166:169], v[220:223], v[70:73]
	v_mfma_f32_16x16x32_bf16 v[70:73], v[162:165], v[216:219], v[70:73]
	v_mfma_f32_16x16x32_bf16 v[74:77], v[154:157], v[216:219], v[74:77]
	v_mfma_f32_16x16x32_bf16 v[74:77], v[158:161], v[220:223], v[74:77]
	v_mfma_f32_16x16x32_bf16 v[78:81], v[150:153], v[220:223], v[78:81]
	v_mfma_f32_16x16x32_bf16 v[78:81], v[146:149], v[216:219], v[78:81]
	s_barrier
	s_add_i32 s0, s0, s20
	s_mov_b32 m0, s0
	ds_read_b128 v[182:185], v177 offset:16384
	ds_read_b128 v[186:189], v177 offset:17408
	ds_read_b128 v[190:193], v177 offset:18432
	ds_read_b128 v[204:207], v177 offset:19456
	ds_read_b128 v[208:211], v177 offset:20480
	ds_read_b128 v[212:215], v177 offset:21504
	ds_read_b128 v[216:219], v177 offset:22528
	ds_read_b128 v[220:223], v177 offset:23552
	global_load_lds_dwordx4 v132, s[84:85]
	s_add_i32 m0, s0, 0x2000
	s_add_u32 s94, s84, 0x80000
	s_addc_u32 s95, s85, 0
	s_add_i32 s0, s1, s20
	global_load_lds_dwordx4 v130, s[84:85]
	s_mov_b32 m0, s0
	s_nop 0
	global_load_lds_dwordx4 v132, s[94:95]
	s_add_i32 m0, s0, 0x2000
	s_nop 0
	global_load_lds_dwordx4 v130, s[94:95]
	s_mov_b32 m0, s21
	s_nop 0
	global_load_lds_dwordx4 v132, vcc
	s_mov_b32 m0, s26
	s_nop 0
	global_load_lds_dwordx4 v130, vcc
	s_waitcnt vmcnt(8)
	s_waitcnt lgkmcnt(0)
	s_barrier
	s_waitcnt lgkmcnt(0)
	v_mfma_f32_16x16x32_bf16 v[62:65], v[146:149], v[182:185], v[62:65]
	v_mfma_f32_16x16x32_bf16 v[62:65], v[150:153], v[186:189], v[62:65]
	v_mfma_f32_16x16x32_bf16 v[58:61], v[158:161], v[186:189], v[58:61]
	v_mfma_f32_16x16x32_bf16 v[58:61], v[154:157], v[182:185], v[58:61]
	v_mfma_f32_16x16x32_bf16 v[54:57], v[162:165], v[182:185], v[54:57]
	v_mfma_f32_16x16x32_bf16 v[54:57], v[166:169], v[186:189], v[54:57]
	v_mfma_f32_16x16x32_bf16 v[50:53], v[178:181], v[186:189], v[50:53]
	v_mfma_f32_16x16x32_bf16 v[50:53], v[170:173], v[182:185], v[50:53]
	v_mfma_f32_16x16x32_bf16 v[34:37], v[170:173], v[190:193], v[34:37]
	v_mfma_f32_16x16x32_bf16 v[34:37], v[178:181], v[204:207], v[34:37]
	v_mfma_f32_16x16x32_bf16 v[38:41], v[166:169], v[204:207], v[38:41]
	v_mfma_f32_16x16x32_bf16 v[38:41], v[162:165], v[190:193], v[38:41]
	v_mfma_f32_16x16x32_bf16 v[42:45], v[154:157], v[190:193], v[42:45]
	v_mfma_f32_16x16x32_bf16 v[42:45], v[158:161], v[204:207], v[42:45]
	v_mfma_f32_16x16x32_bf16 v[46:49], v[150:153], v[204:207], v[46:49]
	v_mfma_f32_16x16x32_bf16 v[46:49], v[146:149], v[190:193], v[46:49]
	v_mfma_f32_16x16x32_bf16 v[30:33], v[146:149], v[208:211], v[30:33]
	v_mfma_f32_16x16x32_bf16 v[30:33], v[150:153], v[212:215], v[30:33]
	v_mfma_f32_16x16x32_bf16 v[26:29], v[158:161], v[212:215], v[26:29]
	v_mfma_f32_16x16x32_bf16 v[26:29], v[154:157], v[208:211], v[26:29]
	v_mfma_f32_16x16x32_bf16 v[22:25], v[162:165], v[208:211], v[22:25]
	v_mfma_f32_16x16x32_bf16 v[22:25], v[166:169], v[212:215], v[22:25]
	v_mfma_f32_16x16x32_bf16 v[18:21], v[178:181], v[212:215], v[18:21]
	v_mfma_f32_16x16x32_bf16 v[18:21], v[170:173], v[208:211], v[18:21]
	v_mfma_f32_16x16x32_bf16 v[2:5], v[170:173], v[216:219], v[2:5]
	v_mfma_f32_16x16x32_bf16 v[2:5], v[178:181], v[220:223], v[2:5]
	v_mfma_f32_16x16x32_bf16 v[6:9], v[166:169], v[220:223], v[6:9]
	v_mfma_f32_16x16x32_bf16 v[6:9], v[162:165], v[216:219], v[6:9]
	v_mfma_f32_16x16x32_bf16 v[10:13], v[154:157], v[216:219], v[10:13]
	v_mfma_f32_16x16x32_bf16 v[10:13], v[158:161], v[220:223], v[10:13]
	v_mfma_f32_16x16x32_bf16 v[14:17], v[150:153], v[220:223], v[14:17]
	v_mfma_f32_16x16x32_bf16 v[14:17], v[146:149], v[216:219], v[14:17]
	s_barrier
	s_add_i32 s0, 0, 0x18000
	s_add_i32 s1, 0, 0x1c000
	v_add_u32_e32 v158, s0, v176
	v_add_u32_e32 v178, s1, v176
	ds_read_b128 v[146:149], v158
	ds_read_b128 v[150:153], v158 offset:1024
	ds_read_b128 v[154:157], v158 offset:2048
	ds_read_b128 v[158:161], v158 offset:3072
	ds_read_b128 v[162:165], v178
	ds_read_b128 v[166:169], v178 offset:1024
	ds_read_b128 v[170:173], v178 offset:2048
	ds_read_b128 v[178:181], v178 offset:3072
	s_add_u32 s94, vcc_lo, 0x80000
	s_addc_u32 s95, vcc_hi, 0
	s_mov_b32 m0, s27
	ds_read_b128 v[182:185], v177 offset:32768
	ds_read_b128 v[186:189], v177 offset:33792
	ds_read_b128 v[190:193], v177 offset:34816
	ds_read_b128 v[204:207], v177 offset:35840
	ds_read_b128 v[208:211], v177 offset:36864
	ds_read_b128 v[212:215], v177 offset:37888
	ds_read_b128 v[216:219], v177 offset:38912
	ds_read_b128 v[220:223], v177 offset:39936
	global_load_lds_dwordx4 v132, s[94:95]
	s_mov_b32 m0, s29
	s_nop 0
	global_load_lds_dwordx4 v130, s[94:95]
	s_waitcnt vmcnt(8)
	s_waitcnt lgkmcnt(0)
	s_barrier
	s_waitcnt lgkmcnt(0)
	v_mfma_f32_16x16x32_bf16 v[126:129], v[146:149], v[182:185], v[126:129]
	v_mfma_f32_16x16x32_bf16 v[126:129], v[150:153], v[186:189], v[126:129]
	v_mfma_f32_16x16x32_bf16 v[122:125], v[158:161], v[186:189], v[122:125]
	v_mfma_f32_16x16x32_bf16 v[122:125], v[154:157], v[182:185], v[122:125]
	v_mfma_f32_16x16x32_bf16 v[118:121], v[162:165], v[182:185], v[118:121]
	v_mfma_f32_16x16x32_bf16 v[118:121], v[166:169], v[186:189], v[118:121]
	v_mfma_f32_16x16x32_bf16 v[114:117], v[178:181], v[186:189], v[114:117]
	v_mfma_f32_16x16x32_bf16 v[114:117], v[170:173], v[182:185], v[114:117]
	v_mfma_f32_16x16x32_bf16 v[98:101], v[170:173], v[190:193], v[98:101]
	v_mfma_f32_16x16x32_bf16 v[98:101], v[178:181], v[204:207], v[98:101]
	v_mfma_f32_16x16x32_bf16 v[102:105], v[166:169], v[204:207], v[102:105]
	v_mfma_f32_16x16x32_bf16 v[102:105], v[162:165], v[190:193], v[102:105]
	v_mfma_f32_16x16x32_bf16 v[106:109], v[154:157], v[190:193], v[106:109]
	v_mfma_f32_16x16x32_bf16 v[106:109], v[158:161], v[204:207], v[106:109]
	v_mfma_f32_16x16x32_bf16 v[110:113], v[150:153], v[204:207], v[110:113]
	v_mfma_f32_16x16x32_bf16 v[110:113], v[146:149], v[190:193], v[110:113]
	v_mfma_f32_16x16x32_bf16 v[94:97], v[146:149], v[208:211], v[94:97]
	v_mfma_f32_16x16x32_bf16 v[94:97], v[150:153], v[212:215], v[94:97]
	v_mfma_f32_16x16x32_bf16 v[90:93], v[158:161], v[212:215], v[90:93]
	v_mfma_f32_16x16x32_bf16 v[90:93], v[154:157], v[208:211], v[90:93]
	v_mfma_f32_16x16x32_bf16 v[86:89], v[162:165], v[208:211], v[86:89]
	v_mfma_f32_16x16x32_bf16 v[86:89], v[166:169], v[212:215], v[86:89]
	v_mfma_f32_16x16x32_bf16 v[82:85], v[178:181], v[212:215], v[82:85]
	v_mfma_f32_16x16x32_bf16 v[82:85], v[170:173], v[208:211], v[82:85]
	v_mfma_f32_16x16x32_bf16 v[66:69], v[170:173], v[216:219], v[66:69]
	v_mfma_f32_16x16x32_bf16 v[66:69], v[178:181], v[220:223], v[66:69]
	v_mfma_f32_16x16x32_bf16 v[70:73], v[166:169], v[220:223], v[70:73]
	v_mfma_f32_16x16x32_bf16 v[70:73], v[162:165], v[216:219], v[70:73]
	v_mfma_f32_16x16x32_bf16 v[74:77], v[154:157], v[216:219], v[74:77]
	v_mfma_f32_16x16x32_bf16 v[74:77], v[158:161], v[220:223], v[74:77]
	v_mfma_f32_16x16x32_bf16 v[78:81], v[150:153], v[220:223], v[78:81]
	v_mfma_f32_16x16x32_bf16 v[78:81], v[146:149], v[216:219], v[78:81]
	s_barrier
	s_add_u32 s98, s84, 0x80
	s_addc_u32 s99, s85, 0
	s_add_u32 s100, vcc_lo, 0x80
	s_addc_u32 s101, vcc_hi, 0
	s_add_i32 s0, s0, s20
	s_mov_b32 m0, s0
	ds_read_b128 v[182:185], v177 offset:49152
	ds_read_b128 v[186:189], v177 offset:50176
	ds_read_b128 v[190:193], v177 offset:51200
	ds_read_b128 v[204:207], v177 offset:52224
	ds_read_b128 v[208:211], v177 offset:53248
	ds_read_b128 v[212:215], v177 offset:54272
	ds_read_b128 v[216:219], v177 offset:55296
	ds_read_b128 v[220:223], v177 offset:56320
	global_load_lds_dwordx4 v132, s[98:99]
	s_add_i32 m0, s0, 0x2000
	s_add_u32 s84, s84, 0x80080
	s_addc_u32 s85, s85, 0
	s_add_i32 s0, s1, s20
	global_load_lds_dwordx4 v130, s[98:99]
	s_mov_b32 m0, s0
	s_nop 0
	global_load_lds_dwordx4 v132, s[84:85]
	s_add_i32 m0, s0, 0x2000
	s_nop 0
	global_load_lds_dwordx4 v130, s[84:85]
	s_mov_b32 m0, s40
	s_nop 0
	global_load_lds_dwordx4 v132, s[100:101]
	s_mov_b32 m0, s41
	s_nop 0
	global_load_lds_dwordx4 v130, s[100:101]
	s_add_i32 s65, s65, 2
	s_add_u32 s76, s76, 0x100
	s_addc_u32 s77, s77, 0
	s_add_u32 s51, s51, 0x100
	s_addc_u32 s58, s58, 0
	s_cmp_eq_u32 s65, 28
	s_cselect_b64 s[84:85], -1, 0
	s_and_b64 s[100:101], s[84:85], s[36:37]
	s_add_u32 s0, s76, 0xfff80080
	s_addc_u32 s1, s77, -1
	s_and_b64 s[84:85], s[84:85], exec
	s_cselect_b32 vcc_hi, s22, s1
	s_cselect_b32 vcc_lo, s23, s0
	s_cselect_b32 s85, s49, s58
	s_cselect_b32 s84, s57, s51
	s_cmp_gt_u32 s65, 29
	s_waitcnt vmcnt(8)
	s_waitcnt lgkmcnt(0)
	s_barrier
	s_waitcnt lgkmcnt(0)
	v_mfma_f32_16x16x32_bf16 v[62:65], v[146:149], v[182:185], v[62:65]
	v_mfma_f32_16x16x32_bf16 v[62:65], v[150:153], v[186:189], v[62:65]
	v_mfma_f32_16x16x32_bf16 v[58:61], v[158:161], v[186:189], v[58:61]
	v_mfma_f32_16x16x32_bf16 v[58:61], v[154:157], v[182:185], v[58:61]
	v_mfma_f32_16x16x32_bf16 v[54:57], v[162:165], v[182:185], v[54:57]
	v_mfma_f32_16x16x32_bf16 v[54:57], v[166:169], v[186:189], v[54:57]
	v_mfma_f32_16x16x32_bf16 v[50:53], v[178:181], v[186:189], v[50:53]
	v_mfma_f32_16x16x32_bf16 v[50:53], v[170:173], v[182:185], v[50:53]
	v_mfma_f32_16x16x32_bf16 v[34:37], v[170:173], v[190:193], v[34:37]
	v_mfma_f32_16x16x32_bf16 v[34:37], v[178:181], v[204:207], v[34:37]
	v_mfma_f32_16x16x32_bf16 v[38:41], v[166:169], v[204:207], v[38:41]
	v_mfma_f32_16x16x32_bf16 v[38:41], v[162:165], v[190:193], v[38:41]
	v_mfma_f32_16x16x32_bf16 v[42:45], v[154:157], v[190:193], v[42:45]
	v_mfma_f32_16x16x32_bf16 v[42:45], v[158:161], v[204:207], v[42:45]
	v_mfma_f32_16x16x32_bf16 v[46:49], v[150:153], v[204:207], v[46:49]
	v_mfma_f32_16x16x32_bf16 v[46:49], v[146:149], v[190:193], v[46:49]
	v_mfma_f32_16x16x32_bf16 v[30:33], v[146:149], v[208:211], v[30:33]
	v_mfma_f32_16x16x32_bf16 v[30:33], v[150:153], v[212:215], v[30:33]
	v_mfma_f32_16x16x32_bf16 v[26:29], v[158:161], v[212:215], v[26:29]
	v_mfma_f32_16x16x32_bf16 v[26:29], v[154:157], v[208:211], v[26:29]
	v_mfma_f32_16x16x32_bf16 v[22:25], v[162:165], v[208:211], v[22:25]
	v_mfma_f32_16x16x32_bf16 v[22:25], v[166:169], v[212:215], v[22:25]
	v_mfma_f32_16x16x32_bf16 v[18:21], v[178:181], v[212:215], v[18:21]
	v_mfma_f32_16x16x32_bf16 v[18:21], v[170:173], v[208:211], v[18:21]
	v_mfma_f32_16x16x32_bf16 v[2:5], v[170:173], v[216:219], v[2:5]
	v_mfma_f32_16x16x32_bf16 v[2:5], v[178:181], v[220:223], v[2:5]
	v_mfma_f32_16x16x32_bf16 v[6:9], v[166:169], v[220:223], v[6:9]
	v_mfma_f32_16x16x32_bf16 v[6:9], v[162:165], v[216:219], v[6:9]
	v_mfma_f32_16x16x32_bf16 v[10:13], v[154:157], v[216:219], v[10:13]
	v_mfma_f32_16x16x32_bf16 v[10:13], v[158:161], v[220:223], v[10:13]
	v_mfma_f32_16x16x32_bf16 v[14:17], v[150:153], v[220:223], v[14:17]
	v_mfma_f32_16x16x32_bf16 v[14:17], v[146:149], v[216:219], v[14:17]
	s_barrier
	s_cbranch_scc1 .LBB0_264
	s_cmp_lg_u64 s[100:101], 0
	s_cbranch_scc1 .Lrot_rare_ine
	s_branch .Lrot_body_ine

.LBB0_285:
.LBB0_286:
	s_cmp_eq_u32 s43, 28
	s_cselect_b64 s[70:71], -1, 0
	s_and_b64 vcc, s[70:71], s[10:11]
	s_andn2_b64 vcc, exec, vcc
	s_cbranch_vccnz .Lpeel_disp_ino
	s_mov_b32 m0, s59
	s_nop 0
	global_load_lds_dwordx4 v[130:131], off
	s_mov_b32 m0, s60
	s_nop 0
	global_load_lds_dwordx4 v[132:133], off
	s_branch .Lpeel_disp_ino
.Lpeel_disp_ino:
	s_add_u32 s0, s76, 0xfff80080
	s_addc_u32 s1, s77, -1
	s_and_b64 s[70:71], s[70:71], exec
	s_cselect_b32 vcc_hi, s21, s1
	s_cselect_b32 vcc_lo, s22, s0
	s_cselect_b32 s71, s23, s41
	s_cselect_b32 s70, s39, s7
	s_add_i32 s0, 0, 0x10000
	s_add_i32 s1, 0, 0x14000
	v_add_u32_e32 v146, s0, v1
	v_add_u32_e32 v174, s1, v1
	ds_read_b128 v[134:137], v146
	ds_read_b128 v[138:141], v146 offset:1024
	ds_read_b128 v[142:145], v146 offset:2048
	ds_read_b128 v[146:149], v146 offset:3072
	ds_read_b128 v[150:153], v174
	ds_read_b128 v[154:157], v174 offset:1024
	ds_read_b128 v[158:161], v174 offset:2048
	ds_read_b128 v[174:177], v174 offset:3072
	s_add_i32 m0, s67, 0xc000
	ds_read_b128 v[178:181], v222
	ds_read_b128 v[182:185], v222 offset:1024
	ds_read_b128 v[186:189], v222 offset:2048
	ds_read_b128 v[190:193], v222 offset:3072
	ds_read_b128 v[204:207], v222 offset:4096
	ds_read_b128 v[208:211], v222 offset:5120
	ds_read_b128 v[212:215], v222 offset:6144
	ds_read_b128 v[216:219], v222 offset:7168
	global_load_lds_dwordx4 v170, s[76:77]
	s_add_i32 m0, s67, 0xe000
	s_nop 0
	global_load_lds_dwordx4 v172, s[76:77]
	s_waitcnt vmcnt(8)
	s_waitcnt lgkmcnt(0)
	s_barrier
	s_waitcnt lgkmcnt(0)
	v_mfma_f32_16x16x32_bf16 v[126:129], v[134:137], v[178:181], 0
	v_mfma_f32_16x16x32_bf16 v[126:129], v[138:141], v[182:185], v[126:129]
	v_mfma_f32_16x16x32_bf16 v[122:125], v[146:149], v[182:185], 0
	v_mfma_f32_16x16x32_bf16 v[122:125], v[142:145], v[178:181], v[122:125]
	v_mfma_f32_16x16x32_bf16 v[118:121], v[150:153], v[178:181], 0
	v_mfma_f32_16x16x32_bf16 v[118:121], v[154:157], v[182:185], v[118:121]
	v_mfma_f32_16x16x32_bf16 v[114:117], v[174:177], v[182:185], 0
	v_mfma_f32_16x16x32_bf16 v[114:117], v[158:161], v[178:181], v[114:117]
	v_mfma_f32_16x16x32_bf16 v[98:101], v[158:161], v[186:189], 0
	v_mfma_f32_16x16x32_bf16 v[98:101], v[174:177], v[190:193], v[98:101]
	v_mfma_f32_16x16x32_bf16 v[102:105], v[154:157], v[190:193], 0
	v_mfma_f32_16x16x32_bf16 v[102:105], v[150:153], v[186:189], v[102:105]
	v_mfma_f32_16x16x32_bf16 v[106:109], v[142:145], v[186:189], 0
	v_mfma_f32_16x16x32_bf16 v[106:109], v[146:149], v[190:193], v[106:109]
	v_mfma_f32_16x16x32_bf16 v[110:113], v[138:141], v[190:193], 0
	v_mfma_f32_16x16x32_bf16 v[110:113], v[134:137], v[186:189], v[110:113]
	v_mfma_f32_16x16x32_bf16 v[94:97], v[134:137], v[204:207], 0
	v_mfma_f32_16x16x32_bf16 v[94:97], v[138:141], v[208:211], v[94:97]
	v_mfma_f32_16x16x32_bf16 v[90:93], v[146:149], v[208:211], 0
	v_mfma_f32_16x16x32_bf16 v[90:93], v[142:145], v[204:207], v[90:93]
	v_mfma_f32_16x16x32_bf16 v[86:89], v[150:153], v[204:207], 0
	v_mfma_f32_16x16x32_bf16 v[86:89], v[154:157], v[208:211], v[86:89]
	v_mfma_f32_16x16x32_bf16 v[82:85], v[174:177], v[208:211], 0
	v_mfma_f32_16x16x32_bf16 v[82:85], v[158:161], v[204:207], v[82:85]
	v_mfma_f32_16x16x32_bf16 v[66:69], v[158:161], v[212:215], 0
	v_mfma_f32_16x16x32_bf16 v[66:69], v[174:177], v[216:219], v[66:69]
	v_mfma_f32_16x16x32_bf16 v[70:73], v[154:157], v[216:219], 0
	v_mfma_f32_16x16x32_bf16 v[70:73], v[150:153], v[212:215], v[70:73]
	v_mfma_f32_16x16x32_bf16 v[74:77], v[142:145], v[212:215], 0
	v_mfma_f32_16x16x32_bf16 v[74:77], v[146:149], v[216:219], v[74:77]
	v_mfma_f32_16x16x32_bf16 v[78:81], v[138:141], v[216:219], 0
	v_mfma_f32_16x16x32_bf16 v[78:81], v[134:137], v[212:215], v[78:81]
	s_barrier
	s_add_i32 s0, s0, s54
	s_mov_b32 m0, s0
	ds_read_b128 v[178:181], v222 offset:16384
	ds_read_b128 v[182:185], v222 offset:17408
	ds_read_b128 v[186:189], v222 offset:18432
	ds_read_b128 v[190:193], v222 offset:19456
	ds_read_b128 v[204:207], v222 offset:20480
	ds_read_b128 v[208:211], v222 offset:21504
	ds_read_b128 v[212:215], v222 offset:22528
	ds_read_b128 v[216:219], v222 offset:23552
	global_load_lds_dwordx4 v164, s[70:71]
	s_add_i32 m0, s0, 0x2000
	s_add_u32 s44, s70, 0x80000
	s_addc_u32 s45, s71, 0
	s_add_i32 s0, s1, s54
	global_load_lds_dwordx4 v162, s[70:71]
	s_mov_b32 m0, s0
	s_nop 0
	global_load_lds_dwordx4 v164, s[44:45]
	s_add_i32 m0, s0, 0x2000
	s_nop 0
	global_load_lds_dwordx4 v162, s[44:45]
	s_mov_b32 m0, s67
	s_nop 0
	global_load_lds_dwordx4 v164, vcc
	s_mov_b32 m0, s68
	s_nop 0
	global_load_lds_dwordx4 v162, vcc
	s_waitcnt vmcnt(8)
	s_waitcnt lgkmcnt(0)
	s_barrier
	s_waitcnt lgkmcnt(0)
	v_mfma_f32_16x16x32_bf16 v[62:65], v[134:137], v[178:181], 0
	v_mfma_f32_16x16x32_bf16 v[62:65], v[138:141], v[182:185], v[62:65]
	v_mfma_f32_16x16x32_bf16 v[58:61], v[146:149], v[182:185], 0
	v_mfma_f32_16x16x32_bf16 v[58:61], v[142:145], v[178:181], v[58:61]
	v_mfma_f32_16x16x32_bf16 v[54:57], v[150:153], v[178:181], 0
	v_mfma_f32_16x16x32_bf16 v[54:57], v[154:157], v[182:185], v[54:57]
	v_mfma_f32_16x16x32_bf16 v[50:53], v[174:177], v[182:185], 0
	v_mfma_f32_16x16x32_bf16 v[50:53], v[158:161], v[178:181], v[50:53]
	v_mfma_f32_16x16x32_bf16 v[34:37], v[158:161], v[186:189], 0
	v_mfma_f32_16x16x32_bf16 v[34:37], v[174:177], v[190:193], v[34:37]
	v_mfma_f32_16x16x32_bf16 v[38:41], v[154:157], v[190:193], 0
	v_mfma_f32_16x16x32_bf16 v[38:41], v[150:153], v[186:189], v[38:41]
	v_mfma_f32_16x16x32_bf16 v[42:45], v[142:145], v[186:189], 0
	v_mfma_f32_16x16x32_bf16 v[42:45], v[146:149], v[190:193], v[42:45]
	v_mfma_f32_16x16x32_bf16 v[46:49], v[138:141], v[190:193], 0
	v_mfma_f32_16x16x32_bf16 v[46:49], v[134:137], v[186:189], v[46:49]
	v_mfma_f32_16x16x32_bf16 v[30:33], v[134:137], v[204:207], 0
	v_mfma_f32_16x16x32_bf16 v[30:33], v[138:141], v[208:211], v[30:33]
	v_mfma_f32_16x16x32_bf16 v[26:29], v[146:149], v[208:211], 0
	v_mfma_f32_16x16x32_bf16 v[26:29], v[142:145], v[204:207], v[26:29]
	v_mfma_f32_16x16x32_bf16 v[22:25], v[150:153], v[204:207], 0
	v_mfma_f32_16x16x32_bf16 v[22:25], v[154:157], v[208:211], v[22:25]
	v_mfma_f32_16x16x32_bf16 v[18:21], v[174:177], v[208:211], 0
	v_mfma_f32_16x16x32_bf16 v[18:21], v[158:161], v[204:207], v[18:21]
	v_mfma_f32_16x16x32_bf16 v[2:5], v[158:161], v[212:215], 0
	v_mfma_f32_16x16x32_bf16 v[2:5], v[174:177], v[216:219], v[2:5]
	v_mfma_f32_16x16x32_bf16 v[6:9], v[154:157], v[216:219], 0
	v_mfma_f32_16x16x32_bf16 v[6:9], v[150:153], v[212:215], v[6:9]
	v_mfma_f32_16x16x32_bf16 v[10:13], v[142:145], v[212:215], 0
	v_mfma_f32_16x16x32_bf16 v[10:13], v[146:149], v[216:219], v[10:13]
	v_mfma_f32_16x16x32_bf16 v[14:17], v[138:141], v[216:219], 0
	v_mfma_f32_16x16x32_bf16 v[14:17], v[134:137], v[212:215], v[14:17]
	s_barrier
	s_add_i32 s0, 0, 0x18000
	s_add_i32 s1, 0, 0x1c000
	v_add_u32_e32 v146, s0, v1
	v_add_u32_e32 v174, s1, v1
	ds_read_b128 v[134:137], v146
	ds_read_b128 v[138:141], v146 offset:1024
	ds_read_b128 v[142:145], v146 offset:2048
	ds_read_b128 v[146:149], v146 offset:3072
	ds_read_b128 v[150:153], v174
	ds_read_b128 v[154:157], v174 offset:1024
	ds_read_b128 v[158:161], v174 offset:2048
	ds_read_b128 v[174:177], v174 offset:3072
	s_add_u32 s44, vcc_lo, 0x80000
	s_addc_u32 s45, vcc_hi, 0
	s_mov_b32 m0, s8
	ds_read_b128 v[178:181], v222 offset:32768
	ds_read_b128 v[182:185], v222 offset:33792
	ds_read_b128 v[186:189], v222 offset:34816
	ds_read_b128 v[190:193], v222 offset:35840
	ds_read_b128 v[204:207], v222 offset:36864
	ds_read_b128 v[208:211], v222 offset:37888
	ds_read_b128 v[212:215], v222 offset:38912
	ds_read_b128 v[216:219], v222 offset:39936
	global_load_lds_dwordx4 v164, s[44:45]
	s_mov_b32 m0, s9
	s_nop 0
	global_load_lds_dwordx4 v162, s[44:45]
	s_waitcnt vmcnt(8)
	s_waitcnt lgkmcnt(0)
	s_barrier
	s_waitcnt lgkmcnt(0)
	v_mfma_f32_16x16x32_bf16 v[126:129], v[134:137], v[178:181], v[126:129]
	v_mfma_f32_16x16x32_bf16 v[126:129], v[138:141], v[182:185], v[126:129]
	v_mfma_f32_16x16x32_bf16 v[122:125], v[146:149], v[182:185], v[122:125]
	v_mfma_f32_16x16x32_bf16 v[122:125], v[142:145], v[178:181], v[122:125]
	v_mfma_f32_16x16x32_bf16 v[118:121], v[150:153], v[178:181], v[118:121]
	v_mfma_f32_16x16x32_bf16 v[118:121], v[154:157], v[182:185], v[118:121]
	v_mfma_f32_16x16x32_bf16 v[114:117], v[174:177], v[182:185], v[114:117]
	v_mfma_f32_16x16x32_bf16 v[114:117], v[158:161], v[178:181], v[114:117]
	v_mfma_f32_16x16x32_bf16 v[98:101], v[158:161], v[186:189], v[98:101]
	v_mfma_f32_16x16x32_bf16 v[98:101], v[174:177], v[190:193], v[98:101]
	v_mfma_f32_16x16x32_bf16 v[102:105], v[154:157], v[190:193], v[102:105]
	v_mfma_f32_16x16x32_bf16 v[102:105], v[150:153], v[186:189], v[102:105]
	v_mfma_f32_16x16x32_bf16 v[106:109], v[142:145], v[186:189], v[106:109]
	v_mfma_f32_16x16x32_bf16 v[106:109], v[146:149], v[190:193], v[106:109]
	v_mfma_f32_16x16x32_bf16 v[110:113], v[138:141], v[190:193], v[110:113]
	v_mfma_f32_16x16x32_bf16 v[110:113], v[134:137], v[186:189], v[110:113]
	v_mfma_f32_16x16x32_bf16 v[94:97], v[134:137], v[204:207], v[94:97]
	v_mfma_f32_16x16x32_bf16 v[94:97], v[138:141], v[208:211], v[94:97]
	v_mfma_f32_16x16x32_bf16 v[90:93], v[146:149], v[208:211], v[90:93]
	v_mfma_f32_16x16x32_bf16 v[90:93], v[142:145], v[204:207], v[90:93]
	v_mfma_f32_16x16x32_bf16 v[86:89], v[150:153], v[204:207], v[86:89]
	v_mfma_f32_16x16x32_bf16 v[86:89], v[154:157], v[208:211], v[86:89]
	v_mfma_f32_16x16x32_bf16 v[82:85], v[174:177], v[208:211], v[82:85]
	v_mfma_f32_16x16x32_bf16 v[82:85], v[158:161], v[204:207], v[82:85]
	v_mfma_f32_16x16x32_bf16 v[66:69], v[158:161], v[212:215], v[66:69]
	v_mfma_f32_16x16x32_bf16 v[66:69], v[174:177], v[216:219], v[66:69]
	v_mfma_f32_16x16x32_bf16 v[70:73], v[154:157], v[216:219], v[70:73]
	v_mfma_f32_16x16x32_bf16 v[70:73], v[150:153], v[212:215], v[70:73]
	v_mfma_f32_16x16x32_bf16 v[74:77], v[142:145], v[212:215], v[74:77]
	v_mfma_f32_16x16x32_bf16 v[74:77], v[146:149], v[216:219], v[74:77]
	v_mfma_f32_16x16x32_bf16 v[78:81], v[138:141], v[216:219], v[78:81]
	v_mfma_f32_16x16x32_bf16 v[78:81], v[134:137], v[212:215], v[78:81]
	s_barrier
	s_add_u32 s98, s70, 0x80
	s_addc_u32 s99, s71, 0
	s_add_u32 s100, vcc_lo, 0x80
	s_addc_u32 s101, vcc_hi, 0
	s_add_i32 s0, s0, s54
	s_mov_b32 m0, s0
	ds_read_b128 v[178:181], v222 offset:49152
	ds_read_b128 v[182:185], v222 offset:50176
	ds_read_b128 v[186:189], v222 offset:51200
	ds_read_b128 v[190:193], v222 offset:52224
	ds_read_b128 v[204:207], v222 offset:53248
	ds_read_b128 v[208:211], v222 offset:54272
	ds_read_b128 v[212:215], v222 offset:55296
	ds_read_b128 v[216:219], v222 offset:56320
	global_load_lds_dwordx4 v164, s[98:99]
	s_add_i32 m0, s0, 0x2000
	s_add_u32 s44, s70, 0x80080
	s_addc_u32 s45, s71, 0
	s_add_i32 s0, s1, s54
	global_load_lds_dwordx4 v162, s[98:99]
	s_mov_b32 m0, s0
	s_nop 0
	global_load_lds_dwordx4 v164, s[44:45]
	s_add_i32 m0, s0, 0x2000
	s_nop 0
	global_load_lds_dwordx4 v162, s[44:45]
	s_mov_b32 m0, s27
	s_nop 0
	global_load_lds_dwordx4 v164, s[100:101]
	s_mov_b32 m0, s26
	s_nop 0
	global_load_lds_dwordx4 v162, s[100:101]
	s_add_i32 s43, s43, 2
	s_add_u32 s76, s76, 0x100
	s_addc_u32 s77, s77, 0
	s_add_u32 s7, s7, 0x100
	s_addc_u32 s41, s41, 0
	s_cmp_eq_u32 s43, 28
	s_cselect_b64 s[70:71], -1, 0
	s_and_b64 s[100:101], s[70:71], s[10:11]
	s_add_u32 s0, s76, 0xfff80080
	s_addc_u32 s1, s77, -1
	s_and_b64 s[70:71], s[70:71], exec
	s_cselect_b32 vcc_hi, s21, s1
	s_cselect_b32 vcc_lo, s22, s0
	s_cselect_b32 s71, s23, s41
	s_cselect_b32 s70, s39, s7
	s_cmp_gt_u32 s43, 29
	s_waitcnt vmcnt(8)
	s_waitcnt lgkmcnt(0)
	s_barrier
	s_waitcnt lgkmcnt(0)
	v_mfma_f32_16x16x32_bf16 v[62:65], v[134:137], v[178:181], v[62:65]
	v_mfma_f32_16x16x32_bf16 v[62:65], v[138:141], v[182:185], v[62:65]
	v_mfma_f32_16x16x32_bf16 v[58:61], v[146:149], v[182:185], v[58:61]
	v_mfma_f32_16x16x32_bf16 v[58:61], v[142:145], v[178:181], v[58:61]
	v_mfma_f32_16x16x32_bf16 v[54:57], v[150:153], v[178:181], v[54:57]
	v_mfma_f32_16x16x32_bf16 v[54:57], v[154:157], v[182:185], v[54:57]
	v_mfma_f32_16x16x32_bf16 v[50:53], v[174:177], v[182:185], v[50:53]
	v_mfma_f32_16x16x32_bf16 v[50:53], v[158:161], v[178:181], v[50:53]
	v_mfma_f32_16x16x32_bf16 v[34:37], v[158:161], v[186:189], v[34:37]
	v_mfma_f32_16x16x32_bf16 v[34:37], v[174:177], v[190:193], v[34:37]
	v_mfma_f32_16x16x32_bf16 v[38:41], v[154:157], v[190:193], v[38:41]
	v_mfma_f32_16x16x32_bf16 v[38:41], v[150:153], v[186:189], v[38:41]
	v_mfma_f32_16x16x32_bf16 v[42:45], v[142:145], v[186:189], v[42:45]
	v_mfma_f32_16x16x32_bf16 v[42:45], v[146:149], v[190:193], v[42:45]
	v_mfma_f32_16x16x32_bf16 v[46:49], v[138:141], v[190:193], v[46:49]
	v_mfma_f32_16x16x32_bf16 v[46:49], v[134:137], v[186:189], v[46:49]
	v_mfma_f32_16x16x32_bf16 v[30:33], v[134:137], v[204:207], v[30:33]
	v_mfma_f32_16x16x32_bf16 v[30:33], v[138:141], v[208:211], v[30:33]
	v_mfma_f32_16x16x32_bf16 v[26:29], v[146:149], v[208:211], v[26:29]
	v_mfma_f32_16x16x32_bf16 v[26:29], v[142:145], v[204:207], v[26:29]
	v_mfma_f32_16x16x32_bf16 v[22:25], v[150:153], v[204:207], v[22:25]
	v_mfma_f32_16x16x32_bf16 v[22:25], v[154:157], v[208:211], v[22:25]
	v_mfma_f32_16x16x32_bf16 v[18:21], v[174:177], v[208:211], v[18:21]
	v_mfma_f32_16x16x32_bf16 v[18:21], v[158:161], v[204:207], v[18:21]
	v_mfma_f32_16x16x32_bf16 v[2:5], v[158:161], v[212:215], v[2:5]
	v_mfma_f32_16x16x32_bf16 v[2:5], v[174:177], v[216:219], v[2:5]
	v_mfma_f32_16x16x32_bf16 v[6:9], v[154:157], v[216:219], v[6:9]
	v_mfma_f32_16x16x32_bf16 v[6:9], v[150:153], v[212:215], v[6:9]
	v_mfma_f32_16x16x32_bf16 v[10:13], v[142:145], v[212:215], v[10:13]
	v_mfma_f32_16x16x32_bf16 v[10:13], v[146:149], v[216:219], v[10:13]
	v_mfma_f32_16x16x32_bf16 v[14:17], v[138:141], v[216:219], v[14:17]
	v_mfma_f32_16x16x32_bf16 v[14:17], v[134:137], v[212:215], v[14:17]
	s_barrier
	s_cbranch_scc1 .LBB0_288
	s_cmp_lg_u64 s[100:101], 0
	s_cbranch_scc1 .Lrot_rare_ino
	s_branch .Lrot_body_ino
.Lrot_rare_ino:
	s_mov_b32 m0, s59
	s_nop 0
	global_load_lds_dwordx4 v[130:131], off
	s_mov_b32 m0, s60
	s_nop 0
	global_load_lds_dwordx4 v[132:133], off
	s_branch .Lrot_body_ino
.Lrot_body_ino:
	s_add_i32 s0, 0, 0x10000
	s_add_i32 s1, 0, 0x14000
	v_add_u32_e32 v146, s0, v1
	v_add_u32_e32 v174, s1, v1
	ds_read_b128 v[134:137], v146
	ds_read_b128 v[138:141], v146 offset:1024
	ds_read_b128 v[142:145], v146 offset:2048
	ds_read_b128 v[146:149], v146 offset:3072
	ds_read_b128 v[150:153], v174
	ds_read_b128 v[154:157], v174 offset:1024
	ds_read_b128 v[158:161], v174 offset:2048
	ds_read_b128 v[174:177], v174 offset:3072
	s_add_i32 m0, s67, 0xc000
	ds_read_b128 v[178:181], v222
	ds_read_b128 v[182:185], v222 offset:1024
	ds_read_b128 v[186:189], v222 offset:2048
	ds_read_b128 v[190:193], v222 offset:3072
	ds_read_b128 v[204:207], v222 offset:4096
	ds_read_b128 v[208:211], v222 offset:5120
	ds_read_b128 v[212:215], v222 offset:6144
	ds_read_b128 v[216:219], v222 offset:7168
	global_load_lds_dwordx4 v170, s[76:77]
	s_add_i32 m0, s67, 0xe000
	s_nop 0
	global_load_lds_dwordx4 v172, s[76:77]
	s_waitcnt vmcnt(8)
	s_waitcnt lgkmcnt(0)
	s_barrier
	s_waitcnt lgkmcnt(0)
	v_mfma_f32_16x16x32_bf16 v[126:129], v[134:137], v[178:181], v[126:129]
	v_mfma_f32_16x16x32_bf16 v[126:129], v[138:141], v[182:185], v[126:129]
	v_mfma_f32_16x16x32_bf16 v[122:125], v[146:149], v[182:185], v[122:125]
	v_mfma_f32_16x16x32_bf16 v[122:125], v[142:145], v[178:181], v[122:125]
	v_mfma_f32_16x16x32_bf16 v[118:121], v[150:153], v[178:181], v[118:121]
	v_mfma_f32_16x16x32_bf16 v[118:121], v[154:157], v[182:185], v[118:121]
	v_mfma_f32_16x16x32_bf16 v[114:117], v[174:177], v[182:185], v[114:117]
	v_mfma_f32_16x16x32_bf16 v[114:117], v[158:161], v[178:181], v[114:117]
	v_mfma_f32_16x16x32_bf16 v[98:101], v[158:161], v[186:189], v[98:101]
	v_mfma_f32_16x16x32_bf16 v[98:101], v[174:177], v[190:193], v[98:101]
	v_mfma_f32_16x16x32_bf16 v[102:105], v[154:157], v[190:193], v[102:105]
	v_mfma_f32_16x16x32_bf16 v[102:105], v[150:153], v[186:189], v[102:105]
	v_mfma_f32_16x16x32_bf16 v[106:109], v[142:145], v[186:189], v[106:109]
	v_mfma_f32_16x16x32_bf16 v[106:109], v[146:149], v[190:193], v[106:109]
	v_mfma_f32_16x16x32_bf16 v[110:113], v[138:141], v[190:193], v[110:113]
	v_mfma_f32_16x16x32_bf16 v[110:113], v[134:137], v[186:189], v[110:113]
	v_mfma_f32_16x16x32_bf16 v[94:97], v[134:137], v[204:207], v[94:97]
	v_mfma_f32_16x16x32_bf16 v[94:97], v[138:141], v[208:211], v[94:97]
	v_mfma_f32_16x16x32_bf16 v[90:93], v[146:149], v[208:211], v[90:93]
	v_mfma_f32_16x16x32_bf16 v[90:93], v[142:145], v[204:207], v[90:93]
	v_mfma_f32_16x16x32_bf16 v[86:89], v[150:153], v[204:207], v[86:89]
	v_mfma_f32_16x16x32_bf16 v[86:89], v[154:157], v[208:211], v[86:89]
	v_mfma_f32_16x16x32_bf16 v[82:85], v[174:177], v[208:211], v[82:85]
	v_mfma_f32_16x16x32_bf16 v[82:85], v[158:161], v[204:207], v[82:85]
	v_mfma_f32_16x16x32_bf16 v[66:69], v[158:161], v[212:215], v[66:69]
	v_mfma_f32_16x16x32_bf16 v[66:69], v[174:177], v[216:219], v[66:69]
	v_mfma_f32_16x16x32_bf16 v[70:73], v[154:157], v[216:219], v[70:73]
	v_mfma_f32_16x16x32_bf16 v[70:73], v[150:153], v[212:215], v[70:73]
	v_mfma_f32_16x16x32_bf16 v[74:77], v[142:145], v[212:215], v[74:77]
	v_mfma_f32_16x16x32_bf16 v[74:77], v[146:149], v[216:219], v[74:77]
	v_mfma_f32_16x16x32_bf16 v[78:81], v[138:141], v[216:219], v[78:81]
	v_mfma_f32_16x16x32_bf16 v[78:81], v[134:137], v[212:215], v[78:81]
	s_barrier
	s_add_i32 s0, s0, s54
	s_mov_b32 m0, s0
	ds_read_b128 v[178:181], v222 offset:16384
	ds_read_b128 v[182:185], v222 offset:17408
	ds_read_b128 v[186:189], v222 offset:18432
	ds_read_b128 v[190:193], v222 offset:19456
	ds_read_b128 v[204:207], v222 offset:20480
	ds_read_b128 v[208:211], v222 offset:21504
	ds_read_b128 v[212:215], v222 offset:22528
	ds_read_b128 v[216:219], v222 offset:23552
	global_load_lds_dwordx4 v164, s[70:71]
	s_add_i32 m0, s0, 0x2000
	s_add_u32 s44, s70, 0x80000
	s_addc_u32 s45, s71, 0
	s_add_i32 s0, s1, s54
	global_load_lds_dwordx4 v162, s[70:71]
	s_mov_b32 m0, s0
	s_nop 0
	global_load_lds_dwordx4 v164, s[44:45]
	s_add_i32 m0, s0, 0x2000
	s_nop 0
	global_load_lds_dwordx4 v162, s[44:45]
	s_mov_b32 m0, s67
	s_nop 0
	global_load_lds_dwordx4 v164, vcc
	s_mov_b32 m0, s68
	s_nop 0
	global_load_lds_dwordx4 v162, vcc
	s_waitcnt vmcnt(8)
	s_waitcnt lgkmcnt(0)
	s_barrier
	s_waitcnt lgkmcnt(0)
	v_mfma_f32_16x16x32_bf16 v[62:65], v[134:137], v[178:181], v[62:65]
	v_mfma_f32_16x16x32_bf16 v[62:65], v[138:141], v[182:185], v[62:65]
	v_mfma_f32_16x16x32_bf16 v[58:61], v[146:149], v[182:185], v[58:61]
	v_mfma_f32_16x16x32_bf16 v[58:61], v[142:145], v[178:181], v[58:61]
	v_mfma_f32_16x16x32_bf16 v[54:57], v[150:153], v[178:181], v[54:57]
	v_mfma_f32_16x16x32_bf16 v[54:57], v[154:157], v[182:185], v[54:57]
	v_mfma_f32_16x16x32_bf16 v[50:53], v[174:177], v[182:185], v[50:53]
	v_mfma_f32_16x16x32_bf16 v[50:53], v[158:161], v[178:181], v[50:53]
	v_mfma_f32_16x16x32_bf16 v[34:37], v[158:161], v[186:189], v[34:37]
	v_mfma_f32_16x16x32_bf16 v[34:37], v[174:177], v[190:193], v[34:37]
	v_mfma_f32_16x16x32_bf16 v[38:41], v[154:157], v[190:193], v[38:41]
	v_mfma_f32_16x16x32_bf16 v[38:41], v[150:153], v[186:189], v[38:41]
	v_mfma_f32_16x16x32_bf16 v[42:45], v[142:145], v[186:189], v[42:45]
	v_mfma_f32_16x16x32_bf16 v[42:45], v[146:149], v[190:193], v[42:45]
	v_mfma_f32_16x16x32_bf16 v[46:49], v[138:141], v[190:193], v[46:49]
	v_mfma_f32_16x16x32_bf16 v[46:49], v[134:137], v[186:189], v[46:49]
	v_mfma_f32_16x16x32_bf16 v[30:33], v[134:137], v[204:207], v[30:33]
	v_mfma_f32_16x16x32_bf16 v[30:33], v[138:141], v[208:211], v[30:33]
	v_mfma_f32_16x16x32_bf16 v[26:29], v[146:149], v[208:211], v[26:29]
	v_mfma_f32_16x16x32_bf16 v[26:29], v[142:145], v[204:207], v[26:29]
	v_mfma_f32_16x16x32_bf16 v[22:25], v[150:153], v[204:207], v[22:25]
	v_mfma_f32_16x16x32_bf16 v[22:25], v[154:157], v[208:211], v[22:25]
	v_mfma_f32_16x16x32_bf16 v[18:21], v[174:177], v[208:211], v[18:21]
	v_mfma_f32_16x16x32_bf16 v[18:21], v[158:161], v[204:207], v[18:21]
	v_mfma_f32_16x16x32_bf16 v[2:5], v[158:161], v[212:215], v[2:5]
	v_mfma_f32_16x16x32_bf16 v[2:5], v[174:177], v[216:219], v[2:5]
	v_mfma_f32_16x16x32_bf16 v[6:9], v[154:157], v[216:219], v[6:9]
	v_mfma_f32_16x16x32_bf16 v[6:9], v[150:153], v[212:215], v[6:9]
	v_mfma_f32_16x16x32_bf16 v[10:13], v[142:145], v[212:215], v[10:13]
	v_mfma_f32_16x16x32_bf16 v[10:13], v[146:149], v[216:219], v[10:13]
	v_mfma_f32_16x16x32_bf16 v[14:17], v[138:141], v[216:219], v[14:17]
	v_mfma_f32_16x16x32_bf16 v[14:17], v[134:137], v[212:215], v[14:17]
	s_barrier
	s_add_i32 s0, 0, 0x18000
	s_add_i32 s1, 0, 0x1c000
	v_add_u32_e32 v146, s0, v1
	v_add_u32_e32 v174, s1, v1
	ds_read_b128 v[134:137], v146
	ds_read_b128 v[138:141], v146 offset:1024
	ds_read_b128 v[142:145], v146 offset:2048
	ds_read_b128 v[146:149], v146 offset:3072
	ds_read_b128 v[150:153], v174
	ds_read_b128 v[154:157], v174 offset:1024
	ds_read_b128 v[158:161], v174 offset:2048
	ds_read_b128 v[174:177], v174 offset:3072
	s_add_u32 s44, vcc_lo, 0x80000
	s_addc_u32 s45, vcc_hi, 0
	s_mov_b32 m0, s8
	ds_read_b128 v[178:181], v222 offset:32768
	ds_read_b128 v[182:185], v222 offset:33792
	ds_read_b128 v[186:189], v222 offset:34816
	ds_read_b128 v[190:193], v222 offset:35840
	ds_read_b128 v[204:207], v222 offset:36864
	ds_read_b128 v[208:211], v222 offset:37888
	ds_read_b128 v[212:215], v222 offset:38912
	ds_read_b128 v[216:219], v222 offset:39936
	global_load_lds_dwordx4 v164, s[44:45]
	s_mov_b32 m0, s9
	s_nop 0
	global_load_lds_dwordx4 v162, s[44:45]
	s_waitcnt vmcnt(8)
	s_waitcnt lgkmcnt(0)
	s_barrier
	s_waitcnt lgkmcnt(0)
	v_mfma_f32_16x16x32_bf16 v[126:129], v[134:137], v[178:181], v[126:129]
	v_mfma_f32_16x16x32_bf16 v[126:129], v[138:141], v[182:185], v[126:129]
	v_mfma_f32_16x16x32_bf16 v[122:125], v[146:149], v[182:185], v[122:125]
	v_mfma_f32_16x16x32_bf16 v[122:125], v[142:145], v[178:181], v[122:125]
	v_mfma_f32_16x16x32_bf16 v[118:121], v[150:153], v[178:181], v[118:121]
	v_mfma_f32_16x16x32_bf16 v[118:121], v[154:157], v[182:185], v[118:121]
	v_mfma_f32_16x16x32_bf16 v[114:117], v[174:177], v[182:185], v[114:117]
	v_mfma_f32_16x16x32_bf16 v[114:117], v[158:161], v[178:181], v[114:117]
	v_mfma_f32_16x16x32_bf16 v[98:101], v[158:161], v[186:189], v[98:101]
	v_mfma_f32_16x16x32_bf16 v[98:101], v[174:177], v[190:193], v[98:101]
	v_mfma_f32_16x16x32_bf16 v[102:105], v[154:157], v[190:193], v[102:105]
	v_mfma_f32_16x16x32_bf16 v[102:105], v[150:153], v[186:189], v[102:105]
	v_mfma_f32_16x16x32_bf16 v[106:109], v[142:145], v[186:189], v[106:109]
	v_mfma_f32_16x16x32_bf16 v[106:109], v[146:149], v[190:193], v[106:109]
	v_mfma_f32_16x16x32_bf16 v[110:113], v[138:141], v[190:193], v[110:113]
	v_mfma_f32_16x16x32_bf16 v[110:113], v[134:137], v[186:189], v[110:113]
	v_mfma_f32_16x16x32_bf16 v[94:97], v[134:137], v[204:207], v[94:97]
	v_mfma_f32_16x16x32_bf16 v[94:97], v[138:141], v[208:211], v[94:97]
	v_mfma_f32_16x16x32_bf16 v[90:93], v[146:149], v[208:211], v[90:93]
	v_mfma_f32_16x16x32_bf16 v[90:93], v[142:145], v[204:207], v[90:93]
	v_mfma_f32_16x16x32_bf16 v[86:89], v[150:153], v[204:207], v[86:89]
	v_mfma_f32_16x16x32_bf16 v[86:89], v[154:157], v[208:211], v[86:89]
	v_mfma_f32_16x16x32_bf16 v[82:85], v[174:177], v[208:211], v[82:85]
	v_mfma_f32_16x16x32_bf16 v[82:85], v[158:161], v[204:207], v[82:85]
	v_mfma_f32_16x16x32_bf16 v[66:69], v[158:161], v[212:215], v[66:69]
	v_mfma_f32_16x16x32_bf16 v[66:69], v[174:177], v[216:219], v[66:69]
	v_mfma_f32_16x16x32_bf16 v[70:73], v[154:157], v[216:219], v[70:73]
	v_mfma_f32_16x16x32_bf16 v[70:73], v[150:153], v[212:215], v[70:73]
	v_mfma_f32_16x16x32_bf16 v[74:77], v[142:145], v[212:215], v[74:77]
	v_mfma_f32_16x16x32_bf16 v[74:77], v[146:149], v[216:219], v[74:77]
	v_mfma_f32_16x16x32_bf16 v[78:81], v[138:141], v[216:219], v[78:81]
	v_mfma_f32_16x16x32_bf16 v[78:81], v[134:137], v[212:215], v[78:81]
	s_barrier
	s_add_u32 s98, s70, 0x80
	s_addc_u32 s99, s71, 0
	s_add_u32 s100, vcc_lo, 0x80
	s_addc_u32 s101, vcc_hi, 0
	s_add_i32 s0, s0, s54
	s_mov_b32 m0, s0
	ds_read_b128 v[178:181], v222 offset:49152
	ds_read_b128 v[182:185], v222 offset:50176
	ds_read_b128 v[186:189], v222 offset:51200
	ds_read_b128 v[190:193], v222 offset:52224
	ds_read_b128 v[204:207], v222 offset:53248
	ds_read_b128 v[208:211], v222 offset:54272
	ds_read_b128 v[212:215], v222 offset:55296
	ds_read_b128 v[216:219], v222 offset:56320
	global_load_lds_dwordx4 v164, s[98:99]
	s_add_i32 m0, s0, 0x2000
	s_add_u32 s44, s70, 0x80080
	s_addc_u32 s45, s71, 0
	s_add_i32 s0, s1, s54
	global_load_lds_dwordx4 v162, s[98:99]
	s_mov_b32 m0, s0
	s_nop 0
	global_load_lds_dwordx4 v164, s[44:45]
	s_add_i32 m0, s0, 0x2000
	s_nop 0
	global_load_lds_dwordx4 v162, s[44:45]
	s_mov_b32 m0, s27
	s_nop 0
	global_load_lds_dwordx4 v164, s[100:101]
	s_mov_b32 m0, s26
	s_nop 0
	global_load_lds_dwordx4 v162, s[100:101]
	s_add_i32 s43, s43, 2
	s_add_u32 s76, s76, 0x100
	s_addc_u32 s77, s77, 0
	s_add_u32 s7, s7, 0x100
	s_addc_u32 s41, s41, 0
	s_cmp_eq_u32 s43, 28
	s_cselect_b64 s[70:71], -1, 0
	s_and_b64 s[100:101], s[70:71], s[10:11]
	s_add_u32 s0, s76, 0xfff80080
	s_addc_u32 s1, s77, -1
	s_and_b64 s[70:71], s[70:71], exec
	s_cselect_b32 vcc_hi, s21, s1
	s_cselect_b32 vcc_lo, s22, s0
	s_cselect_b32 s71, s23, s41
	s_cselect_b32 s70, s39, s7
	s_cmp_gt_u32 s43, 29
	s_waitcnt vmcnt(8)
	s_waitcnt lgkmcnt(0)
	s_barrier
	s_waitcnt lgkmcnt(0)
	v_mfma_f32_16x16x32_bf16 v[62:65], v[134:137], v[178:181], v[62:65]
	v_mfma_f32_16x16x32_bf16 v[62:65], v[138:141], v[182:185], v[62:65]
	v_mfma_f32_16x16x32_bf16 v[58:61], v[146:149], v[182:185], v[58:61]
	v_mfma_f32_16x16x32_bf16 v[58:61], v[142:145], v[178:181], v[58:61]
	v_mfma_f32_16x16x32_bf16 v[54:57], v[150:153], v[178:181], v[54:57]
	v_mfma_f32_16x16x32_bf16 v[54:57], v[154:157], v[182:185], v[54:57]
	v_mfma_f32_16x16x32_bf16 v[50:53], v[174:177], v[182:185], v[50:53]
	v_mfma_f32_16x16x32_bf16 v[50:53], v[158:161], v[178:181], v[50:53]
	v_mfma_f32_16x16x32_bf16 v[34:37], v[158:161], v[186:189], v[34:37]
	v_mfma_f32_16x16x32_bf16 v[34:37], v[174:177], v[190:193], v[34:37]
	v_mfma_f32_16x16x32_bf16 v[38:41], v[154:157], v[190:193], v[38:41]
	v_mfma_f32_16x16x32_bf16 v[38:41], v[150:153], v[186:189], v[38:41]
	v_mfma_f32_16x16x32_bf16 v[42:45], v[142:145], v[186:189], v[42:45]
	v_mfma_f32_16x16x32_bf16 v[42:45], v[146:149], v[190:193], v[42:45]
	v_mfma_f32_16x16x32_bf16 v[46:49], v[138:141], v[190:193], v[46:49]
	v_mfma_f32_16x16x32_bf16 v[46:49], v[134:137], v[186:189], v[46:49]
	v_mfma_f32_16x16x32_bf16 v[30:33], v[134:137], v[204:207], v[30:33]
	v_mfma_f32_16x16x32_bf16 v[30:33], v[138:141], v[208:211], v[30:33]
	v_mfma_f32_16x16x32_bf16 v[26:29], v[146:149], v[208:211], v[26:29]
	v_mfma_f32_16x16x32_bf16 v[26:29], v[142:145], v[204:207], v[26:29]
	v_mfma_f32_16x16x32_bf16 v[22:25], v[150:153], v[204:207], v[22:25]
	v_mfma_f32_16x16x32_bf16 v[22:25], v[154:157], v[208:211], v[22:25]
	v_mfma_f32_16x16x32_bf16 v[18:21], v[174:177], v[208:211], v[18:21]
	v_mfma_f32_16x16x32_bf16 v[18:21], v[158:161], v[204:207], v[18:21]
	v_mfma_f32_16x16x32_bf16 v[2:5], v[158:161], v[212:215], v[2:5]
	v_mfma_f32_16x16x32_bf16 v[2:5], v[174:177], v[216:219], v[2:5]
	v_mfma_f32_16x16x32_bf16 v[6:9], v[154:157], v[216:219], v[6:9]
	v_mfma_f32_16x16x32_bf16 v[6:9], v[150:153], v[212:215], v[6:9]
	v_mfma_f32_16x16x32_bf16 v[10:13], v[142:145], v[212:215], v[10:13]
	v_mfma_f32_16x16x32_bf16 v[10:13], v[146:149], v[216:219], v[10:13]
	v_mfma_f32_16x16x32_bf16 v[14:17], v[138:141], v[216:219], v[14:17]
	v_mfma_f32_16x16x32_bf16 v[14:17], v[134:137], v[212:215], v[14:17]
	s_barrier
	s_cbranch_scc1 .LBB0_288
	s_cmp_lg_u64 s[100:101], 0
	s_cbranch_scc1 .Lrot_rare_ino
	s_branch .Lrot_body_ino

.LBB0_509:
.LBB0_510:
	s_cmp_eq_u32 s57, 28
	s_cselect_b64 s[70:71], -1, 0
	s_and_b64 s[0:1], s[70:71], s[46:47]
	s_andn2_b64 vcc, exec, s[0:1]
	s_cbranch_vccnz .Lpeel_disp_out
	s_mov_b32 m0, s59
	s_nop 0
	global_load_lds_dwordx4 v[70:71], off
	s_mov_b32 m0, s60
	s_nop 0
	global_load_lds_dwordx4 v[72:73], off
	s_branch .Lpeel_disp_out
.Lpeel_disp_out:
	s_add_u32 s90, s76, 0x100
	s_addc_u32 s91, s77, 0
	s_and_b64 s[0:1], s[70:71], exec
	s_cselect_b32 vcc_hi, s22, s91
	s_cselect_b32 vcc_lo, s23, s90
	s_cselect_b32 s71, s41, s53
	s_cselect_b32 s70, s44, s51
	s_add_i32 s0, 0, 0x10000
	s_add_i32 s18, 0, 0x14000
	v_add_u32_e32 v114, s0, v1
	v_add_u32_e32 v154, s18, v1
	ds_read_b128 v[78:81], v114
	ds_read_b128 v[90:93], v114 offset:1024
	ds_read_b128 v[102:105], v114 offset:2048
	ds_read_b128 v[114:117], v114 offset:3072
	ds_read_b128 v[126:129], v154
	ds_read_b128 v[134:137], v154 offset:1024
	ds_read_b128 v[142:145], v154 offset:2048
	ds_read_b128 v[154:157], v154 offset:3072
	s_add_i32 m0, s29, 0xc000
	ds_read_b128 v[158:161], v237
	ds_read_b128 v[162:165], v237 offset:1024
	ds_read_b128 v[166:169], v237 offset:2048
	ds_read_b128 v[178:181], v237 offset:3072
	ds_read_b128 v[182:185], v237 offset:4096
	ds_read_b128 v[186:189], v237 offset:5120
	ds_read_b128 v[190:193], v237 offset:6144
	ds_read_b128 v[214:217], v237 offset:7168
	global_load_lds_dwordx4 v210, s[76:77]
	s_add_i32 m0, s29, 0xe000
	s_nop 0
	global_load_lds_dwordx4 v212, s[76:77]
	s_waitcnt vmcnt(8)
	s_waitcnt lgkmcnt(0)
	s_barrier
	s_waitcnt lgkmcnt(0)
	v_mfma_f32_16x16x32_bf16 v[174:177], v[78:81], v[158:161], 0
	v_mfma_f32_16x16x32_bf16 v[174:177], v[90:93], v[162:165], v[174:177]
	v_mfma_f32_16x16x32_bf16 v[170:173], v[114:117], v[162:165], 0
	v_mfma_f32_16x16x32_bf16 v[170:173], v[102:105], v[158:161], v[170:173]
	v_mfma_f32_16x16x32_bf16 v[150:153], v[126:129], v[158:161], 0
	v_mfma_f32_16x16x32_bf16 v[150:153], v[134:137], v[162:165], v[150:153]
	v_mfma_f32_16x16x32_bf16 v[146:149], v[154:157], v[162:165], 0
	v_mfma_f32_16x16x32_bf16 v[146:149], v[142:145], v[158:161], v[146:149]
	v_mfma_f32_16x16x32_bf16 v[118:121], v[142:145], v[166:169], 0
	v_mfma_f32_16x16x32_bf16 v[118:121], v[154:157], v[178:181], v[118:121]
	v_mfma_f32_16x16x32_bf16 v[122:125], v[134:137], v[178:181], 0
	v_mfma_f32_16x16x32_bf16 v[122:125], v[126:129], v[166:169], v[122:125]
	v_mfma_f32_16x16x32_bf16 v[130:133], v[102:105], v[166:169], 0
	v_mfma_f32_16x16x32_bf16 v[130:133], v[114:117], v[178:181], v[130:133]
	v_mfma_f32_16x16x32_bf16 v[138:141], v[90:93], v[178:181], 0
	v_mfma_f32_16x16x32_bf16 v[138:141], v[78:81], v[166:169], v[138:141]
	v_mfma_f32_16x16x32_bf16 v[110:113], v[78:81], v[182:185], 0
	v_mfma_f32_16x16x32_bf16 v[110:113], v[90:93], v[186:189], v[110:113]
	v_mfma_f32_16x16x32_bf16 v[106:109], v[114:117], v[186:189], 0
	v_mfma_f32_16x16x32_bf16 v[106:109], v[102:105], v[182:185], v[106:109]
	v_mfma_f32_16x16x32_bf16 v[98:101], v[126:129], v[182:185], 0
	v_mfma_f32_16x16x32_bf16 v[98:101], v[134:137], v[186:189], v[98:101]
	v_mfma_f32_16x16x32_bf16 v[94:97], v[154:157], v[186:189], 0
	v_mfma_f32_16x16x32_bf16 v[94:97], v[142:145], v[182:185], v[94:97]
	v_mfma_f32_16x16x32_bf16 v[66:69], v[142:145], v[190:193], 0
	v_mfma_f32_16x16x32_bf16 v[66:69], v[154:157], v[214:217], v[66:69]
	v_mfma_f32_16x16x32_bf16 v[74:77], v[134:137], v[214:217], 0
	v_mfma_f32_16x16x32_bf16 v[74:77], v[126:129], v[190:193], v[74:77]
	v_mfma_f32_16x16x32_bf16 v[82:85], v[102:105], v[190:193], 0
	v_mfma_f32_16x16x32_bf16 v[82:85], v[114:117], v[214:217], v[82:85]
	v_mfma_f32_16x16x32_bf16 v[86:89], v[90:93], v[214:217], 0
	v_mfma_f32_16x16x32_bf16 v[86:89], v[78:81], v[190:193], v[86:89]
	s_barrier
	s_add_i32 s0, s0, s28
	s_mov_b32 m0, s0
	ds_read_b128 v[158:161], v237 offset:16384
	ds_read_b128 v[162:165], v237 offset:17408
	ds_read_b128 v[166:169], v237 offset:18432
	ds_read_b128 v[178:181], v237 offset:19456
	ds_read_b128 v[182:185], v237 offset:20480
	ds_read_b128 v[186:189], v237 offset:21504
	ds_read_b128 v[190:193], v237 offset:22528
	ds_read_b128 v[214:217], v237 offset:23552
	global_load_lds_dwordx4 v194, s[70:71]
	s_add_i32 m0, s0, 0x2000
	s_add_u32 s0, s70, 0x80000
	s_addc_u32 s1, s71, 0
	s_add_i32 s18, s18, s28
	global_load_lds_dwordx4 v204, s[70:71]
	s_mov_b32 m0, s18
	s_nop 0
	global_load_lds_dwordx4 v194, s[0:1]
	s_add_i32 m0, s18, 0x2000
	s_nop 0
	global_load_lds_dwordx4 v204, s[0:1]
	s_mov_b32 m0, s29
	s_nop 0
	global_load_lds_dwordx4 v194, vcc
	s_mov_b32 m0, s31
	s_nop 0
	global_load_lds_dwordx4 v204, vcc
	s_waitcnt vmcnt(8)
	s_waitcnt lgkmcnt(0)
	s_barrier
	s_waitcnt lgkmcnt(0)
	v_mfma_f32_16x16x32_bf16 v[62:65], v[78:81], v[158:161], 0
	v_mfma_f32_16x16x32_bf16 v[62:65], v[90:93], v[162:165], v[62:65]
	v_mfma_f32_16x16x32_bf16 v[58:61], v[114:117], v[162:165], 0
	v_mfma_f32_16x16x32_bf16 v[58:61], v[102:105], v[158:161], v[58:61]
	v_mfma_f32_16x16x32_bf16 v[54:57], v[126:129], v[158:161], 0
	v_mfma_f32_16x16x32_bf16 v[54:57], v[134:137], v[162:165], v[54:57]
	v_mfma_f32_16x16x32_bf16 v[50:53], v[154:157], v[162:165], 0
	v_mfma_f32_16x16x32_bf16 v[50:53], v[142:145], v[158:161], v[50:53]
	v_mfma_f32_16x16x32_bf16 v[34:37], v[142:145], v[166:169], 0
	v_mfma_f32_16x16x32_bf16 v[34:37], v[154:157], v[178:181], v[34:37]
	v_mfma_f32_16x16x32_bf16 v[38:41], v[134:137], v[178:181], 0
	v_mfma_f32_16x16x32_bf16 v[38:41], v[126:129], v[166:169], v[38:41]
	v_mfma_f32_16x16x32_bf16 v[42:45], v[102:105], v[166:169], 0
	v_mfma_f32_16x16x32_bf16 v[42:45], v[114:117], v[178:181], v[42:45]
	v_mfma_f32_16x16x32_bf16 v[46:49], v[90:93], v[178:181], 0
	v_mfma_f32_16x16x32_bf16 v[46:49], v[78:81], v[166:169], v[46:49]
	v_mfma_f32_16x16x32_bf16 v[30:33], v[78:81], v[182:185], 0
	v_mfma_f32_16x16x32_bf16 v[30:33], v[90:93], v[186:189], v[30:33]
	v_mfma_f32_16x16x32_bf16 v[26:29], v[114:117], v[186:189], 0
	v_mfma_f32_16x16x32_bf16 v[26:29], v[102:105], v[182:185], v[26:29]
	v_mfma_f32_16x16x32_bf16 v[22:25], v[126:129], v[182:185], 0
	v_mfma_f32_16x16x32_bf16 v[22:25], v[134:137], v[186:189], v[22:25]
	v_mfma_f32_16x16x32_bf16 v[18:21], v[154:157], v[186:189], 0
	v_mfma_f32_16x16x32_bf16 v[18:21], v[142:145], v[182:185], v[18:21]
	v_mfma_f32_16x16x32_bf16 v[2:5], v[142:145], v[190:193], 0
	v_mfma_f32_16x16x32_bf16 v[2:5], v[154:157], v[214:217], v[2:5]
	v_mfma_f32_16x16x32_bf16 v[6:9], v[134:137], v[214:217], 0
	v_mfma_f32_16x16x32_bf16 v[6:9], v[126:129], v[190:193], v[6:9]
	v_mfma_f32_16x16x32_bf16 v[10:13], v[102:105], v[190:193], 0
	v_mfma_f32_16x16x32_bf16 v[10:13], v[114:117], v[214:217], v[10:13]
	v_mfma_f32_16x16x32_bf16 v[14:17], v[90:93], v[214:217], 0
	v_mfma_f32_16x16x32_bf16 v[14:17], v[78:81], v[190:193], v[14:17]
	s_barrier
	s_add_i32 s18, 0, 0x18000
	s_add_i32 s19, 0, 0x1c000
	v_add_u32_e32 v114, s18, v1
	v_add_u32_e32 v154, s19, v1
	ds_read_b128 v[78:81], v114
	ds_read_b128 v[90:93], v114 offset:1024
	ds_read_b128 v[102:105], v114 offset:2048
	ds_read_b128 v[114:117], v114 offset:3072
	ds_read_b128 v[126:129], v154
	ds_read_b128 v[134:137], v154 offset:1024
	ds_read_b128 v[142:145], v154 offset:2048
	ds_read_b128 v[154:157], v154 offset:3072
	s_add_u32 s0, vcc_lo, 0x80000
	s_addc_u32 s1, vcc_hi, 0
	s_mov_b32 m0, s33
	ds_read_b128 v[158:161], v237 offset:32768
	ds_read_b128 v[162:165], v237 offset:33792
	ds_read_b128 v[166:169], v237 offset:34816
	ds_read_b128 v[178:181], v237 offset:35840
	ds_read_b128 v[182:185], v237 offset:36864
	ds_read_b128 v[186:189], v237 offset:37888
	ds_read_b128 v[190:193], v237 offset:38912
	ds_read_b128 v[214:217], v237 offset:39936
	global_load_lds_dwordx4 v194, s[0:1]
	s_mov_b32 m0, s43
	s_nop 0
	global_load_lds_dwordx4 v204, s[0:1]
	s_waitcnt vmcnt(8)
	s_waitcnt lgkmcnt(0)
	s_barrier
	s_waitcnt lgkmcnt(0)
	v_mfma_f32_16x16x32_bf16 v[174:177], v[78:81], v[158:161], v[174:177]
	v_mfma_f32_16x16x32_bf16 v[174:177], v[90:93], v[162:165], v[174:177]
	v_mfma_f32_16x16x32_bf16 v[170:173], v[114:117], v[162:165], v[170:173]
	v_mfma_f32_16x16x32_bf16 v[170:173], v[102:105], v[158:161], v[170:173]
	v_mfma_f32_16x16x32_bf16 v[150:153], v[126:129], v[158:161], v[150:153]
	v_mfma_f32_16x16x32_bf16 v[150:153], v[134:137], v[162:165], v[150:153]
	v_mfma_f32_16x16x32_bf16 v[146:149], v[154:157], v[162:165], v[146:149]
	v_mfma_f32_16x16x32_bf16 v[146:149], v[142:145], v[158:161], v[146:149]
	v_mfma_f32_16x16x32_bf16 v[118:121], v[142:145], v[166:169], v[118:121]
	v_mfma_f32_16x16x32_bf16 v[118:121], v[154:157], v[178:181], v[118:121]
	v_mfma_f32_16x16x32_bf16 v[122:125], v[134:137], v[178:181], v[122:125]
	v_mfma_f32_16x16x32_bf16 v[122:125], v[126:129], v[166:169], v[122:125]
	v_mfma_f32_16x16x32_bf16 v[130:133], v[102:105], v[166:169], v[130:133]
	v_mfma_f32_16x16x32_bf16 v[130:133], v[114:117], v[178:181], v[130:133]
	v_mfma_f32_16x16x32_bf16 v[138:141], v[90:93], v[178:181], v[138:141]
	v_mfma_f32_16x16x32_bf16 v[138:141], v[78:81], v[166:169], v[138:141]
	v_mfma_f32_16x16x32_bf16 v[110:113], v[78:81], v[182:185], v[110:113]
	v_mfma_f32_16x16x32_bf16 v[110:113], v[90:93], v[186:189], v[110:113]
	v_mfma_f32_16x16x32_bf16 v[106:109], v[114:117], v[186:189], v[106:109]
	v_mfma_f32_16x16x32_bf16 v[106:109], v[102:105], v[182:185], v[106:109]
	v_mfma_f32_16x16x32_bf16 v[98:101], v[126:129], v[182:185], v[98:101]
	v_mfma_f32_16x16x32_bf16 v[98:101], v[134:137], v[186:189], v[98:101]
	v_mfma_f32_16x16x32_bf16 v[94:97], v[154:157], v[186:189], v[94:97]
	v_mfma_f32_16x16x32_bf16 v[94:97], v[142:145], v[182:185], v[94:97]
	v_mfma_f32_16x16x32_bf16 v[66:69], v[142:145], v[190:193], v[66:69]
	v_mfma_f32_16x16x32_bf16 v[66:69], v[154:157], v[214:217], v[66:69]
	v_mfma_f32_16x16x32_bf16 v[74:77], v[134:137], v[214:217], v[74:77]
	v_mfma_f32_16x16x32_bf16 v[74:77], v[126:129], v[190:193], v[74:77]
	v_mfma_f32_16x16x32_bf16 v[82:85], v[102:105], v[190:193], v[82:85]
	v_mfma_f32_16x16x32_bf16 v[82:85], v[114:117], v[214:217], v[82:85]
	v_mfma_f32_16x16x32_bf16 v[86:89], v[90:93], v[214:217], v[86:89]
	v_mfma_f32_16x16x32_bf16 v[86:89], v[78:81], v[190:193], v[86:89]
	s_barrier
	s_add_u32 s98, s70, 0x80
	s_addc_u32 s99, s71, 0
	s_add_u32 s100, vcc_lo, 0x80
	s_addc_u32 s101, vcc_hi, 0
	s_add_i32 s0, s18, s28
	s_mov_b32 m0, s0
	ds_read_b128 v[158:161], v237 offset:49152
	ds_read_b128 v[162:165], v237 offset:50176
	ds_read_b128 v[166:169], v237 offset:51200
	ds_read_b128 v[178:181], v237 offset:52224
	ds_read_b128 v[182:185], v237 offset:53248
	ds_read_b128 v[186:189], v237 offset:54272
	ds_read_b128 v[190:193], v237 offset:55296
	ds_read_b128 v[214:217], v237 offset:56320
	global_load_lds_dwordx4 v194, s[98:99]
	s_add_i32 m0, s0, 0x2000
	s_add_u32 s0, s70, 0x80080
	s_addc_u32 s1, s71, 0
	s_add_i32 s18, s19, s28
	global_load_lds_dwordx4 v204, s[98:99]
	s_mov_b32 m0, s18
	s_nop 0
	global_load_lds_dwordx4 v194, s[0:1]
	s_add_i32 m0, s18, 0x2000
	s_nop 0
	global_load_lds_dwordx4 v204, s[0:1]
	s_mov_b32 m0, s68
	s_nop 0
	global_load_lds_dwordx4 v194, s[100:101]
	s_mov_b32 m0, s79
	s_nop 0
	global_load_lds_dwordx4 v204, s[100:101]
	s_add_i32 s57, s57, 2
	s_add_u32 s51, s51, 0x100
	s_addc_u32 s53, s53, 0
	s_mov_b64 s[76:77], s[90:91]
	s_cmp_eq_u32 s57, 28
	s_cselect_b64 s[70:71], -1, 0
	s_and_b64 s[100:101], s[70:71], s[46:47]
	s_add_u32 s90, s76, 0x100
	s_addc_u32 s91, s77, 0
	s_and_b64 s[0:1], s[70:71], exec
	s_cselect_b32 vcc_hi, s22, s91
	s_cselect_b32 vcc_lo, s23, s90
	s_cselect_b32 s71, s41, s53
	s_cselect_b32 s70, s44, s51
	s_cmp_gt_u32 s57, 29
	s_waitcnt vmcnt(8)
	s_waitcnt lgkmcnt(0)
	s_barrier
	s_waitcnt lgkmcnt(0)
	v_mfma_f32_16x16x32_bf16 v[62:65], v[78:81], v[158:161], v[62:65]
	v_mfma_f32_16x16x32_bf16 v[62:65], v[90:93], v[162:165], v[62:65]
	v_mfma_f32_16x16x32_bf16 v[58:61], v[114:117], v[162:165], v[58:61]
	v_mfma_f32_16x16x32_bf16 v[58:61], v[102:105], v[158:161], v[58:61]
	v_mfma_f32_16x16x32_bf16 v[54:57], v[126:129], v[158:161], v[54:57]
	v_mfma_f32_16x16x32_bf16 v[54:57], v[134:137], v[162:165], v[54:57]
	v_mfma_f32_16x16x32_bf16 v[50:53], v[154:157], v[162:165], v[50:53]
	v_mfma_f32_16x16x32_bf16 v[50:53], v[142:145], v[158:161], v[50:53]
	v_mfma_f32_16x16x32_bf16 v[34:37], v[142:145], v[166:169], v[34:37]
	v_mfma_f32_16x16x32_bf16 v[34:37], v[154:157], v[178:181], v[34:37]
	v_mfma_f32_16x16x32_bf16 v[38:41], v[134:137], v[178:181], v[38:41]
	v_mfma_f32_16x16x32_bf16 v[38:41], v[126:129], v[166:169], v[38:41]
	v_mfma_f32_16x16x32_bf16 v[42:45], v[102:105], v[166:169], v[42:45]
	v_mfma_f32_16x16x32_bf16 v[42:45], v[114:117], v[178:181], v[42:45]
	v_mfma_f32_16x16x32_bf16 v[46:49], v[90:93], v[178:181], v[46:49]
	v_mfma_f32_16x16x32_bf16 v[46:49], v[78:81], v[166:169], v[46:49]
	v_mfma_f32_16x16x32_bf16 v[30:33], v[78:81], v[182:185], v[30:33]
	v_mfma_f32_16x16x32_bf16 v[30:33], v[90:93], v[186:189], v[30:33]
	v_mfma_f32_16x16x32_bf16 v[26:29], v[114:117], v[186:189], v[26:29]
	v_mfma_f32_16x16x32_bf16 v[26:29], v[102:105], v[182:185], v[26:29]
	v_mfma_f32_16x16x32_bf16 v[22:25], v[126:129], v[182:185], v[22:25]
	v_mfma_f32_16x16x32_bf16 v[22:25], v[134:137], v[186:189], v[22:25]
	v_mfma_f32_16x16x32_bf16 v[18:21], v[154:157], v[186:189], v[18:21]
	v_mfma_f32_16x16x32_bf16 v[18:21], v[142:145], v[182:185], v[18:21]
	v_mfma_f32_16x16x32_bf16 v[2:5], v[142:145], v[190:193], v[2:5]
	v_mfma_f32_16x16x32_bf16 v[2:5], v[154:157], v[214:217], v[2:5]
	v_mfma_f32_16x16x32_bf16 v[6:9], v[134:137], v[214:217], v[6:9]
	v_mfma_f32_16x16x32_bf16 v[6:9], v[126:129], v[190:193], v[6:9]
	v_mfma_f32_16x16x32_bf16 v[10:13], v[102:105], v[190:193], v[10:13]
	v_mfma_f32_16x16x32_bf16 v[10:13], v[114:117], v[214:217], v[10:13]
	v_mfma_f32_16x16x32_bf16 v[14:17], v[90:93], v[214:217], v[14:17]
	v_mfma_f32_16x16x32_bf16 v[14:17], v[78:81], v[190:193], v[14:17]
	s_barrier
	s_cbranch_scc1 .LBB0_512
	s_cmp_lg_u64 s[100:101], 0
	s_cbranch_scc1 .Lrot_rare_out
	s_branch .Lrot_body_out
.Lrot_rare_out:
	s_mov_b32 m0, s59
	s_nop 0
	global_load_lds_dwordx4 v[70:71], off
	s_mov_b32 m0, s60
	s_nop 0
	global_load_lds_dwordx4 v[72:73], off
	s_branch .Lrot_body_out
.Lrot_body_out:
	s_add_i32 s0, 0, 0x10000
	s_add_i32 s18, 0, 0x14000
	v_add_u32_e32 v114, s0, v1
	v_add_u32_e32 v154, s18, v1
	ds_read_b128 v[78:81], v114
	ds_read_b128 v[90:93], v114 offset:1024
	ds_read_b128 v[102:105], v114 offset:2048
	ds_read_b128 v[114:117], v114 offset:3072
	ds_read_b128 v[126:129], v154
	ds_read_b128 v[134:137], v154 offset:1024
	ds_read_b128 v[142:145], v154 offset:2048
	ds_read_b128 v[154:157], v154 offset:3072
	s_add_i32 m0, s29, 0xc000
	ds_read_b128 v[158:161], v237
	ds_read_b128 v[162:165], v237 offset:1024
	ds_read_b128 v[166:169], v237 offset:2048
	ds_read_b128 v[178:181], v237 offset:3072
	ds_read_b128 v[182:185], v237 offset:4096
	ds_read_b128 v[186:189], v237 offset:5120
	ds_read_b128 v[190:193], v237 offset:6144
	ds_read_b128 v[214:217], v237 offset:7168
	global_load_lds_dwordx4 v210, s[76:77]
	s_add_i32 m0, s29, 0xe000
	s_nop 0
	global_load_lds_dwordx4 v212, s[76:77]
	s_waitcnt vmcnt(8)
	s_waitcnt lgkmcnt(0)
	s_barrier
	s_waitcnt lgkmcnt(0)
	v_mfma_f32_16x16x32_bf16 v[174:177], v[78:81], v[158:161], v[174:177]
	v_mfma_f32_16x16x32_bf16 v[174:177], v[90:93], v[162:165], v[174:177]
	v_mfma_f32_16x16x32_bf16 v[170:173], v[114:117], v[162:165], v[170:173]
	v_mfma_f32_16x16x32_bf16 v[170:173], v[102:105], v[158:161], v[170:173]
	v_mfma_f32_16x16x32_bf16 v[150:153], v[126:129], v[158:161], v[150:153]
	v_mfma_f32_16x16x32_bf16 v[150:153], v[134:137], v[162:165], v[150:153]
	v_mfma_f32_16x16x32_bf16 v[146:149], v[154:157], v[162:165], v[146:149]
	v_mfma_f32_16x16x32_bf16 v[146:149], v[142:145], v[158:161], v[146:149]
	v_mfma_f32_16x16x32_bf16 v[118:121], v[142:145], v[166:169], v[118:121]
	v_mfma_f32_16x16x32_bf16 v[118:121], v[154:157], v[178:181], v[118:121]
	v_mfma_f32_16x16x32_bf16 v[122:125], v[134:137], v[178:181], v[122:125]
	v_mfma_f32_16x16x32_bf16 v[122:125], v[126:129], v[166:169], v[122:125]
	v_mfma_f32_16x16x32_bf16 v[130:133], v[102:105], v[166:169], v[130:133]
	v_mfma_f32_16x16x32_bf16 v[130:133], v[114:117], v[178:181], v[130:133]
	v_mfma_f32_16x16x32_bf16 v[138:141], v[90:93], v[178:181], v[138:141]
	v_mfma_f32_16x16x32_bf16 v[138:141], v[78:81], v[166:169], v[138:141]
	v_mfma_f32_16x16x32_bf16 v[110:113], v[78:81], v[182:185], v[110:113]
	v_mfma_f32_16x16x32_bf16 v[110:113], v[90:93], v[186:189], v[110:113]
	v_mfma_f32_16x16x32_bf16 v[106:109], v[114:117], v[186:189], v[106:109]
	v_mfma_f32_16x16x32_bf16 v[106:109], v[102:105], v[182:185], v[106:109]
	v_mfma_f32_16x16x32_bf16 v[98:101], v[126:129], v[182:185], v[98:101]
	v_mfma_f32_16x16x32_bf16 v[98:101], v[134:137], v[186:189], v[98:101]
	v_mfma_f32_16x16x32_bf16 v[94:97], v[154:157], v[186:189], v[94:97]
	v_mfma_f32_16x16x32_bf16 v[94:97], v[142:145], v[182:185], v[94:97]
	v_mfma_f32_16x16x32_bf16 v[66:69], v[142:145], v[190:193], v[66:69]
	v_mfma_f32_16x16x32_bf16 v[66:69], v[154:157], v[214:217], v[66:69]
	v_mfma_f32_16x16x32_bf16 v[74:77], v[134:137], v[214:217], v[74:77]
	v_mfma_f32_16x16x32_bf16 v[74:77], v[126:129], v[190:193], v[74:77]
	v_mfma_f32_16x16x32_bf16 v[82:85], v[102:105], v[190:193], v[82:85]
	v_mfma_f32_16x16x32_bf16 v[82:85], v[114:117], v[214:217], v[82:85]
	v_mfma_f32_16x16x32_bf16 v[86:89], v[90:93], v[214:217], v[86:89]
	v_mfma_f32_16x16x32_bf16 v[86:89], v[78:81], v[190:193], v[86:89]
	s_barrier
	s_add_i32 s0, s0, s28
	s_mov_b32 m0, s0
	ds_read_b128 v[158:161], v237 offset:16384
	ds_read_b128 v[162:165], v237 offset:17408
	ds_read_b128 v[166:169], v237 offset:18432
	ds_read_b128 v[178:181], v237 offset:19456
	ds_read_b128 v[182:185], v237 offset:20480
	ds_read_b128 v[186:189], v237 offset:21504
	ds_read_b128 v[190:193], v237 offset:22528
	ds_read_b128 v[214:217], v237 offset:23552
	global_load_lds_dwordx4 v194, s[70:71]
	s_add_i32 m0, s0, 0x2000
	s_add_u32 s0, s70, 0x80000
	s_addc_u32 s1, s71, 0
	s_add_i32 s18, s18, s28
	global_load_lds_dwordx4 v204, s[70:71]
	s_mov_b32 m0, s18
	s_nop 0
	global_load_lds_dwordx4 v194, s[0:1]
	s_add_i32 m0, s18, 0x2000
	s_nop 0
	global_load_lds_dwordx4 v204, s[0:1]
	s_mov_b32 m0, s29
	s_nop 0
	global_load_lds_dwordx4 v194, vcc
	s_mov_b32 m0, s31
	s_nop 0
	global_load_lds_dwordx4 v204, vcc
	s_waitcnt vmcnt(8)
	s_waitcnt lgkmcnt(0)
	s_barrier
	s_waitcnt lgkmcnt(0)
	v_mfma_f32_16x16x32_bf16 v[62:65], v[78:81], v[158:161], v[62:65]
	v_mfma_f32_16x16x32_bf16 v[62:65], v[90:93], v[162:165], v[62:65]
	v_mfma_f32_16x16x32_bf16 v[58:61], v[114:117], v[162:165], v[58:61]
	v_mfma_f32_16x16x32_bf16 v[58:61], v[102:105], v[158:161], v[58:61]
	v_mfma_f32_16x16x32_bf16 v[54:57], v[126:129], v[158:161], v[54:57]
	v_mfma_f32_16x16x32_bf16 v[54:57], v[134:137], v[162:165], v[54:57]
	v_mfma_f32_16x16x32_bf16 v[50:53], v[154:157], v[162:165], v[50:53]
	v_mfma_f32_16x16x32_bf16 v[50:53], v[142:145], v[158:161], v[50:53]
	v_mfma_f32_16x16x32_bf16 v[34:37], v[142:145], v[166:169], v[34:37]
	v_mfma_f32_16x16x32_bf16 v[34:37], v[154:157], v[178:181], v[34:37]
	v_mfma_f32_16x16x32_bf16 v[38:41], v[134:137], v[178:181], v[38:41]
	v_mfma_f32_16x16x32_bf16 v[38:41], v[126:129], v[166:169], v[38:41]
	v_mfma_f32_16x16x32_bf16 v[42:45], v[102:105], v[166:169], v[42:45]
	v_mfma_f32_16x16x32_bf16 v[42:45], v[114:117], v[178:181], v[42:45]
	v_mfma_f32_16x16x32_bf16 v[46:49], v[90:93], v[178:181], v[46:49]
	v_mfma_f32_16x16x32_bf16 v[46:49], v[78:81], v[166:169], v[46:49]
	v_mfma_f32_16x16x32_bf16 v[30:33], v[78:81], v[182:185], v[30:33]
	v_mfma_f32_16x16x32_bf16 v[30:33], v[90:93], v[186:189], v[30:33]
	v_mfma_f32_16x16x32_bf16 v[26:29], v[114:117], v[186:189], v[26:29]
	v_mfma_f32_16x16x32_bf16 v[26:29], v[102:105], v[182:185], v[26:29]
	v_mfma_f32_16x16x32_bf16 v[22:25], v[126:129], v[182:185], v[22:25]
	v_mfma_f32_16x16x32_bf16 v[22:25], v[134:137], v[186:189], v[22:25]
	v_mfma_f32_16x16x32_bf16 v[18:21], v[154:157], v[186:189], v[18:21]
	v_mfma_f32_16x16x32_bf16 v[18:21], v[142:145], v[182:185], v[18:21]
	v_mfma_f32_16x16x32_bf16 v[2:5], v[142:145], v[190:193], v[2:5]
	v_mfma_f32_16x16x32_bf16 v[2:5], v[154:157], v[214:217], v[2:5]
	v_mfma_f32_16x16x32_bf16 v[6:9], v[134:137], v[214:217], v[6:9]
	v_mfma_f32_16x16x32_bf16 v[6:9], v[126:129], v[190:193], v[6:9]
	v_mfma_f32_16x16x32_bf16 v[10:13], v[102:105], v[190:193], v[10:13]
	v_mfma_f32_16x16x32_bf16 v[10:13], v[114:117], v[214:217], v[10:13]
	v_mfma_f32_16x16x32_bf16 v[14:17], v[90:93], v[214:217], v[14:17]
	v_mfma_f32_16x16x32_bf16 v[14:17], v[78:81], v[190:193], v[14:17]
	s_barrier
	s_add_i32 s18, 0, 0x18000
	s_add_i32 s19, 0, 0x1c000
	v_add_u32_e32 v114, s18, v1
	v_add_u32_e32 v154, s19, v1
	ds_read_b128 v[78:81], v114
	ds_read_b128 v[90:93], v114 offset:1024
	ds_read_b128 v[102:105], v114 offset:2048
	ds_read_b128 v[114:117], v114 offset:3072
	ds_read_b128 v[126:129], v154
	ds_read_b128 v[134:137], v154 offset:1024
	ds_read_b128 v[142:145], v154 offset:2048
	ds_read_b128 v[154:157], v154 offset:3072
	s_add_u32 s0, vcc_lo, 0x80000
	s_addc_u32 s1, vcc_hi, 0
	s_mov_b32 m0, s33
	ds_read_b128 v[158:161], v237 offset:32768
	ds_read_b128 v[162:165], v237 offset:33792
	ds_read_b128 v[166:169], v237 offset:34816
	ds_read_b128 v[178:181], v237 offset:35840
	ds_read_b128 v[182:185], v237 offset:36864
	ds_read_b128 v[186:189], v237 offset:37888
	ds_read_b128 v[190:193], v237 offset:38912
	ds_read_b128 v[214:217], v237 offset:39936
	global_load_lds_dwordx4 v194, s[0:1]
	s_mov_b32 m0, s43
	s_nop 0
	global_load_lds_dwordx4 v204, s[0:1]
	s_waitcnt vmcnt(8)
	s_waitcnt lgkmcnt(0)
	s_barrier
	s_waitcnt lgkmcnt(0)
	v_mfma_f32_16x16x32_bf16 v[174:177], v[78:81], v[158:161], v[174:177]
	v_mfma_f32_16x16x32_bf16 v[174:177], v[90:93], v[162:165], v[174:177]
	v_mfma_f32_16x16x32_bf16 v[170:173], v[114:117], v[162:165], v[170:173]
	v_mfma_f32_16x16x32_bf16 v[170:173], v[102:105], v[158:161], v[170:173]
	v_mfma_f32_16x16x32_bf16 v[150:153], v[126:129], v[158:161], v[150:153]
	v_mfma_f32_16x16x32_bf16 v[150:153], v[134:137], v[162:165], v[150:153]
	v_mfma_f32_16x16x32_bf16 v[146:149], v[154:157], v[162:165], v[146:149]
	v_mfma_f32_16x16x32_bf16 v[146:149], v[142:145], v[158:161], v[146:149]
	v_mfma_f32_16x16x32_bf16 v[118:121], v[142:145], v[166:169], v[118:121]
	v_mfma_f32_16x16x32_bf16 v[118:121], v[154:157], v[178:181], v[118:121]
	v_mfma_f32_16x16x32_bf16 v[122:125], v[134:137], v[178:181], v[122:125]
	v_mfma_f32_16x16x32_bf16 v[122:125], v[126:129], v[166:169], v[122:125]
	v_mfma_f32_16x16x32_bf16 v[130:133], v[102:105], v[166:169], v[130:133]
	v_mfma_f32_16x16x32_bf16 v[130:133], v[114:117], v[178:181], v[130:133]
	v_mfma_f32_16x16x32_bf16 v[138:141], v[90:93], v[178:181], v[138:141]
	v_mfma_f32_16x16x32_bf16 v[138:141], v[78:81], v[166:169], v[138:141]
	v_mfma_f32_16x16x32_bf16 v[110:113], v[78:81], v[182:185], v[110:113]
	v_mfma_f32_16x16x32_bf16 v[110:113], v[90:93], v[186:189], v[110:113]
	v_mfma_f32_16x16x32_bf16 v[106:109], v[114:117], v[186:189], v[106:109]
	v_mfma_f32_16x16x32_bf16 v[106:109], v[102:105], v[182:185], v[106:109]
	v_mfma_f32_16x16x32_bf16 v[98:101], v[126:129], v[182:185], v[98:101]
	v_mfma_f32_16x16x32_bf16 v[98:101], v[134:137], v[186:189], v[98:101]
	v_mfma_f32_16x16x32_bf16 v[94:97], v[154:157], v[186:189], v[94:97]
	v_mfma_f32_16x16x32_bf16 v[94:97], v[142:145], v[182:185], v[94:97]
	v_mfma_f32_16x16x32_bf16 v[66:69], v[142:145], v[190:193], v[66:69]
	v_mfma_f32_16x16x32_bf16 v[66:69], v[154:157], v[214:217], v[66:69]
	v_mfma_f32_16x16x32_bf16 v[74:77], v[134:137], v[214:217], v[74:77]
	v_mfma_f32_16x16x32_bf16 v[74:77], v[126:129], v[190:193], v[74:77]
	v_mfma_f32_16x16x32_bf16 v[82:85], v[102:105], v[190:193], v[82:85]
	v_mfma_f32_16x16x32_bf16 v[82:85], v[114:117], v[214:217], v[82:85]
	v_mfma_f32_16x16x32_bf16 v[86:89], v[90:93], v[214:217], v[86:89]
	v_mfma_f32_16x16x32_bf16 v[86:89], v[78:81], v[190:193], v[86:89]
	s_barrier
	s_add_u32 s98, s70, 0x80
	s_addc_u32 s99, s71, 0
	s_add_u32 s100, vcc_lo, 0x80
	s_addc_u32 s101, vcc_hi, 0
	s_add_i32 s0, s18, s28
	s_mov_b32 m0, s0
	ds_read_b128 v[158:161], v237 offset:49152
	ds_read_b128 v[162:165], v237 offset:50176
	ds_read_b128 v[166:169], v237 offset:51200
	ds_read_b128 v[178:181], v237 offset:52224
	ds_read_b128 v[182:185], v237 offset:53248
	ds_read_b128 v[186:189], v237 offset:54272
	ds_read_b128 v[190:193], v237 offset:55296
	ds_read_b128 v[214:217], v237 offset:56320
	global_load_lds_dwordx4 v194, s[98:99]
	s_add_i32 m0, s0, 0x2000
	s_add_u32 s0, s70, 0x80080
	s_addc_u32 s1, s71, 0
	s_add_i32 s18, s19, s28
	global_load_lds_dwordx4 v204, s[98:99]
	s_mov_b32 m0, s18
	s_nop 0
	global_load_lds_dwordx4 v194, s[0:1]
	s_add_i32 m0, s18, 0x2000
	s_nop 0
	global_load_lds_dwordx4 v204, s[0:1]
	s_mov_b32 m0, s68
	s_nop 0
	global_load_lds_dwordx4 v194, s[100:101]
	s_mov_b32 m0, s79
	s_nop 0
	global_load_lds_dwordx4 v204, s[100:101]
	s_add_i32 s57, s57, 2
	s_add_u32 s51, s51, 0x100
	s_addc_u32 s53, s53, 0
	s_mov_b64 s[76:77], s[90:91]
	s_cmp_eq_u32 s57, 28
	s_cselect_b64 s[70:71], -1, 0
	s_and_b64 s[100:101], s[70:71], s[46:47]
	s_add_u32 s90, s76, 0x100
	s_addc_u32 s91, s77, 0
	s_and_b64 s[0:1], s[70:71], exec
	s_cselect_b32 vcc_hi, s22, s91
	s_cselect_b32 vcc_lo, s23, s90
	s_cselect_b32 s71, s41, s53
	s_cselect_b32 s70, s44, s51
	s_cmp_gt_u32 s57, 29
	s_waitcnt vmcnt(8)
	s_waitcnt lgkmcnt(0)
	s_barrier
	s_waitcnt lgkmcnt(0)
	v_mfma_f32_16x16x32_bf16 v[62:65], v[78:81], v[158:161], v[62:65]
	v_mfma_f32_16x16x32_bf16 v[62:65], v[90:93], v[162:165], v[62:65]
	v_mfma_f32_16x16x32_bf16 v[58:61], v[114:117], v[162:165], v[58:61]
	v_mfma_f32_16x16x32_bf16 v[58:61], v[102:105], v[158:161], v[58:61]
	v_mfma_f32_16x16x32_bf16 v[54:57], v[126:129], v[158:161], v[54:57]
	v_mfma_f32_16x16x32_bf16 v[54:57], v[134:137], v[162:165], v[54:57]
	v_mfma_f32_16x16x32_bf16 v[50:53], v[154:157], v[162:165], v[50:53]
	v_mfma_f32_16x16x32_bf16 v[50:53], v[142:145], v[158:161], v[50:53]
	v_mfma_f32_16x16x32_bf16 v[34:37], v[142:145], v[166:169], v[34:37]
	v_mfma_f32_16x16x32_bf16 v[34:37], v[154:157], v[178:181], v[34:37]
	v_mfma_f32_16x16x32_bf16 v[38:41], v[134:137], v[178:181], v[38:41]
	v_mfma_f32_16x16x32_bf16 v[38:41], v[126:129], v[166:169], v[38:41]
	v_mfma_f32_16x16x32_bf16 v[42:45], v[102:105], v[166:169], v[42:45]
	v_mfma_f32_16x16x32_bf16 v[42:45], v[114:117], v[178:181], v[42:45]
	v_mfma_f32_16x16x32_bf16 v[46:49], v[90:93], v[178:181], v[46:49]
	v_mfma_f32_16x16x32_bf16 v[46:49], v[78:81], v[166:169], v[46:49]
	v_mfma_f32_16x16x32_bf16 v[30:33], v[78:81], v[182:185], v[30:33]
	v_mfma_f32_16x16x32_bf16 v[30:33], v[90:93], v[186:189], v[30:33]
	v_mfma_f32_16x16x32_bf16 v[26:29], v[114:117], v[186:189], v[26:29]
	v_mfma_f32_16x16x32_bf16 v[26:29], v[102:105], v[182:185], v[26:29]
	v_mfma_f32_16x16x32_bf16 v[22:25], v[126:129], v[182:185], v[22:25]
	v_mfma_f32_16x16x32_bf16 v[22:25], v[134:137], v[186:189], v[22:25]
	v_mfma_f32_16x16x32_bf16 v[18:21], v[154:157], v[186:189], v[18:21]
	v_mfma_f32_16x16x32_bf16 v[18:21], v[142:145], v[182:185], v[18:21]
	v_mfma_f32_16x16x32_bf16 v[2:5], v[142:145], v[190:193], v[2:5]
	v_mfma_f32_16x16x32_bf16 v[2:5], v[154:157], v[214:217], v[2:5]
	v_mfma_f32_16x16x32_bf16 v[6:9], v[134:137], v[214:217], v[6:9]
	v_mfma_f32_16x16x32_bf16 v[6:9], v[126:129], v[190:193], v[6:9]
	v_mfma_f32_16x16x32_bf16 v[10:13], v[102:105], v[190:193], v[10:13]
	v_mfma_f32_16x16x32_bf16 v[10:13], v[114:117], v[214:217], v[10:13]
	v_mfma_f32_16x16x32_bf16 v[14:17], v[90:93], v[214:217], v[14:17]
	v_mfma_f32_16x16x32_bf16 v[14:17], v[78:81], v[190:193], v[14:17]
	s_barrier
	s_cbranch_scc1 .LBB0_512
	s_cmp_lg_u64 s[100:101], 0
	s_cbranch_scc1 .Lrot_rare_out
	s_branch .Lrot_body_out

.LBB0_581:
.LBB0_582:
	s_cmp_eq_u32 s76, 28
	s_cselect_b64 s[64:65], -1, 0
	s_and_b64 s[0:1], s[64:65], s[12:13]
	s_andn2_b64 vcc, exec, s[0:1]
	s_cbranch_vccnz .Lpeel_disp_gu
	s_mov_b32 m0, s59
	s_nop 0
	global_load_lds_dwordx4 v[140:141], off
	s_mov_b32 m0, s60
	s_nop 0
	global_load_lds_dwordx4 v[142:143], off
	s_branch .Lpeel_disp_gu
.Lpeel_disp_gu:
	s_add_u32 s18, s62, 0xfff80080
	s_addc_u32 s19, s63, -1
	s_and_b64 s[0:1], s[64:65], exec
	s_cselect_b32 s71, s22, s19
	s_cselect_b32 s70, s23, s18
	s_cselect_b32 s65, s39, s58
	s_cselect_b32 s64, s47, s53
	s_add_i32 s0, 0, 0x10000
	v_add_u32_e32 v153, s0, v1
	s_add_i32 s18, 0, 0x14000
	ds_read_b128 v[144:147], v153
	ds_read_b128 v[148:151], v153 offset:1024
	ds_read_b128 v[154:157], v153 offset:2048
	ds_read_b128 v[158:161], v153 offset:3072
	v_add_u32_e32 v153, s18, v1
	ds_read_b128 v[162:165], v153
	ds_read_b128 v[166:169], v153 offset:1024
	ds_read_b128 v[170:173], v153 offset:2048
	ds_read_b128 v[174:177], v153 offset:3072
	s_add_i32 m0, s29, 0xc000
	ds_read_b128 v[178:181], v152
	ds_read_b128 v[182:185], v152 offset:1024
	ds_read_b128 v[186:189], v152 offset:2048
	ds_read_b128 v[190:193], v152 offset:3072
	ds_read_b128 v[204:207], v152 offset:4096
	ds_read_b128 v[208:211], v152 offset:5120
	ds_read_b128 v[212:215], v152 offset:6144
	ds_read_b128 v[216:219], v152 offset:7168
	global_load_lds_dwordx4 v136, s[62:63]
	s_add_i32 m0, s29, 0xe000
	s_nop 0
	global_load_lds_dwordx4 v138, s[62:63]
	s_waitcnt vmcnt(8)
	s_waitcnt lgkmcnt(0)
	s_barrier
	s_waitcnt lgkmcnt(0)
	v_mfma_f32_16x16x32_bf16 v[126:129], v[144:147], v[178:181], 0
	v_mfma_f32_16x16x32_bf16 v[126:129], v[148:151], v[182:185], v[126:129]
	v_mfma_f32_16x16x32_bf16 v[122:125], v[158:161], v[182:185], 0
	v_mfma_f32_16x16x32_bf16 v[122:125], v[154:157], v[178:181], v[122:125]
	v_mfma_f32_16x16x32_bf16 v[118:121], v[162:165], v[178:181], 0
	v_mfma_f32_16x16x32_bf16 v[118:121], v[166:169], v[182:185], v[118:121]
	v_mfma_f32_16x16x32_bf16 v[114:117], v[174:177], v[182:185], 0
	v_mfma_f32_16x16x32_bf16 v[114:117], v[170:173], v[178:181], v[114:117]
	v_mfma_f32_16x16x32_bf16 v[98:101], v[170:173], v[186:189], 0
	v_mfma_f32_16x16x32_bf16 v[98:101], v[174:177], v[190:193], v[98:101]
	v_mfma_f32_16x16x32_bf16 v[102:105], v[166:169], v[190:193], 0
	v_mfma_f32_16x16x32_bf16 v[102:105], v[162:165], v[186:189], v[102:105]
	v_mfma_f32_16x16x32_bf16 v[106:109], v[154:157], v[186:189], 0
	v_mfma_f32_16x16x32_bf16 v[106:109], v[158:161], v[190:193], v[106:109]
	v_mfma_f32_16x16x32_bf16 v[110:113], v[148:151], v[190:193], 0
	v_mfma_f32_16x16x32_bf16 v[110:113], v[144:147], v[186:189], v[110:113]
	v_mfma_f32_16x16x32_bf16 v[94:97], v[144:147], v[204:207], 0
	v_mfma_f32_16x16x32_bf16 v[94:97], v[148:151], v[208:211], v[94:97]
	v_mfma_f32_16x16x32_bf16 v[90:93], v[158:161], v[208:211], 0
	v_mfma_f32_16x16x32_bf16 v[90:93], v[154:157], v[204:207], v[90:93]
	v_mfma_f32_16x16x32_bf16 v[86:89], v[162:165], v[204:207], 0
	v_mfma_f32_16x16x32_bf16 v[86:89], v[166:169], v[208:211], v[86:89]
	v_mfma_f32_16x16x32_bf16 v[82:85], v[174:177], v[208:211], 0
	v_mfma_f32_16x16x32_bf16 v[82:85], v[170:173], v[204:207], v[82:85]
	v_mfma_f32_16x16x32_bf16 v[66:69], v[170:173], v[212:215], 0
	v_mfma_f32_16x16x32_bf16 v[66:69], v[174:177], v[216:219], v[66:69]
	v_mfma_f32_16x16x32_bf16 v[70:73], v[166:169], v[216:219], 0
	v_mfma_f32_16x16x32_bf16 v[70:73], v[162:165], v[212:215], v[70:73]
	v_mfma_f32_16x16x32_bf16 v[74:77], v[154:157], v[212:215], 0
	v_mfma_f32_16x16x32_bf16 v[74:77], v[158:161], v[216:219], v[74:77]
	v_mfma_f32_16x16x32_bf16 v[78:81], v[148:151], v[216:219], 0
	v_mfma_f32_16x16x32_bf16 v[78:81], v[144:147], v[212:215], v[78:81]
	s_barrier
	s_add_i32 s0, s0, s28
	s_mov_b32 m0, s0
	ds_read_b128 v[178:181], v152 offset:16384
	ds_read_b128 v[182:185], v152 offset:17408
	ds_read_b128 v[186:189], v152 offset:18432
	ds_read_b128 v[190:193], v152 offset:19456
	ds_read_b128 v[204:207], v152 offset:20480
	ds_read_b128 v[208:211], v152 offset:21504
	ds_read_b128 v[212:215], v152 offset:22528
	ds_read_b128 v[216:219], v152 offset:23552
	global_load_lds_dwordx4 v194, s[64:65]
	s_add_i32 m0, s0, 0x2000
	s_add_u32 s0, s64, 0x80000
	s_addc_u32 s1, s65, 0
	s_add_i32 s18, s18, s28
	global_load_lds_dwordx4 v130, s[64:65]
	s_mov_b32 m0, s18
	s_nop 0
	global_load_lds_dwordx4 v194, s[0:1]
	s_add_i32 m0, s18, 0x2000
	s_nop 0
	global_load_lds_dwordx4 v130, s[0:1]
	s_mov_b32 m0, s29
	s_nop 0
	global_load_lds_dwordx4 v194, s[70:71]
	s_mov_b32 m0, s31
	s_nop 0
	global_load_lds_dwordx4 v130, s[70:71]
	s_waitcnt vmcnt(8)
	s_waitcnt lgkmcnt(0)
	s_barrier
	s_waitcnt lgkmcnt(0)
	v_mfma_f32_16x16x32_bf16 v[62:65], v[144:147], v[178:181], 0
	v_mfma_f32_16x16x32_bf16 v[62:65], v[148:151], v[182:185], v[62:65]
	v_mfma_f32_16x16x32_bf16 v[58:61], v[158:161], v[182:185], 0
	v_mfma_f32_16x16x32_bf16 v[58:61], v[154:157], v[178:181], v[58:61]
	v_mfma_f32_16x16x32_bf16 v[54:57], v[162:165], v[178:181], 0
	v_mfma_f32_16x16x32_bf16 v[54:57], v[166:169], v[182:185], v[54:57]
	v_mfma_f32_16x16x32_bf16 v[50:53], v[174:177], v[182:185], 0
	v_mfma_f32_16x16x32_bf16 v[50:53], v[170:173], v[178:181], v[50:53]
	v_mfma_f32_16x16x32_bf16 v[34:37], v[170:173], v[186:189], 0
	v_mfma_f32_16x16x32_bf16 v[34:37], v[174:177], v[190:193], v[34:37]
	v_mfma_f32_16x16x32_bf16 v[38:41], v[166:169], v[190:193], 0
	v_mfma_f32_16x16x32_bf16 v[38:41], v[162:165], v[186:189], v[38:41]
	v_mfma_f32_16x16x32_bf16 v[42:45], v[154:157], v[186:189], 0
	v_mfma_f32_16x16x32_bf16 v[42:45], v[158:161], v[190:193], v[42:45]
	v_mfma_f32_16x16x32_bf16 v[46:49], v[148:151], v[190:193], 0
	v_mfma_f32_16x16x32_bf16 v[46:49], v[144:147], v[186:189], v[46:49]
	v_mfma_f32_16x16x32_bf16 v[30:33], v[144:147], v[204:207], 0
	v_mfma_f32_16x16x32_bf16 v[30:33], v[148:151], v[208:211], v[30:33]
	v_mfma_f32_16x16x32_bf16 v[26:29], v[158:161], v[208:211], 0
	v_mfma_f32_16x16x32_bf16 v[26:29], v[154:157], v[204:207], v[26:29]
	v_mfma_f32_16x16x32_bf16 v[22:25], v[162:165], v[204:207], 0
	v_mfma_f32_16x16x32_bf16 v[22:25], v[166:169], v[208:211], v[22:25]
	v_mfma_f32_16x16x32_bf16 v[18:21], v[174:177], v[208:211], 0
	v_mfma_f32_16x16x32_bf16 v[18:21], v[170:173], v[204:207], v[18:21]
	v_mfma_f32_16x16x32_bf16 v[2:5], v[170:173], v[212:215], 0
	v_mfma_f32_16x16x32_bf16 v[2:5], v[174:177], v[216:219], v[2:5]
	v_mfma_f32_16x16x32_bf16 v[6:9], v[166:169], v[216:219], 0
	v_mfma_f32_16x16x32_bf16 v[6:9], v[162:165], v[212:215], v[6:9]
	v_mfma_f32_16x16x32_bf16 v[10:13], v[154:157], v[212:215], 0
	v_mfma_f32_16x16x32_bf16 v[10:13], v[158:161], v[216:219], v[10:13]
	v_mfma_f32_16x16x32_bf16 v[14:17], v[148:151], v[216:219], 0
	v_mfma_f32_16x16x32_bf16 v[14:17], v[144:147], v[212:215], v[14:17]
	s_barrier
	s_add_i32 s18, 0, 0x18000
	v_add_u32_e32 v153, s18, v1
	s_add_i32 s19, 0, 0x1c000
	ds_read_b128 v[144:147], v153
	ds_read_b128 v[148:151], v153 offset:1024
	ds_read_b128 v[154:157], v153 offset:2048
	ds_read_b128 v[158:161], v153 offset:3072
	v_add_u32_e32 v153, s19, v1
	ds_read_b128 v[162:165], v153
	ds_read_b128 v[166:169], v153 offset:1024
	ds_read_b128 v[170:173], v153 offset:2048
	ds_read_b128 v[174:177], v153 offset:3072
	s_add_u32 s0, s70, 0x80000
	s_addc_u32 s1, s71, 0
	s_mov_b32 m0, s33
	ds_read_b128 v[178:181], v152 offset:32768
	ds_read_b128 v[182:185], v152 offset:33792
	ds_read_b128 v[186:189], v152 offset:34816
	ds_read_b128 v[190:193], v152 offset:35840
	ds_read_b128 v[204:207], v152 offset:36864
	ds_read_b128 v[208:211], v152 offset:37888
	ds_read_b128 v[212:215], v152 offset:38912
	ds_read_b128 v[216:219], v152 offset:39936
	global_load_lds_dwordx4 v194, s[0:1]
	s_mov_b32 m0, s40
	s_nop 0
	global_load_lds_dwordx4 v130, s[0:1]
	s_waitcnt vmcnt(8)
	s_waitcnt lgkmcnt(0)
	s_barrier
	s_waitcnt lgkmcnt(0)
	v_mfma_f32_16x16x32_bf16 v[126:129], v[144:147], v[178:181], v[126:129]
	v_mfma_f32_16x16x32_bf16 v[126:129], v[148:151], v[182:185], v[126:129]
	v_mfma_f32_16x16x32_bf16 v[122:125], v[158:161], v[182:185], v[122:125]
	v_mfma_f32_16x16x32_bf16 v[122:125], v[154:157], v[178:181], v[122:125]
	v_mfma_f32_16x16x32_bf16 v[118:121], v[162:165], v[178:181], v[118:121]
	v_mfma_f32_16x16x32_bf16 v[118:121], v[166:169], v[182:185], v[118:121]
	v_mfma_f32_16x16x32_bf16 v[114:117], v[174:177], v[182:185], v[114:117]
	v_mfma_f32_16x16x32_bf16 v[114:117], v[170:173], v[178:181], v[114:117]
	v_mfma_f32_16x16x32_bf16 v[98:101], v[170:173], v[186:189], v[98:101]
	v_mfma_f32_16x16x32_bf16 v[98:101], v[174:177], v[190:193], v[98:101]
	v_mfma_f32_16x16x32_bf16 v[102:105], v[166:169], v[190:193], v[102:105]
	v_mfma_f32_16x16x32_bf16 v[102:105], v[162:165], v[186:189], v[102:105]
	v_mfma_f32_16x16x32_bf16 v[106:109], v[154:157], v[186:189], v[106:109]
	v_mfma_f32_16x16x32_bf16 v[106:109], v[158:161], v[190:193], v[106:109]
	v_mfma_f32_16x16x32_bf16 v[110:113], v[148:151], v[190:193], v[110:113]
	v_mfma_f32_16x16x32_bf16 v[110:113], v[144:147], v[186:189], v[110:113]
	v_mfma_f32_16x16x32_bf16 v[94:97], v[144:147], v[204:207], v[94:97]
	v_mfma_f32_16x16x32_bf16 v[94:97], v[148:151], v[208:211], v[94:97]
	v_mfma_f32_16x16x32_bf16 v[90:93], v[158:161], v[208:211], v[90:93]
	v_mfma_f32_16x16x32_bf16 v[90:93], v[154:157], v[204:207], v[90:93]
	v_mfma_f32_16x16x32_bf16 v[86:89], v[162:165], v[204:207], v[86:89]
	v_mfma_f32_16x16x32_bf16 v[86:89], v[166:169], v[208:211], v[86:89]
	v_mfma_f32_16x16x32_bf16 v[82:85], v[174:177], v[208:211], v[82:85]
	v_mfma_f32_16x16x32_bf16 v[82:85], v[170:173], v[204:207], v[82:85]
	v_mfma_f32_16x16x32_bf16 v[66:69], v[170:173], v[212:215], v[66:69]
	v_mfma_f32_16x16x32_bf16 v[66:69], v[174:177], v[216:219], v[66:69]
	v_mfma_f32_16x16x32_bf16 v[70:73], v[166:169], v[216:219], v[70:73]
	v_mfma_f32_16x16x32_bf16 v[70:73], v[162:165], v[212:215], v[70:73]
	v_mfma_f32_16x16x32_bf16 v[74:77], v[154:157], v[212:215], v[74:77]
	v_mfma_f32_16x16x32_bf16 v[74:77], v[158:161], v[216:219], v[74:77]
	v_mfma_f32_16x16x32_bf16 v[78:81], v[148:151], v[216:219], v[78:81]
	v_mfma_f32_16x16x32_bf16 v[78:81], v[144:147], v[212:215], v[78:81]
	s_barrier
	s_add_u32 s98, s64, 0x80
	s_addc_u32 s99, s65, 0
	s_add_u32 s100, s70, 0x80
	s_addc_u32 s101, s71, 0
	s_add_i32 s0, s18, s28
	s_mov_b32 m0, s0
	ds_read_b128 v[178:181], v152 offset:49152
	ds_read_b128 v[182:185], v152 offset:50176
	ds_read_b128 v[186:189], v152 offset:51200
	ds_read_b128 v[190:193], v152 offset:52224
	ds_read_b128 v[204:207], v152 offset:53248
	ds_read_b128 v[208:211], v152 offset:54272
	ds_read_b128 v[212:215], v152 offset:55296
	ds_read_b128 v[216:219], v152 offset:56320
	global_load_lds_dwordx4 v194, s[98:99]
	s_add_i32 m0, s0, 0x2000
	s_add_u32 s0, s64, 0x80080
	s_addc_u32 s1, s65, 0
	s_add_i32 s18, s19, s28
	global_load_lds_dwordx4 v130, s[98:99]
	s_mov_b32 m0, s18
	s_nop 0
	global_load_lds_dwordx4 v194, s[0:1]
	s_add_i32 m0, s18, 0x2000
	s_nop 0
	global_load_lds_dwordx4 v130, s[0:1]
	s_mov_b32 m0, s54
	s_nop 0
	global_load_lds_dwordx4 v194, s[100:101]
	s_mov_b32 m0, s57
	s_nop 0
	global_load_lds_dwordx4 v130, s[100:101]
	s_add_i32 s76, s76, 2
	s_add_u32 s62, s62, 0x100
	s_addc_u32 s63, s63, 0
	s_add_u32 s53, s53, 0x100
	s_addc_u32 s58, s58, 0
	s_cmp_eq_u32 s76, 28
	s_cselect_b64 s[64:65], -1, 0
	s_and_b64 s[100:101], s[64:65], s[12:13]
	s_add_u32 s18, s62, 0xfff80080
	s_addc_u32 s19, s63, -1
	s_and_b64 s[0:1], s[64:65], exec
	s_cselect_b32 s71, s22, s19
	s_cselect_b32 s70, s23, s18
	s_cselect_b32 s65, s39, s58
	s_cselect_b32 s64, s47, s53
	s_cmp_gt_u32 s76, 29
	s_waitcnt vmcnt(8)
	s_waitcnt lgkmcnt(0)
	s_barrier
	s_waitcnt lgkmcnt(0)
	v_mfma_f32_16x16x32_bf16 v[62:65], v[144:147], v[178:181], v[62:65]
	v_mfma_f32_16x16x32_bf16 v[62:65], v[148:151], v[182:185], v[62:65]
	v_mfma_f32_16x16x32_bf16 v[58:61], v[158:161], v[182:185], v[58:61]
	v_mfma_f32_16x16x32_bf16 v[58:61], v[154:157], v[178:181], v[58:61]
	v_mfma_f32_16x16x32_bf16 v[54:57], v[162:165], v[178:181], v[54:57]
	v_mfma_f32_16x16x32_bf16 v[54:57], v[166:169], v[182:185], v[54:57]
	v_mfma_f32_16x16x32_bf16 v[50:53], v[174:177], v[182:185], v[50:53]
	v_mfma_f32_16x16x32_bf16 v[50:53], v[170:173], v[178:181], v[50:53]
	v_mfma_f32_16x16x32_bf16 v[34:37], v[170:173], v[186:189], v[34:37]
	v_mfma_f32_16x16x32_bf16 v[34:37], v[174:177], v[190:193], v[34:37]
	v_mfma_f32_16x16x32_bf16 v[38:41], v[166:169], v[190:193], v[38:41]
	v_mfma_f32_16x16x32_bf16 v[38:41], v[162:165], v[186:189], v[38:41]
	v_mfma_f32_16x16x32_bf16 v[42:45], v[154:157], v[186:189], v[42:45]
	v_mfma_f32_16x16x32_bf16 v[42:45], v[158:161], v[190:193], v[42:45]
	v_mfma_f32_16x16x32_bf16 v[46:49], v[148:151], v[190:193], v[46:49]
	v_mfma_f32_16x16x32_bf16 v[46:49], v[144:147], v[186:189], v[46:49]
	v_mfma_f32_16x16x32_bf16 v[30:33], v[144:147], v[204:207], v[30:33]
	v_mfma_f32_16x16x32_bf16 v[30:33], v[148:151], v[208:211], v[30:33]
	v_mfma_f32_16x16x32_bf16 v[26:29], v[158:161], v[208:211], v[26:29]
	v_mfma_f32_16x16x32_bf16 v[26:29], v[154:157], v[204:207], v[26:29]
	v_mfma_f32_16x16x32_bf16 v[22:25], v[162:165], v[204:207], v[22:25]
	v_mfma_f32_16x16x32_bf16 v[22:25], v[166:169], v[208:211], v[22:25]
	v_mfma_f32_16x16x32_bf16 v[18:21], v[174:177], v[208:211], v[18:21]
	v_mfma_f32_16x16x32_bf16 v[18:21], v[170:173], v[204:207], v[18:21]
	v_mfma_f32_16x16x32_bf16 v[2:5], v[170:173], v[212:215], v[2:5]
	v_mfma_f32_16x16x32_bf16 v[2:5], v[174:177], v[216:219], v[2:5]
	v_mfma_f32_16x16x32_bf16 v[6:9], v[166:169], v[216:219], v[6:9]
	v_mfma_f32_16x16x32_bf16 v[6:9], v[162:165], v[212:215], v[6:9]
	v_mfma_f32_16x16x32_bf16 v[10:13], v[154:157], v[212:215], v[10:13]
	v_mfma_f32_16x16x32_bf16 v[10:13], v[158:161], v[216:219], v[10:13]
	v_mfma_f32_16x16x32_bf16 v[14:17], v[148:151], v[216:219], v[14:17]
	v_mfma_f32_16x16x32_bf16 v[14:17], v[144:147], v[212:215], v[14:17]
	s_barrier
	s_cbranch_scc1 .LBB0_584
	s_cmp_lg_u64 s[100:101], 0
	s_cbranch_scc1 .Lrot_rare_gu
	s_branch .Lrot_body_gu
.Lrot_rare_gu:
	s_mov_b32 m0, s59
	s_nop 0
	global_load_lds_dwordx4 v[140:141], off
	s_mov_b32 m0, s60
	s_nop 0
	global_load_lds_dwordx4 v[142:143], off
	s_branch .Lrot_body_gu
.Lrot_body_gu:
	s_add_i32 s0, 0, 0x10000
	v_add_u32_e32 v153, s0, v1
	s_add_i32 s18, 0, 0x14000
	ds_read_b128 v[144:147], v153
	ds_read_b128 v[148:151], v153 offset:1024
	ds_read_b128 v[154:157], v153 offset:2048
	ds_read_b128 v[158:161], v153 offset:3072
	v_add_u32_e32 v153, s18, v1
	ds_read_b128 v[162:165], v153
	ds_read_b128 v[166:169], v153 offset:1024
	ds_read_b128 v[170:173], v153 offset:2048
	ds_read_b128 v[174:177], v153 offset:3072
	s_add_i32 m0, s29, 0xc000
	ds_read_b128 v[178:181], v152
	ds_read_b128 v[182:185], v152 offset:1024
	ds_read_b128 v[186:189], v152 offset:2048
	ds_read_b128 v[190:193], v152 offset:3072
	ds_read_b128 v[204:207], v152 offset:4096
	ds_read_b128 v[208:211], v152 offset:5120
	ds_read_b128 v[212:215], v152 offset:6144
	ds_read_b128 v[216:219], v152 offset:7168
	global_load_lds_dwordx4 v136, s[62:63]
	s_add_i32 m0, s29, 0xe000
	s_nop 0
	global_load_lds_dwordx4 v138, s[62:63]
	s_waitcnt vmcnt(8)
	s_waitcnt lgkmcnt(0)
	s_barrier
	s_waitcnt lgkmcnt(0)
	v_mfma_f32_16x16x32_bf16 v[126:129], v[144:147], v[178:181], v[126:129]
	v_mfma_f32_16x16x32_bf16 v[126:129], v[148:151], v[182:185], v[126:129]
	v_mfma_f32_16x16x32_bf16 v[122:125], v[158:161], v[182:185], v[122:125]
	v_mfma_f32_16x16x32_bf16 v[122:125], v[154:157], v[178:181], v[122:125]
	v_mfma_f32_16x16x32_bf16 v[118:121], v[162:165], v[178:181], v[118:121]
	v_mfma_f32_16x16x32_bf16 v[118:121], v[166:169], v[182:185], v[118:121]
	v_mfma_f32_16x16x32_bf16 v[114:117], v[174:177], v[182:185], v[114:117]
	v_mfma_f32_16x16x32_bf16 v[114:117], v[170:173], v[178:181], v[114:117]
	v_mfma_f32_16x16x32_bf16 v[98:101], v[170:173], v[186:189], v[98:101]
	v_mfma_f32_16x16x32_bf16 v[98:101], v[174:177], v[190:193], v[98:101]
	v_mfma_f32_16x16x32_bf16 v[102:105], v[166:169], v[190:193], v[102:105]
	v_mfma_f32_16x16x32_bf16 v[102:105], v[162:165], v[186:189], v[102:105]
	v_mfma_f32_16x16x32_bf16 v[106:109], v[154:157], v[186:189], v[106:109]
	v_mfma_f32_16x16x32_bf16 v[106:109], v[158:161], v[190:193], v[106:109]
	v_mfma_f32_16x16x32_bf16 v[110:113], v[148:151], v[190:193], v[110:113]
	v_mfma_f32_16x16x32_bf16 v[110:113], v[144:147], v[186:189], v[110:113]
	v_mfma_f32_16x16x32_bf16 v[94:97], v[144:147], v[204:207], v[94:97]
	v_mfma_f32_16x16x32_bf16 v[94:97], v[148:151], v[208:211], v[94:97]
	v_mfma_f32_16x16x32_bf16 v[90:93], v[158:161], v[208:211], v[90:93]
	v_mfma_f32_16x16x32_bf16 v[90:93], v[154:157], v[204:207], v[90:93]
	v_mfma_f32_16x16x32_bf16 v[86:89], v[162:165], v[204:207], v[86:89]
	v_mfma_f32_16x16x32_bf16 v[86:89], v[166:169], v[208:211], v[86:89]
	v_mfma_f32_16x16x32_bf16 v[82:85], v[174:177], v[208:211], v[82:85]
	v_mfma_f32_16x16x32_bf16 v[82:85], v[170:173], v[204:207], v[82:85]
	v_mfma_f32_16x16x32_bf16 v[66:69], v[170:173], v[212:215], v[66:69]
	v_mfma_f32_16x16x32_bf16 v[66:69], v[174:177], v[216:219], v[66:69]
	v_mfma_f32_16x16x32_bf16 v[70:73], v[166:169], v[216:219], v[70:73]
	v_mfma_f32_16x16x32_bf16 v[70:73], v[162:165], v[212:215], v[70:73]
	v_mfma_f32_16x16x32_bf16 v[74:77], v[154:157], v[212:215], v[74:77]
	v_mfma_f32_16x16x32_bf16 v[74:77], v[158:161], v[216:219], v[74:77]
	v_mfma_f32_16x16x32_bf16 v[78:81], v[148:151], v[216:219], v[78:81]
	v_mfma_f32_16x16x32_bf16 v[78:81], v[144:147], v[212:215], v[78:81]
	s_barrier
	s_add_i32 s0, s0, s28
	s_mov_b32 m0, s0
	ds_read_b128 v[178:181], v152 offset:16384
	ds_read_b128 v[182:185], v152 offset:17408
	ds_read_b128 v[186:189], v152 offset:18432
	ds_read_b128 v[190:193], v152 offset:19456
	ds_read_b128 v[204:207], v152 offset:20480
	ds_read_b128 v[208:211], v152 offset:21504
	ds_read_b128 v[212:215], v152 offset:22528
	ds_read_b128 v[216:219], v152 offset:23552
	global_load_lds_dwordx4 v194, s[64:65]
	s_add_i32 m0, s0, 0x2000
	s_add_u32 s0, s64, 0x80000
	s_addc_u32 s1, s65, 0
	s_add_i32 s18, s18, s28
	global_load_lds_dwordx4 v130, s[64:65]
	s_mov_b32 m0, s18
	s_nop 0
	global_load_lds_dwordx4 v194, s[0:1]
	s_add_i32 m0, s18, 0x2000
	s_nop 0
	global_load_lds_dwordx4 v130, s[0:1]
	s_mov_b32 m0, s29
	s_nop 0
	global_load_lds_dwordx4 v194, s[70:71]
	s_mov_b32 m0, s31
	s_nop 0
	global_load_lds_dwordx4 v130, s[70:71]
	s_waitcnt vmcnt(8)
	s_waitcnt lgkmcnt(0)
	s_barrier
	s_waitcnt lgkmcnt(0)
	v_mfma_f32_16x16x32_bf16 v[62:65], v[144:147], v[178:181], v[62:65]
	v_mfma_f32_16x16x32_bf16 v[62:65], v[148:151], v[182:185], v[62:65]
	v_mfma_f32_16x16x32_bf16 v[58:61], v[158:161], v[182:185], v[58:61]
	v_mfma_f32_16x16x32_bf16 v[58:61], v[154:157], v[178:181], v[58:61]
	v_mfma_f32_16x16x32_bf16 v[54:57], v[162:165], v[178:181], v[54:57]
	v_mfma_f32_16x16x32_bf16 v[54:57], v[166:169], v[182:185], v[54:57]
	v_mfma_f32_16x16x32_bf16 v[50:53], v[174:177], v[182:185], v[50:53]
	v_mfma_f32_16x16x32_bf16 v[50:53], v[170:173], v[178:181], v[50:53]
	v_mfma_f32_16x16x32_bf16 v[34:37], v[170:173], v[186:189], v[34:37]
	v_mfma_f32_16x16x32_bf16 v[34:37], v[174:177], v[190:193], v[34:37]
	v_mfma_f32_16x16x32_bf16 v[38:41], v[166:169], v[190:193], v[38:41]
	v_mfma_f32_16x16x32_bf16 v[38:41], v[162:165], v[186:189], v[38:41]
	v_mfma_f32_16x16x32_bf16 v[42:45], v[154:157], v[186:189], v[42:45]
	v_mfma_f32_16x16x32_bf16 v[42:45], v[158:161], v[190:193], v[42:45]
	v_mfma_f32_16x16x32_bf16 v[46:49], v[148:151], v[190:193], v[46:49]
	v_mfma_f32_16x16x32_bf16 v[46:49], v[144:147], v[186:189], v[46:49]
	v_mfma_f32_16x16x32_bf16 v[30:33], v[144:147], v[204:207], v[30:33]
	v_mfma_f32_16x16x32_bf16 v[30:33], v[148:151], v[208:211], v[30:33]
	v_mfma_f32_16x16x32_bf16 v[26:29], v[158:161], v[208:211], v[26:29]
	v_mfma_f32_16x16x32_bf16 v[26:29], v[154:157], v[204:207], v[26:29]
	v_mfma_f32_16x16x32_bf16 v[22:25], v[162:165], v[204:207], v[22:25]
	v_mfma_f32_16x16x32_bf16 v[22:25], v[166:169], v[208:211], v[22:25]
	v_mfma_f32_16x16x32_bf16 v[18:21], v[174:177], v[208:211], v[18:21]
	v_mfma_f32_16x16x32_bf16 v[18:21], v[170:173], v[204:207], v[18:21]
	v_mfma_f32_16x16x32_bf16 v[2:5], v[170:173], v[212:215], v[2:5]
	v_mfma_f32_16x16x32_bf16 v[2:5], v[174:177], v[216:219], v[2:5]
	v_mfma_f32_16x16x32_bf16 v[6:9], v[166:169], v[216:219], v[6:9]
	v_mfma_f32_16x16x32_bf16 v[6:9], v[162:165], v[212:215], v[6:9]
	v_mfma_f32_16x16x32_bf16 v[10:13], v[154:157], v[212:215], v[10:13]
	v_mfma_f32_16x16x32_bf16 v[10:13], v[158:161], v[216:219], v[10:13]
	v_mfma_f32_16x16x32_bf16 v[14:17], v[148:151], v[216:219], v[14:17]
	v_mfma_f32_16x16x32_bf16 v[14:17], v[144:147], v[212:215], v[14:17]
	s_barrier
	s_add_i32 s18, 0, 0x18000
	v_add_u32_e32 v153, s18, v1
	s_add_i32 s19, 0, 0x1c000
	ds_read_b128 v[144:147], v153
	ds_read_b128 v[148:151], v153 offset:1024
	ds_read_b128 v[154:157], v153 offset:2048
	ds_read_b128 v[158:161], v153 offset:3072
	v_add_u32_e32 v153, s19, v1
	ds_read_b128 v[162:165], v153
	ds_read_b128 v[166:169], v153 offset:1024
	ds_read_b128 v[170:173], v153 offset:2048
	ds_read_b128 v[174:177], v153 offset:3072
	s_add_u32 s0, s70, 0x80000
	s_addc_u32 s1, s71, 0
	s_mov_b32 m0, s33
	ds_read_b128 v[178:181], v152 offset:32768
	ds_read_b128 v[182:185], v152 offset:33792
	ds_read_b128 v[186:189], v152 offset:34816
	ds_read_b128 v[190:193], v152 offset:35840
	ds_read_b128 v[204:207], v152 offset:36864
	ds_read_b128 v[208:211], v152 offset:37888
	ds_read_b128 v[212:215], v152 offset:38912
	ds_read_b128 v[216:219], v152 offset:39936
	global_load_lds_dwordx4 v194, s[0:1]
	s_mov_b32 m0, s40
	s_nop 0
	global_load_lds_dwordx4 v130, s[0:1]
	s_waitcnt vmcnt(8)
	s_waitcnt lgkmcnt(0)
	s_barrier
	s_waitcnt lgkmcnt(0)
	v_mfma_f32_16x16x32_bf16 v[126:129], v[144:147], v[178:181], v[126:129]
	v_mfma_f32_16x16x32_bf16 v[126:129], v[148:151], v[182:185], v[126:129]
	v_mfma_f32_16x16x32_bf16 v[122:125], v[158:161], v[182:185], v[122:125]
	v_mfma_f32_16x16x32_bf16 v[122:125], v[154:157], v[178:181], v[122:125]
	v_mfma_f32_16x16x32_bf16 v[118:121], v[162:165], v[178:181], v[118:121]
	v_mfma_f32_16x16x32_bf16 v[118:121], v[166:169], v[182:185], v[118:121]
	v_mfma_f32_16x16x32_bf16 v[114:117], v[174:177], v[182:185], v[114:117]
	v_mfma_f32_16x16x32_bf16 v[114:117], v[170:173], v[178:181], v[114:117]
	v_mfma_f32_16x16x32_bf16 v[98:101], v[170:173], v[186:189], v[98:101]
	v_mfma_f32_16x16x32_bf16 v[98:101], v[174:177], v[190:193], v[98:101]
	v_mfma_f32_16x16x32_bf16 v[102:105], v[166:169], v[190:193], v[102:105]
	v_mfma_f32_16x16x32_bf16 v[102:105], v[162:165], v[186:189], v[102:105]
	v_mfma_f32_16x16x32_bf16 v[106:109], v[154:157], v[186:189], v[106:109]
	v_mfma_f32_16x16x32_bf16 v[106:109], v[158:161], v[190:193], v[106:109]
	v_mfma_f32_16x16x32_bf16 v[110:113], v[148:151], v[190:193], v[110:113]
	v_mfma_f32_16x16x32_bf16 v[110:113], v[144:147], v[186:189], v[110:113]
	v_mfma_f32_16x16x32_bf16 v[94:97], v[144:147], v[204:207], v[94:97]
	v_mfma_f32_16x16x32_bf16 v[94:97], v[148:151], v[208:211], v[94:97]
	v_mfma_f32_16x16x32_bf16 v[90:93], v[158:161], v[208:211], v[90:93]
	v_mfma_f32_16x16x32_bf16 v[90:93], v[154:157], v[204:207], v[90:93]
	v_mfma_f32_16x16x32_bf16 v[86:89], v[162:165], v[204:207], v[86:89]
	v_mfma_f32_16x16x32_bf16 v[86:89], v[166:169], v[208:211], v[86:89]
	v_mfma_f32_16x16x32_bf16 v[82:85], v[174:177], v[208:211], v[82:85]
	v_mfma_f32_16x16x32_bf16 v[82:85], v[170:173], v[204:207], v[82:85]
	v_mfma_f32_16x16x32_bf16 v[66:69], v[170:173], v[212:215], v[66:69]
	v_mfma_f32_16x16x32_bf16 v[66:69], v[174:177], v[216:219], v[66:69]
	v_mfma_f32_16x16x32_bf16 v[70:73], v[166:169], v[216:219], v[70:73]
	v_mfma_f32_16x16x32_bf16 v[70:73], v[162:165], v[212:215], v[70:73]
	v_mfma_f32_16x16x32_bf16 v[74:77], v[154:157], v[212:215], v[74:77]
	v_mfma_f32_16x16x32_bf16 v[74:77], v[158:161], v[216:219], v[74:77]
	v_mfma_f32_16x16x32_bf16 v[78:81], v[148:151], v[216:219], v[78:81]
	v_mfma_f32_16x16x32_bf16 v[78:81], v[144:147], v[212:215], v[78:81]
	s_barrier
	s_add_u32 s98, s64, 0x80
	s_addc_u32 s99, s65, 0
	s_add_u32 s100, s70, 0x80
	s_addc_u32 s101, s71, 0
	s_add_i32 s0, s18, s28
	s_mov_b32 m0, s0
	ds_read_b128 v[178:181], v152 offset:49152
	ds_read_b128 v[182:185], v152 offset:50176
	ds_read_b128 v[186:189], v152 offset:51200
	ds_read_b128 v[190:193], v152 offset:52224
	ds_read_b128 v[204:207], v152 offset:53248
	ds_read_b128 v[208:211], v152 offset:54272
	ds_read_b128 v[212:215], v152 offset:55296
	ds_read_b128 v[216:219], v152 offset:56320
	global_load_lds_dwordx4 v194, s[98:99]
	s_add_i32 m0, s0, 0x2000
	s_add_u32 s0, s64, 0x80080
	s_addc_u32 s1, s65, 0
	s_add_i32 s18, s19, s28
	global_load_lds_dwordx4 v130, s[98:99]
	s_mov_b32 m0, s18
	s_nop 0
	global_load_lds_dwordx4 v194, s[0:1]
	s_add_i32 m0, s18, 0x2000
	s_nop 0
	global_load_lds_dwordx4 v130, s[0:1]
	s_mov_b32 m0, s54
	s_nop 0
	global_load_lds_dwordx4 v194, s[100:101]
	s_mov_b32 m0, s57
	s_nop 0
	global_load_lds_dwordx4 v130, s[100:101]
	s_add_i32 s76, s76, 2
	s_add_u32 s62, s62, 0x100
	s_addc_u32 s63, s63, 0
	s_add_u32 s53, s53, 0x100
	s_addc_u32 s58, s58, 0
	s_cmp_eq_u32 s76, 28
	s_cselect_b64 s[64:65], -1, 0
	s_and_b64 s[100:101], s[64:65], s[12:13]
	s_add_u32 s18, s62, 0xfff80080
	s_addc_u32 s19, s63, -1
	s_and_b64 s[0:1], s[64:65], exec
	s_cselect_b32 s71, s22, s19
	s_cselect_b32 s70, s23, s18
	s_cselect_b32 s65, s39, s58
	s_cselect_b32 s64, s47, s53
	s_cmp_gt_u32 s76, 29
	s_waitcnt vmcnt(8)
	s_waitcnt lgkmcnt(0)
	s_barrier
	s_waitcnt lgkmcnt(0)
	v_mfma_f32_16x16x32_bf16 v[62:65], v[144:147], v[178:181], v[62:65]
	v_mfma_f32_16x16x32_bf16 v[62:65], v[148:151], v[182:185], v[62:65]
	v_mfma_f32_16x16x32_bf16 v[58:61], v[158:161], v[182:185], v[58:61]
	v_mfma_f32_16x16x32_bf16 v[58:61], v[154:157], v[178:181], v[58:61]
	v_mfma_f32_16x16x32_bf16 v[54:57], v[162:165], v[178:181], v[54:57]
	v_mfma_f32_16x16x32_bf16 v[54:57], v[166:169], v[182:185], v[54:57]
	v_mfma_f32_16x16x32_bf16 v[50:53], v[174:177], v[182:185], v[50:53]
	v_mfma_f32_16x16x32_bf16 v[50:53], v[170:173], v[178:181], v[50:53]
	v_mfma_f32_16x16x32_bf16 v[34:37], v[170:173], v[186:189], v[34:37]
	v_mfma_f32_16x16x32_bf16 v[34:37], v[174:177], v[190:193], v[34:37]
	v_mfma_f32_16x16x32_bf16 v[38:41], v[166:169], v[190:193], v[38:41]
	v_mfma_f32_16x16x32_bf16 v[38:41], v[162:165], v[186:189], v[38:41]
	v_mfma_f32_16x16x32_bf16 v[42:45], v[154:157], v[186:189], v[42:45]
	v_mfma_f32_16x16x32_bf16 v[42:45], v[158:161], v[190:193], v[42:45]
	v_mfma_f32_16x16x32_bf16 v[46:49], v[148:151], v[190:193], v[46:49]
	v_mfma_f32_16x16x32_bf16 v[46:49], v[144:147], v[186:189], v[46:49]
	v_mfma_f32_16x16x32_bf16 v[30:33], v[144:147], v[204:207], v[30:33]
	v_mfma_f32_16x16x32_bf16 v[30:33], v[148:151], v[208:211], v[30:33]
	v_mfma_f32_16x16x32_bf16 v[26:29], v[158:161], v[208:211], v[26:29]
	v_mfma_f32_16x16x32_bf16 v[26:29], v[154:157], v[204:207], v[26:29]
	v_mfma_f32_16x16x32_bf16 v[22:25], v[162:165], v[204:207], v[22:25]
	v_mfma_f32_16x16x32_bf16 v[22:25], v[166:169], v[208:211], v[22:25]
	v_mfma_f32_16x16x32_bf16 v[18:21], v[174:177], v[208:211], v[18:21]
	v_mfma_f32_16x16x32_bf16 v[18:21], v[170:173], v[204:207], v[18:21]
	v_mfma_f32_16x16x32_bf16 v[2:5], v[170:173], v[212:215], v[2:5]
	v_mfma_f32_16x16x32_bf16 v[2:5], v[174:177], v[216:219], v[2:5]
	v_mfma_f32_16x16x32_bf16 v[6:9], v[166:169], v[216:219], v[6:9]
	v_mfma_f32_16x16x32_bf16 v[6:9], v[162:165], v[212:215], v[6:9]
	v_mfma_f32_16x16x32_bf16 v[10:13], v[154:157], v[212:215], v[10:13]
	v_mfma_f32_16x16x32_bf16 v[10:13], v[158:161], v[216:219], v[10:13]
	v_mfma_f32_16x16x32_bf16 v[14:17], v[148:151], v[216:219], v[14:17]
	v_mfma_f32_16x16x32_bf16 v[14:17], v[144:147], v[212:215], v[14:17]
	s_barrier
	s_cbranch_scc1 .LBB0_584
	s_cmp_lg_u64 s[100:101], 0
	s_cbranch_scc1 .Lrot_rare_gu
	s_branch .Lrot_body_gu

.LBB0_645:
.LBB0_646:
	s_cmpk_eq_i32 s41, 0x54
	s_cselect_b64 s[70:71], -1, 0
	s_and_b64 s[0:1], s[70:71], s[50:51]
	s_andn2_b64 vcc, exec, s[0:1]
	s_cbranch_vccnz .Lpeel_disp_down
	s_mov_b32 m0, s59
	s_nop 0
	global_load_lds_dwordx4 v[66:67], off
	s_mov_b32 m0, s60
	s_nop 0
	global_load_lds_dwordx4 v[68:69], off
	s_branch .Lpeel_disp_down
.Lpeel_disp_down:
	s_add_u32 s64, s8, 0x100
	s_addc_u32 s65, s9, 0
	s_and_b64 s[0:1], s[70:71], exec
	s_cselect_b32 s77, s63, s65
	s_cselect_b32 s76, s62, s64
	s_cselect_b32 s71, s85, s23
	s_cselect_b32 s70, s84, s7
	s_add_i32 s0, 0, 0x10000
	s_add_i32 s18, 0, 0x14000
	v_add_u32_e32 v106, s0, v1
	v_add_u32_e32 v154, s18, v1
	ds_read_b128 v[70:73], v106
	ds_read_b128 v[82:85], v106 offset:1024
	ds_read_b128 v[94:97], v106 offset:2048
	ds_read_b128 v[106:109], v106 offset:3072
	ds_read_b128 v[118:121], v154
	ds_read_b128 v[130:133], v154 offset:1024
	ds_read_b128 v[142:145], v154 offset:2048
	ds_read_b128 v[154:157], v154 offset:3072
	s_add_i32 m0, s29, 0xc000
	ds_read_b128 v[158:161], v237
	ds_read_b128 v[170:173], v237 offset:1024
	ds_read_b128 v[174:177], v237 offset:2048
	ds_read_b128 v[178:181], v237 offset:3072
	ds_read_b128 v[182:185], v237 offset:4096
	ds_read_b128 v[186:189], v237 offset:5120
	ds_read_b128 v[210:213], v237 offset:6144
	ds_read_b128 v[214:217], v237 offset:7168
	global_load_lds_dwordx4 v206, s[8:9]
	s_add_i32 m0, s29, 0xe000
	s_nop 0
	global_load_lds_dwordx4 v208, s[8:9]
	s_waitcnt vmcnt(8)
	s_waitcnt lgkmcnt(0)
	s_barrier
	s_waitcnt lgkmcnt(0)
	v_mfma_f32_16x16x32_bf16 v[166:169], v[70:73], v[158:161], 0
	v_mfma_f32_16x16x32_bf16 v[166:169], v[82:85], v[170:173], v[166:169]
	v_mfma_f32_16x16x32_bf16 v[162:165], v[106:109], v[170:173], 0
	v_mfma_f32_16x16x32_bf16 v[162:165], v[94:97], v[158:161], v[162:165]
	v_mfma_f32_16x16x32_bf16 v[150:153], v[118:121], v[158:161], 0
	v_mfma_f32_16x16x32_bf16 v[150:153], v[130:133], v[170:173], v[150:153]
	v_mfma_f32_16x16x32_bf16 v[146:149], v[154:157], v[170:173], 0
	v_mfma_f32_16x16x32_bf16 v[146:149], v[142:145], v[158:161], v[146:149]
	v_mfma_f32_16x16x32_bf16 v[122:125], v[142:145], v[174:177], 0
	v_mfma_f32_16x16x32_bf16 v[122:125], v[154:157], v[178:181], v[122:125]
	v_mfma_f32_16x16x32_bf16 v[126:129], v[130:133], v[178:181], 0
	v_mfma_f32_16x16x32_bf16 v[126:129], v[118:121], v[174:177], v[126:129]
	v_mfma_f32_16x16x32_bf16 v[134:137], v[94:97], v[174:177], 0
	v_mfma_f32_16x16x32_bf16 v[134:137], v[106:109], v[178:181], v[134:137]
	v_mfma_f32_16x16x32_bf16 v[138:141], v[82:85], v[178:181], 0
	v_mfma_f32_16x16x32_bf16 v[138:141], v[70:73], v[174:177], v[138:141]
	v_mfma_f32_16x16x32_bf16 v[114:117], v[70:73], v[182:185], 0
	v_mfma_f32_16x16x32_bf16 v[114:117], v[82:85], v[186:189], v[114:117]
	v_mfma_f32_16x16x32_bf16 v[110:113], v[106:109], v[186:189], 0
	v_mfma_f32_16x16x32_bf16 v[110:113], v[94:97], v[182:185], v[110:113]
	v_mfma_f32_16x16x32_bf16 v[102:105], v[118:121], v[182:185], 0
	v_mfma_f32_16x16x32_bf16 v[102:105], v[130:133], v[186:189], v[102:105]
	v_mfma_f32_16x16x32_bf16 v[98:101], v[154:157], v[186:189], 0
	v_mfma_f32_16x16x32_bf16 v[98:101], v[142:145], v[182:185], v[98:101]
	v_mfma_f32_16x16x32_bf16 v[74:77], v[142:145], v[210:213], 0
	v_mfma_f32_16x16x32_bf16 v[74:77], v[154:157], v[214:217], v[74:77]
	v_mfma_f32_16x16x32_bf16 v[78:81], v[130:133], v[214:217], 0
	v_mfma_f32_16x16x32_bf16 v[78:81], v[118:121], v[210:213], v[78:81]
	v_mfma_f32_16x16x32_bf16 v[86:89], v[94:97], v[210:213], 0
	v_mfma_f32_16x16x32_bf16 v[86:89], v[106:109], v[214:217], v[86:89]
	v_mfma_f32_16x16x32_bf16 v[90:93], v[82:85], v[214:217], 0
	v_mfma_f32_16x16x32_bf16 v[90:93], v[70:73], v[210:213], v[90:93]
	s_barrier
	s_add_i32 s0, s0, s28
	s_mov_b32 m0, s0
	ds_read_b128 v[158:161], v237 offset:16384
	ds_read_b128 v[170:173], v237 offset:17408
	ds_read_b128 v[174:177], v237 offset:18432
	ds_read_b128 v[178:181], v237 offset:19456
	ds_read_b128 v[182:185], v237 offset:20480
	ds_read_b128 v[186:189], v237 offset:21504
	ds_read_b128 v[210:213], v237 offset:22528
	ds_read_b128 v[214:217], v237 offset:23552
	global_load_lds_dwordx4 v192, s[70:71]
	s_add_i32 m0, s0, 0x2000
	s_add_u32 s0, s70, 0x160000
	s_addc_u32 s1, s71, 0
	s_add_i32 s8, s18, s28
	global_load_lds_dwordx4 v190, s[70:71]
	s_mov_b32 m0, s8
	s_nop 0
	global_load_lds_dwordx4 v192, s[0:1]
	s_add_i32 m0, s8, 0x2000
	s_nop 0
	global_load_lds_dwordx4 v190, s[0:1]
	s_mov_b32 m0, s29
	s_nop 0
	global_load_lds_dwordx4 v192, s[76:77]
	s_mov_b32 m0, s31
	s_nop 0
	global_load_lds_dwordx4 v190, s[76:77]
	s_waitcnt vmcnt(8)
	s_waitcnt lgkmcnt(0)
	s_barrier
	s_waitcnt lgkmcnt(0)
	v_mfma_f32_16x16x32_bf16 v[62:65], v[70:73], v[158:161], 0
	v_mfma_f32_16x16x32_bf16 v[62:65], v[82:85], v[170:173], v[62:65]
	v_mfma_f32_16x16x32_bf16 v[58:61], v[106:109], v[170:173], 0
	v_mfma_f32_16x16x32_bf16 v[58:61], v[94:97], v[158:161], v[58:61]
	v_mfma_f32_16x16x32_bf16 v[54:57], v[118:121], v[158:161], 0
	v_mfma_f32_16x16x32_bf16 v[54:57], v[130:133], v[170:173], v[54:57]
	v_mfma_f32_16x16x32_bf16 v[50:53], v[154:157], v[170:173], 0
	v_mfma_f32_16x16x32_bf16 v[50:53], v[142:145], v[158:161], v[50:53]
	v_mfma_f32_16x16x32_bf16 v[34:37], v[142:145], v[174:177], 0
	v_mfma_f32_16x16x32_bf16 v[34:37], v[154:157], v[178:181], v[34:37]
	v_mfma_f32_16x16x32_bf16 v[38:41], v[130:133], v[178:181], 0
	v_mfma_f32_16x16x32_bf16 v[38:41], v[118:121], v[174:177], v[38:41]
	v_mfma_f32_16x16x32_bf16 v[42:45], v[94:97], v[174:177], 0
	v_mfma_f32_16x16x32_bf16 v[42:45], v[106:109], v[178:181], v[42:45]
	v_mfma_f32_16x16x32_bf16 v[46:49], v[82:85], v[178:181], 0
	v_mfma_f32_16x16x32_bf16 v[46:49], v[70:73], v[174:177], v[46:49]
	v_mfma_f32_16x16x32_bf16 v[30:33], v[70:73], v[182:185], 0
	v_mfma_f32_16x16x32_bf16 v[30:33], v[82:85], v[186:189], v[30:33]
	v_mfma_f32_16x16x32_bf16 v[26:29], v[106:109], v[186:189], 0
	v_mfma_f32_16x16x32_bf16 v[26:29], v[94:97], v[182:185], v[26:29]
	v_mfma_f32_16x16x32_bf16 v[22:25], v[118:121], v[182:185], 0
	v_mfma_f32_16x16x32_bf16 v[22:25], v[130:133], v[186:189], v[22:25]
	v_mfma_f32_16x16x32_bf16 v[18:21], v[154:157], v[186:189], 0
	v_mfma_f32_16x16x32_bf16 v[18:21], v[142:145], v[182:185], v[18:21]
	v_mfma_f32_16x16x32_bf16 v[2:5], v[142:145], v[210:213], 0
	v_mfma_f32_16x16x32_bf16 v[2:5], v[154:157], v[214:217], v[2:5]
	v_mfma_f32_16x16x32_bf16 v[6:9], v[130:133], v[214:217], 0
	v_mfma_f32_16x16x32_bf16 v[6:9], v[118:121], v[210:213], v[6:9]
	v_mfma_f32_16x16x32_bf16 v[10:13], v[94:97], v[210:213], 0
	v_mfma_f32_16x16x32_bf16 v[10:13], v[106:109], v[214:217], v[10:13]
	v_mfma_f32_16x16x32_bf16 v[14:17], v[82:85], v[214:217], 0
	v_mfma_f32_16x16x32_bf16 v[14:17], v[70:73], v[210:213], v[14:17]
	s_barrier
	s_add_i32 s8, 0, 0x18000
	s_add_i32 s9, 0, 0x1c000
	v_add_u32_e32 v106, s8, v1
	v_add_u32_e32 v154, s9, v1
	ds_read_b128 v[70:73], v106
	ds_read_b128 v[82:85], v106 offset:1024
	ds_read_b128 v[94:97], v106 offset:2048
	ds_read_b128 v[106:109], v106 offset:3072
	ds_read_b128 v[118:121], v154
	ds_read_b128 v[130:133], v154 offset:1024
	ds_read_b128 v[142:145], v154 offset:2048
	ds_read_b128 v[154:157], v154 offset:3072
	s_add_u32 s0, s76, 0x160000
	s_addc_u32 s1, s77, 0
	s_mov_b32 m0, s33
	ds_read_b128 v[158:161], v237 offset:32768
	ds_read_b128 v[170:173], v237 offset:33792
	ds_read_b128 v[174:177], v237 offset:34816
	ds_read_b128 v[178:181], v237 offset:35840
	ds_read_b128 v[182:185], v237 offset:36864
	ds_read_b128 v[186:189], v237 offset:37888
	ds_read_b128 v[210:213], v237 offset:38912
	ds_read_b128 v[214:217], v237 offset:39936
	global_load_lds_dwordx4 v192, s[0:1]
	s_mov_b32 m0, s43
	s_nop 0
	global_load_lds_dwordx4 v190, s[0:1]
	s_waitcnt vmcnt(8)
	s_waitcnt lgkmcnt(0)
	s_barrier
	s_waitcnt lgkmcnt(0)
	v_mfma_f32_16x16x32_bf16 v[166:169], v[70:73], v[158:161], v[166:169]
	v_mfma_f32_16x16x32_bf16 v[166:169], v[82:85], v[170:173], v[166:169]
	v_mfma_f32_16x16x32_bf16 v[162:165], v[106:109], v[170:173], v[162:165]
	v_mfma_f32_16x16x32_bf16 v[162:165], v[94:97], v[158:161], v[162:165]
	v_mfma_f32_16x16x32_bf16 v[150:153], v[118:121], v[158:161], v[150:153]
	v_mfma_f32_16x16x32_bf16 v[150:153], v[130:133], v[170:173], v[150:153]
	v_mfma_f32_16x16x32_bf16 v[146:149], v[154:157], v[170:173], v[146:149]
	v_mfma_f32_16x16x32_bf16 v[146:149], v[142:145], v[158:161], v[146:149]
	v_mfma_f32_16x16x32_bf16 v[122:125], v[142:145], v[174:177], v[122:125]
	v_mfma_f32_16x16x32_bf16 v[122:125], v[154:157], v[178:181], v[122:125]
	v_mfma_f32_16x16x32_bf16 v[126:129], v[130:133], v[178:181], v[126:129]
	v_mfma_f32_16x16x32_bf16 v[126:129], v[118:121], v[174:177], v[126:129]
	v_mfma_f32_16x16x32_bf16 v[134:137], v[94:97], v[174:177], v[134:137]
	v_mfma_f32_16x16x32_bf16 v[134:137], v[106:109], v[178:181], v[134:137]
	v_mfma_f32_16x16x32_bf16 v[138:141], v[82:85], v[178:181], v[138:141]
	v_mfma_f32_16x16x32_bf16 v[138:141], v[70:73], v[174:177], v[138:141]
	v_mfma_f32_16x16x32_bf16 v[114:117], v[70:73], v[182:185], v[114:117]
	v_mfma_f32_16x16x32_bf16 v[114:117], v[82:85], v[186:189], v[114:117]
	v_mfma_f32_16x16x32_bf16 v[110:113], v[106:109], v[186:189], v[110:113]
	v_mfma_f32_16x16x32_bf16 v[110:113], v[94:97], v[182:185], v[110:113]
	v_mfma_f32_16x16x32_bf16 v[102:105], v[118:121], v[182:185], v[102:105]
	v_mfma_f32_16x16x32_bf16 v[102:105], v[130:133], v[186:189], v[102:105]
	v_mfma_f32_16x16x32_bf16 v[98:101], v[154:157], v[186:189], v[98:101]
	v_mfma_f32_16x16x32_bf16 v[98:101], v[142:145], v[182:185], v[98:101]
	v_mfma_f32_16x16x32_bf16 v[74:77], v[142:145], v[210:213], v[74:77]
	v_mfma_f32_16x16x32_bf16 v[74:77], v[154:157], v[214:217], v[74:77]
	v_mfma_f32_16x16x32_bf16 v[78:81], v[130:133], v[214:217], v[78:81]
	v_mfma_f32_16x16x32_bf16 v[78:81], v[118:121], v[210:213], v[78:81]
	v_mfma_f32_16x16x32_bf16 v[86:89], v[94:97], v[210:213], v[86:89]
	v_mfma_f32_16x16x32_bf16 v[86:89], v[106:109], v[214:217], v[86:89]
	v_mfma_f32_16x16x32_bf16 v[90:93], v[82:85], v[214:217], v[90:93]
	v_mfma_f32_16x16x32_bf16 v[90:93], v[70:73], v[210:213], v[90:93]
	s_barrier
	s_add_u32 s98, s70, 0x80
	s_addc_u32 s99, s71, 0
	s_add_u32 s100, s76, 0x80
	s_addc_u32 s101, s77, 0
	s_add_i32 s0, s8, s28
	s_mov_b32 m0, s0
	ds_read_b128 v[158:161], v237 offset:49152
	ds_read_b128 v[170:173], v237 offset:50176
	ds_read_b128 v[174:177], v237 offset:51200
	ds_read_b128 v[178:181], v237 offset:52224
	ds_read_b128 v[182:185], v237 offset:53248
	ds_read_b128 v[186:189], v237 offset:54272
	ds_read_b128 v[210:213], v237 offset:55296
	ds_read_b128 v[214:217], v237 offset:56320
	global_load_lds_dwordx4 v192, s[98:99]
	s_add_i32 m0, s0, 0x2000
	s_add_u32 s0, s70, 0x160080
	s_addc_u32 s1, s71, 0
	s_add_i32 s8, s9, s28
	global_load_lds_dwordx4 v190, s[98:99]
	s_mov_b32 m0, s8
	s_nop 0
	global_load_lds_dwordx4 v192, s[0:1]
	s_add_i32 m0, s8, 0x2000
	s_nop 0
	global_load_lds_dwordx4 v190, s[0:1]
	s_mov_b32 m0, s68
	s_nop 0
	global_load_lds_dwordx4 v192, s[100:101]
	s_mov_b32 m0, s79
	s_nop 0
	global_load_lds_dwordx4 v190, s[100:101]
	s_add_i32 s41, s41, 2
	s_add_u32 s7, s7, 0x100
	s_addc_u32 s23, s23, 0
	s_mov_b64 s[8:9], s[64:65]
	s_cmpk_eq_i32 s41, 0x54
	s_cselect_b64 s[70:71], -1, 0
	s_and_b64 s[100:101], s[70:71], s[50:51]
	s_add_u32 s64, s8, 0x100
	s_addc_u32 s65, s9, 0
	s_and_b64 s[0:1], s[70:71], exec
	s_cselect_b32 s77, s63, s65
	s_cselect_b32 s76, s62, s64
	s_cselect_b32 s71, s85, s23
	s_cselect_b32 s70, s84, s7
	s_cmpk_gt_u32 s41, 0x55
	s_waitcnt vmcnt(8)
	s_waitcnt lgkmcnt(0)
	s_barrier
	s_waitcnt lgkmcnt(0)
	v_mfma_f32_16x16x32_bf16 v[62:65], v[70:73], v[158:161], v[62:65]
	v_mfma_f32_16x16x32_bf16 v[62:65], v[82:85], v[170:173], v[62:65]
	v_mfma_f32_16x16x32_bf16 v[58:61], v[106:109], v[170:173], v[58:61]
	v_mfma_f32_16x16x32_bf16 v[58:61], v[94:97], v[158:161], v[58:61]
	v_mfma_f32_16x16x32_bf16 v[54:57], v[118:121], v[158:161], v[54:57]
	v_mfma_f32_16x16x32_bf16 v[54:57], v[130:133], v[170:173], v[54:57]
	v_mfma_f32_16x16x32_bf16 v[50:53], v[154:157], v[170:173], v[50:53]
	v_mfma_f32_16x16x32_bf16 v[50:53], v[142:145], v[158:161], v[50:53]
	v_mfma_f32_16x16x32_bf16 v[34:37], v[142:145], v[174:177], v[34:37]
	v_mfma_f32_16x16x32_bf16 v[34:37], v[154:157], v[178:181], v[34:37]
	v_mfma_f32_16x16x32_bf16 v[38:41], v[130:133], v[178:181], v[38:41]
	v_mfma_f32_16x16x32_bf16 v[38:41], v[118:121], v[174:177], v[38:41]
	v_mfma_f32_16x16x32_bf16 v[42:45], v[94:97], v[174:177], v[42:45]
	v_mfma_f32_16x16x32_bf16 v[42:45], v[106:109], v[178:181], v[42:45]
	v_mfma_f32_16x16x32_bf16 v[46:49], v[82:85], v[178:181], v[46:49]
	v_mfma_f32_16x16x32_bf16 v[46:49], v[70:73], v[174:177], v[46:49]
	v_mfma_f32_16x16x32_bf16 v[30:33], v[70:73], v[182:185], v[30:33]
	v_mfma_f32_16x16x32_bf16 v[30:33], v[82:85], v[186:189], v[30:33]
	v_mfma_f32_16x16x32_bf16 v[26:29], v[106:109], v[186:189], v[26:29]
	v_mfma_f32_16x16x32_bf16 v[26:29], v[94:97], v[182:185], v[26:29]
	v_mfma_f32_16x16x32_bf16 v[22:25], v[118:121], v[182:185], v[22:25]
	v_mfma_f32_16x16x32_bf16 v[22:25], v[130:133], v[186:189], v[22:25]
	v_mfma_f32_16x16x32_bf16 v[18:21], v[154:157], v[186:189], v[18:21]
	v_mfma_f32_16x16x32_bf16 v[18:21], v[142:145], v[182:185], v[18:21]
	v_mfma_f32_16x16x32_bf16 v[2:5], v[142:145], v[210:213], v[2:5]
	v_mfma_f32_16x16x32_bf16 v[2:5], v[154:157], v[214:217], v[2:5]
	v_mfma_f32_16x16x32_bf16 v[6:9], v[130:133], v[214:217], v[6:9]
	v_mfma_f32_16x16x32_bf16 v[6:9], v[118:121], v[210:213], v[6:9]
	v_mfma_f32_16x16x32_bf16 v[10:13], v[94:97], v[210:213], v[10:13]
	v_mfma_f32_16x16x32_bf16 v[10:13], v[106:109], v[214:217], v[10:13]
	v_mfma_f32_16x16x32_bf16 v[14:17], v[82:85], v[214:217], v[14:17]
	v_mfma_f32_16x16x32_bf16 v[14:17], v[70:73], v[210:213], v[14:17]
	s_barrier
	s_cbranch_scc1 .LBB0_648
	s_cmp_lg_u64 s[100:101], 0
	s_cbranch_scc1 .Lrot_rare_down
	s_branch .Lrot_body_down
.Lrot_rare_down:
	s_mov_b32 m0, s59
	s_nop 0
	global_load_lds_dwordx4 v[66:67], off
	s_mov_b32 m0, s60
	s_nop 0
	global_load_lds_dwordx4 v[68:69], off
	s_branch .Lrot_body_down
.Lrot_body_down:
	s_add_i32 s0, 0, 0x10000
	s_add_i32 s18, 0, 0x14000
	v_add_u32_e32 v106, s0, v1
	v_add_u32_e32 v154, s18, v1
	ds_read_b128 v[70:73], v106
	ds_read_b128 v[82:85], v106 offset:1024
	ds_read_b128 v[94:97], v106 offset:2048
	ds_read_b128 v[106:109], v106 offset:3072
	ds_read_b128 v[118:121], v154
	ds_read_b128 v[130:133], v154 offset:1024
	ds_read_b128 v[142:145], v154 offset:2048
	ds_read_b128 v[154:157], v154 offset:3072
	s_add_i32 m0, s29, 0xc000
	ds_read_b128 v[158:161], v237
	ds_read_b128 v[170:173], v237 offset:1024
	ds_read_b128 v[174:177], v237 offset:2048
	ds_read_b128 v[178:181], v237 offset:3072
	ds_read_b128 v[182:185], v237 offset:4096
	ds_read_b128 v[186:189], v237 offset:5120
	ds_read_b128 v[210:213], v237 offset:6144
	ds_read_b128 v[214:217], v237 offset:7168
	global_load_lds_dwordx4 v206, s[8:9]
	s_add_i32 m0, s29, 0xe000
	s_nop 0
	global_load_lds_dwordx4 v208, s[8:9]
	s_waitcnt vmcnt(8)
	s_waitcnt lgkmcnt(0)
	s_barrier
	s_waitcnt lgkmcnt(0)
	v_mfma_f32_16x16x32_bf16 v[166:169], v[70:73], v[158:161], v[166:169]
	v_mfma_f32_16x16x32_bf16 v[166:169], v[82:85], v[170:173], v[166:169]
	v_mfma_f32_16x16x32_bf16 v[162:165], v[106:109], v[170:173], v[162:165]
	v_mfma_f32_16x16x32_bf16 v[162:165], v[94:97], v[158:161], v[162:165]
	v_mfma_f32_16x16x32_bf16 v[150:153], v[118:121], v[158:161], v[150:153]
	v_mfma_f32_16x16x32_bf16 v[150:153], v[130:133], v[170:173], v[150:153]
	v_mfma_f32_16x16x32_bf16 v[146:149], v[154:157], v[170:173], v[146:149]
	v_mfma_f32_16x16x32_bf16 v[146:149], v[142:145], v[158:161], v[146:149]
	v_mfma_f32_16x16x32_bf16 v[122:125], v[142:145], v[174:177], v[122:125]
	v_mfma_f32_16x16x32_bf16 v[122:125], v[154:157], v[178:181], v[122:125]
	v_mfma_f32_16x16x32_bf16 v[126:129], v[130:133], v[178:181], v[126:129]
	v_mfma_f32_16x16x32_bf16 v[126:129], v[118:121], v[174:177], v[126:129]
	v_mfma_f32_16x16x32_bf16 v[134:137], v[94:97], v[174:177], v[134:137]
	v_mfma_f32_16x16x32_bf16 v[134:137], v[106:109], v[178:181], v[134:137]
	v_mfma_f32_16x16x32_bf16 v[138:141], v[82:85], v[178:181], v[138:141]
	v_mfma_f32_16x16x32_bf16 v[138:141], v[70:73], v[174:177], v[138:141]
	v_mfma_f32_16x16x32_bf16 v[114:117], v[70:73], v[182:185], v[114:117]
	v_mfma_f32_16x16x32_bf16 v[114:117], v[82:85], v[186:189], v[114:117]
	v_mfma_f32_16x16x32_bf16 v[110:113], v[106:109], v[186:189], v[110:113]
	v_mfma_f32_16x16x32_bf16 v[110:113], v[94:97], v[182:185], v[110:113]
	v_mfma_f32_16x16x32_bf16 v[102:105], v[118:121], v[182:185], v[102:105]
	v_mfma_f32_16x16x32_bf16 v[102:105], v[130:133], v[186:189], v[102:105]
	v_mfma_f32_16x16x32_bf16 v[98:101], v[154:157], v[186:189], v[98:101]
	v_mfma_f32_16x16x32_bf16 v[98:101], v[142:145], v[182:185], v[98:101]
	v_mfma_f32_16x16x32_bf16 v[74:77], v[142:145], v[210:213], v[74:77]
	v_mfma_f32_16x16x32_bf16 v[74:77], v[154:157], v[214:217], v[74:77]
	v_mfma_f32_16x16x32_bf16 v[78:81], v[130:133], v[214:217], v[78:81]
	v_mfma_f32_16x16x32_bf16 v[78:81], v[118:121], v[210:213], v[78:81]
	v_mfma_f32_16x16x32_bf16 v[86:89], v[94:97], v[210:213], v[86:89]
	v_mfma_f32_16x16x32_bf16 v[86:89], v[106:109], v[214:217], v[86:89]
	v_mfma_f32_16x16x32_bf16 v[90:93], v[82:85], v[214:217], v[90:93]
	v_mfma_f32_16x16x32_bf16 v[90:93], v[70:73], v[210:213], v[90:93]
	s_barrier
	s_add_i32 s0, s0, s28
	s_mov_b32 m0, s0
	ds_read_b128 v[158:161], v237 offset:16384
	ds_read_b128 v[170:173], v237 offset:17408
	ds_read_b128 v[174:177], v237 offset:18432
	ds_read_b128 v[178:181], v237 offset:19456
	ds_read_b128 v[182:185], v237 offset:20480
	ds_read_b128 v[186:189], v237 offset:21504
	ds_read_b128 v[210:213], v237 offset:22528
	ds_read_b128 v[214:217], v237 offset:23552
	global_load_lds_dwordx4 v192, s[70:71]
	s_add_i32 m0, s0, 0x2000
	s_add_u32 s0, s70, 0x160000
	s_addc_u32 s1, s71, 0
	s_add_i32 s8, s18, s28
	global_load_lds_dwordx4 v190, s[70:71]
	s_mov_b32 m0, s8
	s_nop 0
	global_load_lds_dwordx4 v192, s[0:1]
	s_add_i32 m0, s8, 0x2000
	s_nop 0
	global_load_lds_dwordx4 v190, s[0:1]
	s_mov_b32 m0, s29
	s_nop 0
	global_load_lds_dwordx4 v192, s[76:77]
	s_mov_b32 m0, s31
	s_nop 0
	global_load_lds_dwordx4 v190, s[76:77]
	s_waitcnt vmcnt(8)
	s_waitcnt lgkmcnt(0)
	s_barrier
	s_waitcnt lgkmcnt(0)
	v_mfma_f32_16x16x32_bf16 v[62:65], v[70:73], v[158:161], v[62:65]
	v_mfma_f32_16x16x32_bf16 v[62:65], v[82:85], v[170:173], v[62:65]
	v_mfma_f32_16x16x32_bf16 v[58:61], v[106:109], v[170:173], v[58:61]
	v_mfma_f32_16x16x32_bf16 v[58:61], v[94:97], v[158:161], v[58:61]
	v_mfma_f32_16x16x32_bf16 v[54:57], v[118:121], v[158:161], v[54:57]
	v_mfma_f32_16x16x32_bf16 v[54:57], v[130:133], v[170:173], v[54:57]
	v_mfma_f32_16x16x32_bf16 v[50:53], v[154:157], v[170:173], v[50:53]
	v_mfma_f32_16x16x32_bf16 v[50:53], v[142:145], v[158:161], v[50:53]
	v_mfma_f32_16x16x32_bf16 v[34:37], v[142:145], v[174:177], v[34:37]
	v_mfma_f32_16x16x32_bf16 v[34:37], v[154:157], v[178:181], v[34:37]
	v_mfma_f32_16x16x32_bf16 v[38:41], v[130:133], v[178:181], v[38:41]
	v_mfma_f32_16x16x32_bf16 v[38:41], v[118:121], v[174:177], v[38:41]
	v_mfma_f32_16x16x32_bf16 v[42:45], v[94:97], v[174:177], v[42:45]
	v_mfma_f32_16x16x32_bf16 v[42:45], v[106:109], v[178:181], v[42:45]
	v_mfma_f32_16x16x32_bf16 v[46:49], v[82:85], v[178:181], v[46:49]
	v_mfma_f32_16x16x32_bf16 v[46:49], v[70:73], v[174:177], v[46:49]
	v_mfma_f32_16x16x32_bf16 v[30:33], v[70:73], v[182:185], v[30:33]
	v_mfma_f32_16x16x32_bf16 v[30:33], v[82:85], v[186:189], v[30:33]
	v_mfma_f32_16x16x32_bf16 v[26:29], v[106:109], v[186:189], v[26:29]
	v_mfma_f32_16x16x32_bf16 v[26:29], v[94:97], v[182:185], v[26:29]
	v_mfma_f32_16x16x32_bf16 v[22:25], v[118:121], v[182:185], v[22:25]
	v_mfma_f32_16x16x32_bf16 v[22:25], v[130:133], v[186:189], v[22:25]
	v_mfma_f32_16x16x32_bf16 v[18:21], v[154:157], v[186:189], v[18:21]
	v_mfma_f32_16x16x32_bf16 v[18:21], v[142:145], v[182:185], v[18:21]
	v_mfma_f32_16x16x32_bf16 v[2:5], v[142:145], v[210:213], v[2:5]
	v_mfma_f32_16x16x32_bf16 v[2:5], v[154:157], v[214:217], v[2:5]
	v_mfma_f32_16x16x32_bf16 v[6:9], v[130:133], v[214:217], v[6:9]
	v_mfma_f32_16x16x32_bf16 v[6:9], v[118:121], v[210:213], v[6:9]
	v_mfma_f32_16x16x32_bf16 v[10:13], v[94:97], v[210:213], v[10:13]
	v_mfma_f32_16x16x32_bf16 v[10:13], v[106:109], v[214:217], v[10:13]
	v_mfma_f32_16x16x32_bf16 v[14:17], v[82:85], v[214:217], v[14:17]
	v_mfma_f32_16x16x32_bf16 v[14:17], v[70:73], v[210:213], v[14:17]
	s_barrier
	s_add_i32 s8, 0, 0x18000
	s_add_i32 s9, 0, 0x1c000
	v_add_u32_e32 v106, s8, v1
	v_add_u32_e32 v154, s9, v1
	ds_read_b128 v[70:73], v106
	ds_read_b128 v[82:85], v106 offset:1024
	ds_read_b128 v[94:97], v106 offset:2048
	ds_read_b128 v[106:109], v106 offset:3072
	ds_read_b128 v[118:121], v154
	ds_read_b128 v[130:133], v154 offset:1024
	ds_read_b128 v[142:145], v154 offset:2048
	ds_read_b128 v[154:157], v154 offset:3072
	s_add_u32 s0, s76, 0x160000
	s_addc_u32 s1, s77, 0
	s_mov_b32 m0, s33
	ds_read_b128 v[158:161], v237 offset:32768
	ds_read_b128 v[170:173], v237 offset:33792
	ds_read_b128 v[174:177], v237 offset:34816
	ds_read_b128 v[178:181], v237 offset:35840
	ds_read_b128 v[182:185], v237 offset:36864
	ds_read_b128 v[186:189], v237 offset:37888
	ds_read_b128 v[210:213], v237 offset:38912
	ds_read_b128 v[214:217], v237 offset:39936
	global_load_lds_dwordx4 v192, s[0:1]
	s_mov_b32 m0, s43
	s_nop 0
	global_load_lds_dwordx4 v190, s[0:1]
	s_waitcnt vmcnt(8)
	s_waitcnt lgkmcnt(0)
	s_barrier
	s_waitcnt lgkmcnt(0)
	v_mfma_f32_16x16x32_bf16 v[166:169], v[70:73], v[158:161], v[166:169]
	v_mfma_f32_16x16x32_bf16 v[166:169], v[82:85], v[170:173], v[166:169]
	v_mfma_f32_16x16x32_bf16 v[162:165], v[106:109], v[170:173], v[162:165]
	v_mfma_f32_16x16x32_bf16 v[162:165], v[94:97], v[158:161], v[162:165]
	v_mfma_f32_16x16x32_bf16 v[150:153], v[118:121], v[158:161], v[150:153]
	v_mfma_f32_16x16x32_bf16 v[150:153], v[130:133], v[170:173], v[150:153]
	v_mfma_f32_16x16x32_bf16 v[146:149], v[154:157], v[170:173], v[146:149]
	v_mfma_f32_16x16x32_bf16 v[146:149], v[142:145], v[158:161], v[146:149]
	v_mfma_f32_16x16x32_bf16 v[122:125], v[142:145], v[174:177], v[122:125]
	v_mfma_f32_16x16x32_bf16 v[122:125], v[154:157], v[178:181], v[122:125]
	v_mfma_f32_16x16x32_bf16 v[126:129], v[130:133], v[178:181], v[126:129]
	v_mfma_f32_16x16x32_bf16 v[126:129], v[118:121], v[174:177], v[126:129]
	v_mfma_f32_16x16x32_bf16 v[134:137], v[94:97], v[174:177], v[134:137]
	v_mfma_f32_16x16x32_bf16 v[134:137], v[106:109], v[178:181], v[134:137]
	v_mfma_f32_16x16x32_bf16 v[138:141], v[82:85], v[178:181], v[138:141]
	v_mfma_f32_16x16x32_bf16 v[138:141], v[70:73], v[174:177], v[138:141]
	v_mfma_f32_16x16x32_bf16 v[114:117], v[70:73], v[182:185], v[114:117]
	v_mfma_f32_16x16x32_bf16 v[114:117], v[82:85], v[186:189], v[114:117]
	v_mfma_f32_16x16x32_bf16 v[110:113], v[106:109], v[186:189], v[110:113]
	v_mfma_f32_16x16x32_bf16 v[110:113], v[94:97], v[182:185], v[110:113]
	v_mfma_f32_16x16x32_bf16 v[102:105], v[118:121], v[182:185], v[102:105]
	v_mfma_f32_16x16x32_bf16 v[102:105], v[130:133], v[186:189], v[102:105]
	v_mfma_f32_16x16x32_bf16 v[98:101], v[154:157], v[186:189], v[98:101]
	v_mfma_f32_16x16x32_bf16 v[98:101], v[142:145], v[182:185], v[98:101]
	v_mfma_f32_16x16x32_bf16 v[74:77], v[142:145], v[210:213], v[74:77]
	v_mfma_f32_16x16x32_bf16 v[74:77], v[154:157], v[214:217], v[74:77]
	v_mfma_f32_16x16x32_bf16 v[78:81], v[130:133], v[214:217], v[78:81]
	v_mfma_f32_16x16x32_bf16 v[78:81], v[118:121], v[210:213], v[78:81]
	v_mfma_f32_16x16x32_bf16 v[86:89], v[94:97], v[210:213], v[86:89]
	v_mfma_f32_16x16x32_bf16 v[86:89], v[106:109], v[214:217], v[86:89]
	v_mfma_f32_16x16x32_bf16 v[90:93], v[82:85], v[214:217], v[90:93]
	v_mfma_f32_16x16x32_bf16 v[90:93], v[70:73], v[210:213], v[90:93]
	s_barrier
	s_add_u32 s98, s70, 0x80
	s_addc_u32 s99, s71, 0
	s_add_u32 s100, s76, 0x80
	s_addc_u32 s101, s77, 0
	s_add_i32 s0, s8, s28
	s_mov_b32 m0, s0
	ds_read_b128 v[158:161], v237 offset:49152
	ds_read_b128 v[170:173], v237 offset:50176
	ds_read_b128 v[174:177], v237 offset:51200
	ds_read_b128 v[178:181], v237 offset:52224
	ds_read_b128 v[182:185], v237 offset:53248
	ds_read_b128 v[186:189], v237 offset:54272
	ds_read_b128 v[210:213], v237 offset:55296
	ds_read_b128 v[214:217], v237 offset:56320
	global_load_lds_dwordx4 v192, s[98:99]
	s_add_i32 m0, s0, 0x2000
	s_add_u32 s0, s70, 0x160080
	s_addc_u32 s1, s71, 0
	s_add_i32 s8, s9, s28
	global_load_lds_dwordx4 v190, s[98:99]
	s_mov_b32 m0, s8
	s_nop 0
	global_load_lds_dwordx4 v192, s[0:1]
	s_add_i32 m0, s8, 0x2000
	s_nop 0
	global_load_lds_dwordx4 v190, s[0:1]
	s_mov_b32 m0, s68
	s_nop 0
	global_load_lds_dwordx4 v192, s[100:101]
	s_mov_b32 m0, s79
	s_nop 0
	global_load_lds_dwordx4 v190, s[100:101]
	s_add_i32 s41, s41, 2
	s_add_u32 s7, s7, 0x100
	s_addc_u32 s23, s23, 0
	s_mov_b64 s[8:9], s[64:65]
	s_cmpk_eq_i32 s41, 0x54
	s_cselect_b64 s[70:71], -1, 0
	s_and_b64 s[100:101], s[70:71], s[50:51]
	s_add_u32 s64, s8, 0x100
	s_addc_u32 s65, s9, 0
	s_and_b64 s[0:1], s[70:71], exec
	s_cselect_b32 s77, s63, s65
	s_cselect_b32 s76, s62, s64
	s_cselect_b32 s71, s85, s23
	s_cselect_b32 s70, s84, s7
	s_cmpk_gt_u32 s41, 0x55
	s_waitcnt vmcnt(8)
	s_waitcnt lgkmcnt(0)
	s_barrier
	s_waitcnt lgkmcnt(0)
	v_mfma_f32_16x16x32_bf16 v[62:65], v[70:73], v[158:161], v[62:65]
	v_mfma_f32_16x16x32_bf16 v[62:65], v[82:85], v[170:173], v[62:65]
	v_mfma_f32_16x16x32_bf16 v[58:61], v[106:109], v[170:173], v[58:61]
	v_mfma_f32_16x16x32_bf16 v[58:61], v[94:97], v[158:161], v[58:61]
	v_mfma_f32_16x16x32_bf16 v[54:57], v[118:121], v[158:161], v[54:57]
	v_mfma_f32_16x16x32_bf16 v[54:57], v[130:133], v[170:173], v[54:57]
	v_mfma_f32_16x16x32_bf16 v[50:53], v[154:157], v[170:173], v[50:53]
	v_mfma_f32_16x16x32_bf16 v[50:53], v[142:145], v[158:161], v[50:53]
	v_mfma_f32_16x16x32_bf16 v[34:37], v[142:145], v[174:177], v[34:37]
	v_mfma_f32_16x16x32_bf16 v[34:37], v[154:157], v[178:181], v[34:37]
	v_mfma_f32_16x16x32_bf16 v[38:41], v[130:133], v[178:181], v[38:41]
	v_mfma_f32_16x16x32_bf16 v[38:41], v[118:121], v[174:177], v[38:41]
	v_mfma_f32_16x16x32_bf16 v[42:45], v[94:97], v[174:177], v[42:45]
	v_mfma_f32_16x16x32_bf16 v[42:45], v[106:109], v[178:181], v[42:45]
	v_mfma_f32_16x16x32_bf16 v[46:49], v[82:85], v[178:181], v[46:49]
	v_mfma_f32_16x16x32_bf16 v[46:49], v[70:73], v[174:177], v[46:49]
	v_mfma_f32_16x16x32_bf16 v[30:33], v[70:73], v[182:185], v[30:33]
	v_mfma_f32_16x16x32_bf16 v[30:33], v[82:85], v[186:189], v[30:33]
	v_mfma_f32_16x16x32_bf16 v[26:29], v[106:109], v[186:189], v[26:29]
	v_mfma_f32_16x16x32_bf16 v[26:29], v[94:97], v[182:185], v[26:29]
	v_mfma_f32_16x16x32_bf16 v[22:25], v[118:121], v[182:185], v[22:25]
	v_mfma_f32_16x16x32_bf16 v[22:25], v[130:133], v[186:189], v[22:25]
	v_mfma_f32_16x16x32_bf16 v[18:21], v[154:157], v[186:189], v[18:21]
	v_mfma_f32_16x16x32_bf16 v[18:21], v[142:145], v[182:185], v[18:21]
	v_mfma_f32_16x16x32_bf16 v[2:5], v[142:145], v[210:213], v[2:5]
	v_mfma_f32_16x16x32_bf16 v[2:5], v[154:157], v[214:217], v[2:5]
	v_mfma_f32_16x16x32_bf16 v[6:9], v[130:133], v[214:217], v[6:9]
	v_mfma_f32_16x16x32_bf16 v[6:9], v[118:121], v[210:213], v[6:9]
	v_mfma_f32_16x16x32_bf16 v[10:13], v[94:97], v[210:213], v[10:13]
	v_mfma_f32_16x16x32_bf16 v[10:13], v[106:109], v[214:217], v[10:13]
	v_mfma_f32_16x16x32_bf16 v[14:17], v[82:85], v[214:217], v[14:17]
	v_mfma_f32_16x16x32_bf16 v[14:17], v[70:73], v[210:213], v[14:17]
	s_barrier
	s_cbranch_scc1 .LBB0_648
	s_cmp_lg_u64 s[100:101], 0
	s_cbranch_scc1 .Lrot_rare_down
	s_branch .Lrot_body_down
